# GEMM epilogue stores marked nt
# baseline (speedup 1.0000x reference)
.LBB0_723:
	v_readlane_b32 s2, v255, 14
	v_cmp_gt_i32_e32 vcc, 2, v248
	v_readlane_b32 s3, v255, 15
	s_and_b64 s[4:5], s[2:3], vcc
	s_and_saveexec_b64 s[2:3], s[4:5]
	s_cbranch_execz .LBB0_725
	s_ashr_i32 s5, s6, 31
	s_add_u32 s4, s6, s57
	s_addc_u32 s5, s5, s35
	v_lshl_add_u64 v[130:131], s[4:5], 0, v[192:193]
	v_readlane_b32 s4, v254, 39
	v_lshlrev_b32_e32 v128, 3, v248
	v_lshlrev_b64 v[130:131], 6, v[130:131]
	v_readlane_b32 s5, v254, 40
	v_ashrrev_i32_e32 v129, 31, v128
	s_nop 0
	v_lshl_add_u64 v[130:131], s[4:5], 0, v[130:131]
	v_lshl_add_u64 v[128:129], v[128:129], 2, v[130:131]
	s_mov_b64 s[4:5], 0x2000
	v_lshl_add_u64 v[130:131], v[128:129], 0, s[4:5]
	s_movk_i32 s4, 0x2000
	v_add_co_u32_e32 v132, vcc, s4, v128
	s_mov_b64 s[4:5], 0x2400
	s_nop 0
	v_addc_co_u32_e32 v133, vcc, 0, v129, vcc
	global_store_dwordx4 v[128:129], v[124:127], off nt
	global_store_dwordx4 v[128:129], v[60:63], off offset:16 nt
	global_store_dwordx4 v[128:129], v[116:119], off offset:1024 nt
	global_store_dwordx4 v[128:129], v[52:55], off offset:1040 nt
	global_store_dwordx4 v[128:129], v[108:111], off offset:2048 nt
	global_store_dwordx4 v[128:129], v[44:47], off offset:2064 nt
	global_store_dwordx4 v[128:129], v[100:103], off offset:3072 nt
	global_store_dwordx4 v[128:129], v[36:39], off offset:3088 nt
	global_store_dwordx4 v[132:133], v[92:95], off nt
	global_store_dwordx4 v[130:131], v[28:31], off offset:16 nt
	v_lshl_add_u64 v[130:131], v[128:129], 0, s[4:5]
	s_mov_b64 s[4:5], 0x2800
	global_store_dwordx4 v[132:133], v[84:87], off offset:1024 nt
	global_store_dwordx4 v[130:131], v[20:23], off offset:16 nt
	v_lshl_add_u64 v[130:131], v[128:129], 0, s[4:5]
	s_mov_b64 s[4:5], 0x2c00
	global_store_dwordx4 v[132:133], v[76:79], off offset:2048 nt
	global_store_dwordx4 v[130:131], v[12:15], off offset:16 nt
	v_lshl_add_u64 v[128:129], v[128:129], 0, s[4:5]
	global_store_dwordx4 v[132:133], v[68:71], off offset:3072 nt
	global_store_dwordx4 v[128:129], v[4:7], off offset:16 nt

.LBB0_732:
	v_cndmask_b32_e64 v136, 0, 1.0, s[4:5]
	v_mov_b32_dpp v232, v120 row_shr:1 row_mask:0xf bank_mask:0xf bound_ctrl:1
	v_mov_b32_dpp v233, v121 row_shr:1 row_mask:0xf bank_mask:0xf bound_ctrl:1
	s_waitcnt lgkmcnt(0)
	v_pk_fma_f32 v[188:189], v[136:137], v[188:189], v[232:233] op_sel_hi:[0,1,1]
	v_mov_b32_dpp v220, v112 row_mirror row_mask:0xf bank_mask:0xf bound_ctrl:1
	v_mov_b32_dpp v248, v120 row_shl:1 row_mask:0xf bank_mask:0xf bound_ctrl:1
	v_mov_b32_dpp v221, v113 row_mirror row_mask:0xf bank_mask:0xf bound_ctrl:1
	v_mov_b32_dpp v249, v121 row_shl:1 row_mask:0xf bank_mask:0xf bound_ctrl:1
	v_pk_fma_f32 v[188:189], v[152:153], v[188:189], v[164:165]
	v_pk_fma_f32 v[232:233], v[208:209], v[220:221], v[248:249] op_sel_hi:[0,1,1]
	v_pk_fma_f32 v[188:189], v[120:121], v[156:157], v[188:189]
	v_or_b32_e32 v144, s57, v192
	v_pk_fma_f32 v[188:189], v[160:161], v[232:233], v[188:189]
	v_mov_b32_dpp v222, v124 row_shr:1 row_mask:0xf bank_mask:0xf bound_ctrl:1
	v_mul_f32_e32 v137, 0xbfb8aa3b, v188
	v_exp_f32_e32 v137, v137
	v_mul_f32_e32 v192, 0xbfb8aa3b, v189
	v_exp_f32_e32 v192, v192
	v_mov_b32_dpp v223, v125 row_shr:1 row_mask:0xf bank_mask:0xf bound_ctrl:1
	v_add_f32_e32 v137, 1.0, v137
	v_mov_b32_dpp v218, v116 row_mirror row_mask:0xf bank_mask:0xf bound_ctrl:1
	v_mov_b32_dpp v234, v124 row_shl:1 row_mask:0xf bank_mask:0xf bound_ctrl:1
	v_mov_b32_dpp v219, v117 row_mirror row_mask:0xf bank_mask:0xf bound_ctrl:1
	v_mov_b32_dpp v235, v125 row_shl:1 row_mask:0xf bank_mask:0xf bound_ctrl:1
	v_pk_fma_f32 v[184:185], v[136:137], v[184:185], v[222:223] op_sel_hi:[0,1,1]
	v_rcp_f32_e32 v232, v137
	v_pk_fma_f32 v[222:223], v[208:209], v[218:219], v[234:235] op_sel_hi:[0,1,1]
	v_add_f32_e32 v137, 1.0, v192
	v_pk_fma_f32 v[184:185], v[128:129], v[184:185], v[148:149]
	v_mov_b32_dpp v234, v122 row_shr:1 row_mask:0xf bank_mask:0xf bound_ctrl:1
	v_mov_b32_dpp v235, v123 row_shr:1 row_mask:0xf bank_mask:0xf bound_ctrl:1
	v_pk_fma_f32 v[184:185], v[124:125], v[132:133], v[184:185]
	v_pk_fma_f32 v[190:191], v[136:137], v[190:191], v[234:235] op_sel_hi:[0,1,1]
	v_pk_fma_f32 v[184:185], v[140:141], v[222:223], v[184:185]
	v_mov_b32_dpp v222, v114 row_mirror row_mask:0xf bank_mask:0xf bound_ctrl:1
	v_mov_b32_dpp v250, v122 row_shl:1 row_mask:0xf bank_mask:0xf bound_ctrl:1
	v_mov_b32_dpp v223, v115 row_mirror row_mask:0xf bank_mask:0xf bound_ctrl:1
	v_mov_b32_dpp v251, v123 row_shl:1 row_mask:0xf bank_mask:0xf bound_ctrl:1
	v_pk_fma_f32 v[190:191], v[154:155], v[190:191], v[166:167]
	v_pk_fma_f32 v[234:235], v[208:209], v[222:223], v[250:251] op_sel_hi:[0,1,1]
	v_pk_fma_f32 v[190:191], v[122:123], v[158:159], v[190:191]
	v_rcp_f32_e32 v233, v137
	v_pk_fma_f32 v[190:191], v[162:163], v[234:235], v[190:191]
	v_mov_b32_dpp v248, v126 row_shl:1 row_mask:0xf bank_mask:0xf bound_ctrl:1
	v_mul_f32_e32 v137, 0xbfb8aa3b, v190
	v_exp_f32_e32 v137, v137
	v_mul_f32_e32 v192, 0xbfb8aa3b, v191
	v_exp_f32_e32 v192, v192
	v_pk_mul_f32 v[188:189], v[188:189], v[232:233]
	v_mov_b32_dpp v232, v126 row_shr:1 row_mask:0xf bank_mask:0xf bound_ctrl:1
	v_mov_b32_dpp v233, v127 row_shr:1 row_mask:0xf bank_mask:0xf bound_ctrl:1
	v_add_f32_e32 v137, 1.0, v137
	v_rcp_f32_e32 v234, v137
	v_pk_fma_f32 v[186:187], v[136:137], v[186:187], v[232:233] op_sel_hi:[0,1,1]
	v_add_f32_e32 v137, 1.0, v192
	v_rcp_f32_e32 v235, v137
	v_pk_mul_f32 v[184:185], v[184:185], v[188:189]
	v_mov_b32_dpp v188, v118 row_mirror row_mask:0xf bank_mask:0xf bound_ctrl:1
	v_mov_b32_dpp v189, v119 row_mirror row_mask:0xf bank_mask:0xf bound_ctrl:1
	v_mov_b32_dpp v249, v127 row_shl:1 row_mask:0xf bank_mask:0xf bound_ctrl:1
	v_pk_fma_f32 v[186:187], v[130:131], v[186:187], v[150:151]
	v_readlane_b32 s2, v254, 51
	v_pk_fma_f32 v[232:233], v[208:209], v[188:189], v[248:249] op_sel_hi:[0,1,1]
	v_pk_fma_f32 v[186:187], v[126:127], v[134:135], v[186:187]
	v_mov_b32_e32 v145, s35
	v_readlane_b32 s3, v254, 52
	v_pk_fma_f32 v[186:187], v[142:143], v[232:233], v[186:187]
	v_pk_mul_f32 v[190:191], v[190:191], v[234:235]
	s_ashr_i32 s7, s6, 31
	v_lshl_add_u64 v[216:217], v[212:213], 1, s[2:3]
	v_pk_mul_f32 v[186:187], v[186:187], v[190:191]
	v_cvt_pk_bf16_f32 v190, v184, v185
	v_lshl_add_u64 v[184:185], v[144:145], 0, s[6:7]
	s_movk_i32 s4, 0x1600
	v_mad_u64_u32 v[144:145], s[2:3], v184, s4, v[216:217]
	v_cvt_pk_bf16_f32 v191, v186, v187
	v_mad_i32_i24 v145, v185, s4, v145
	global_store_dwordx2 v[144:145], v[190:191], off nt
	v_mov_b32_dpp v120, v120 row_mirror row_mask:0xf bank_mask:0xf bound_ctrl:1
	v_mov_b32_dpp v234, v112 row_shr:1 row_mask:0xf bank_mask:0xf bound_ctrl:1
	v_mov_b32_dpp v121, v121 row_mirror row_mask:0xf bank_mask:0xf bound_ctrl:1
	v_mov_b32_dpp v235, v113 row_shr:1 row_mask:0xf bank_mask:0xf bound_ctrl:1
	v_pk_fma_f32 v[120:121], v[136:137], v[120:121], v[234:235] op_sel_hi:[0,1,1]
	v_mov_b32_dpp v186, v104 row_mirror row_mask:0xf bank_mask:0xf bound_ctrl:1
	v_mov_b32_dpp v250, v112 row_shl:1 row_mask:0xf bank_mask:0xf bound_ctrl:1
	v_mov_b32_dpp v187, v105 row_mirror row_mask:0xf bank_mask:0xf bound_ctrl:1
	v_mov_b32_dpp v251, v113 row_shl:1 row_mask:0xf bank_mask:0xf bound_ctrl:1
	v_pk_fma_f32 v[120:121], v[152:153], v[120:121], v[164:165]
	v_pk_fma_f32 v[234:235], v[208:209], v[186:187], v[250:251] op_sel_hi:[0,1,1]
	v_pk_fma_f32 v[112:113], v[112:113], v[156:157], v[120:121]
	v_mov_b32_dpp v190, v124 row_mirror row_mask:0xf bank_mask:0xf bound_ctrl:1
	v_pk_fma_f32 v[112:113], v[160:161], v[234:235], v[112:113]
	v_mov_b32_dpp v232, v116 row_shr:1 row_mask:0xf bank_mask:0xf bound_ctrl:1
	v_mul_f32_e32 v120, 0xbfb8aa3b, v112
	v_mul_f32_e32 v121, 0xbfb8aa3b, v113
	v_exp_f32_e32 v120, v120
	v_exp_f32_e32 v121, v121
	v_mov_b32_dpp v191, v125 row_mirror row_mask:0xf bank_mask:0xf bound_ctrl:1
	v_mov_b32_dpp v233, v117 row_shr:1 row_mask:0xf bank_mask:0xf bound_ctrl:1
	v_add_f32_e32 v120, 1.0, v120
	v_add_f32_e32 v121, 1.0, v121
	v_rcp_f32_e32 v120, v120
	v_pk_fma_f32 v[190:191], v[136:137], v[190:191], v[232:233] op_sel_hi:[0,1,1]
	v_rcp_f32_e32 v121, v121
	v_mov_b32_dpp v124, v108 row_mirror row_mask:0xf bank_mask:0xf bound_ctrl:1
	v_mov_b32_dpp v248, v116 row_shl:1 row_mask:0xf bank_mask:0xf bound_ctrl:1
	v_mov_b32_dpp v125, v109 row_mirror row_mask:0xf bank_mask:0xf bound_ctrl:1
	v_mov_b32_dpp v249, v117 row_shl:1 row_mask:0xf bank_mask:0xf bound_ctrl:1
	v_pk_fma_f32 v[190:191], v[128:129], v[190:191], v[148:149]
	v_pk_fma_f32 v[232:233], v[208:209], v[124:125], v[248:249] op_sel_hi:[0,1,1]
	v_pk_fma_f32 v[116:117], v[116:117], v[132:133], v[190:191]
	v_mov_b32_dpp v122, v122 row_mirror row_mask:0xf bank_mask:0xf bound_ctrl:1
	v_pk_fma_f32 v[116:117], v[140:141], v[232:233], v[116:117]
	v_mov_b32_dpp v232, v114 row_shr:1 row_mask:0xf bank_mask:0xf bound_ctrl:1
	v_mov_b32_dpp v123, v123 row_mirror row_mask:0xf bank_mask:0xf bound_ctrl:1
	v_mov_b32_dpp v233, v115 row_shr:1 row_mask:0xf bank_mask:0xf bound_ctrl:1
	v_pk_mul_f32 v[112:113], v[112:113], v[120:121]
	v_pk_fma_f32 v[122:123], v[136:137], v[122:123], v[232:233] op_sel_hi:[0,1,1]
	v_pk_mul_f32 v[120:121], v[116:117], v[112:113]
	v_mov_b32_dpp v116, v106 row_mirror row_mask:0xf bank_mask:0xf bound_ctrl:1
	v_mov_b32_dpp v248, v114 row_shl:1 row_mask:0xf bank_mask:0xf bound_ctrl:1
	v_mov_b32_dpp v117, v107 row_mirror row_mask:0xf bank_mask:0xf bound_ctrl:1
	v_mov_b32_dpp v249, v115 row_shl:1 row_mask:0xf bank_mask:0xf bound_ctrl:1
	v_pk_fma_f32 v[122:123], v[154:155], v[122:123], v[166:167]
	v_pk_fma_f32 v[232:233], v[208:209], v[116:117], v[248:249] op_sel_hi:[0,1,1]
	v_pk_fma_f32 v[114:115], v[114:115], v[158:159], v[122:123]
	v_mov_b32_dpp v126, v126 row_mirror row_mask:0xf bank_mask:0xf bound_ctrl:1
	v_pk_fma_f32 v[114:115], v[162:163], v[232:233], v[114:115]
	v_mov_b32_dpp v190, v118 row_shr:1 row_mask:0xf bank_mask:0xf bound_ctrl:1
	v_mul_f32_e32 v113, 0xbfb8aa3b, v114
	v_mul_f32_e32 v123, 0xbfb8aa3b, v115
	v_exp_f32_e32 v122, v113
	v_exp_f32_e32 v123, v123
	v_mov_b32_dpp v127, v127 row_mirror row_mask:0xf bank_mask:0xf bound_ctrl:1
	v_mov_b32_dpp v191, v119 row_shr:1 row_mask:0xf bank_mask:0xf bound_ctrl:1
	v_add_f32_e32 v122, 1.0, v122
	v_add_f32_e32 v123, 1.0, v123
	v_rcp_f32_e32 v122, v122
	v_rcp_f32_e32 v123, v123
	v_pk_fma_f32 v[126:127], v[136:137], v[126:127], v[190:191] op_sel_hi:[0,1,1]
	v_mov_b32_dpp v112, v110 row_mirror row_mask:0xf bank_mask:0xf bound_ctrl:1
	v_mov_b32_dpp v234, v118 row_shl:1 row_mask:0xf bank_mask:0xf bound_ctrl:1
	v_mov_b32_dpp v113, v111 row_mirror row_mask:0xf bank_mask:0xf bound_ctrl:1
	v_mov_b32_dpp v235, v119 row_shl:1 row_mask:0xf bank_mask:0xf bound_ctrl:1
	v_pk_fma_f32 v[126:127], v[130:131], v[126:127], v[150:151]
	v_pk_fma_f32 v[190:191], v[208:209], v[112:113], v[234:235] op_sel_hi:[0,1,1]
	v_pk_fma_f32 v[118:119], v[118:119], v[134:135], v[126:127]
	v_pk_mul_f32 v[114:115], v[114:115], v[122:123]
	v_pk_fma_f32 v[118:119], v[142:143], v[190:191], v[118:119]
	s_nop 0
	v_pk_mul_f32 v[114:115], v[118:119], v[114:115]
	v_cvt_pk_bf16_f32 v118, v120, v121
	v_cvt_pk_bf16_f32 v119, v114, v115
	v_lshl_add_u64 v[114:115], v[184:185], 0, 16
	v_mad_u64_u32 v[120:121], s[2:3], v114, s4, v[216:217]
	v_mad_i32_i24 v121, v115, s4, v121
	global_store_dwordx2 v[120:121], v[118:119], off nt
	v_mov_b32_dpp v126, v104 row_shr:1 row_mask:0xf bank_mask:0xf bound_ctrl:1
	v_mov_b32_dpp v127, v105 row_shr:1 row_mask:0xf bank_mask:0xf bound_ctrl:1
	v_pk_fma_f32 v[126:127], v[136:137], v[220:221], v[126:127] op_sel_hi:[0,1,1]
	v_mov_b32_dpp v118, v96 row_mirror row_mask:0xf bank_mask:0xf bound_ctrl:1
	v_mov_b32_dpp v232, v104 row_shl:1 row_mask:0xf bank_mask:0xf bound_ctrl:1
	v_mov_b32_dpp v119, v97 row_mirror row_mask:0xf bank_mask:0xf bound_ctrl:1
	v_mov_b32_dpp v233, v105 row_shl:1 row_mask:0xf bank_mask:0xf bound_ctrl:1
	v_pk_fma_f32 v[126:127], v[152:153], v[126:127], v[164:165]
	v_pk_fma_f32 v[118:119], v[208:209], v[118:119], v[232:233] op_sel_hi:[0,1,1]
	v_pk_fma_f32 v[104:105], v[104:105], v[156:157], v[126:127]
	v_mov_b32_dpp v122, v108 row_shr:1 row_mask:0xf bank_mask:0xf bound_ctrl:1
	v_pk_fma_f32 v[104:105], v[160:161], v[118:119], v[104:105]
	v_mov_b32_dpp v123, v109 row_shr:1 row_mask:0xf bank_mask:0xf bound_ctrl:1
	v_mul_f32_e32 v115, 0xbfb8aa3b, v104
	v_mul_f32_e32 v119, 0xbfb8aa3b, v105
	v_exp_f32_e32 v118, v115
	v_exp_f32_e32 v119, v119
	v_pk_fma_f32 v[122:123], v[136:137], v[218:219], v[122:123] op_sel_hi:[0,1,1]
	v_pk_fma_f32 v[122:123], v[128:129], v[122:123], v[148:149]
	v_add_f32_e32 v118, 1.0, v118
	v_add_f32_e32 v119, 1.0, v119
	v_mov_b32_dpp v114, v100 row_mirror row_mask:0xf bank_mask:0xf bound_ctrl:1
	v_mov_b32_dpp v190, v108 row_shl:1 row_mask:0xf bank_mask:0xf bound_ctrl:1
	v_mov_b32_dpp v115, v101 row_mirror row_mask:0xf bank_mask:0xf bound_ctrl:1
	v_mov_b32_dpp v191, v109 row_shl:1 row_mask:0xf bank_mask:0xf bound_ctrl:1
	v_rcp_f32_e32 v118, v118
	v_rcp_f32_e32 v119, v119
	v_pk_fma_f32 v[108:109], v[108:109], v[132:133], v[122:123]
	v_mov_b32_dpp v122, v106 row_shr:1 row_mask:0xf bank_mask:0xf bound_ctrl:1
	v_mov_b32_dpp v123, v107 row_shr:1 row_mask:0xf bank_mask:0xf bound_ctrl:1
	v_pk_fma_f32 v[114:115], v[208:209], v[114:115], v[190:191] op_sel_hi:[0,1,1]
	v_pk_fma_f32 v[122:123], v[136:137], v[222:223], v[122:123] op_sel_hi:[0,1,1]
	v_pk_fma_f32 v[108:109], v[140:141], v[114:115], v[108:109]
	v_mov_b32_dpp v114, v98 row_mirror row_mask:0xf bank_mask:0xf bound_ctrl:1
	v_mov_b32_dpp v190, v106 row_shl:1 row_mask:0xf bank_mask:0xf bound_ctrl:1
	v_mov_b32_dpp v115, v99 row_mirror row_mask:0xf bank_mask:0xf bound_ctrl:1
	v_mov_b32_dpp v191, v107 row_shl:1 row_mask:0xf bank_mask:0xf bound_ctrl:1
	v_pk_fma_f32 v[122:123], v[154:155], v[122:123], v[166:167]
	v_pk_fma_f32 v[114:115], v[208:209], v[114:115], v[190:191] op_sel_hi:[0,1,1]
	v_pk_fma_f32 v[106:107], v[106:107], v[158:159], v[122:123]
	v_pk_mul_f32 v[104:105], v[104:105], v[118:119]
	v_pk_fma_f32 v[106:107], v[162:163], v[114:115], v[106:107]
	v_pk_mul_f32 v[104:105], v[108:109], v[104:105]
	v_mul_f32_e32 v109, 0xbfb8aa3b, v106
	v_mul_f32_e32 v115, 0xbfb8aa3b, v107
	v_exp_f32_e32 v114, v109
	v_exp_f32_e32 v115, v115
	v_mov_b32_dpp v118, v110 row_shr:1 row_mask:0xf bank_mask:0xf bound_ctrl:1
	v_mov_b32_dpp v119, v111 row_shr:1 row_mask:0xf bank_mask:0xf bound_ctrl:1
	v_add_f32_e32 v114, 1.0, v114
	v_add_f32_e32 v115, 1.0, v115
	v_rcp_f32_e32 v114, v114
	v_rcp_f32_e32 v115, v115
	v_pk_fma_f32 v[118:119], v[136:137], v[188:189], v[118:119] op_sel_hi:[0,1,1]
	v_mov_b32_dpp v108, v102 row_mirror row_mask:0xf bank_mask:0xf bound_ctrl:1
	v_mov_b32_dpp v126, v110 row_shl:1 row_mask:0xf bank_mask:0xf bound_ctrl:1
	v_mov_b32_dpp v109, v103 row_mirror row_mask:0xf bank_mask:0xf bound_ctrl:1
	v_mov_b32_dpp v127, v111 row_shl:1 row_mask:0xf bank_mask:0xf bound_ctrl:1
	v_pk_fma_f32 v[118:119], v[130:131], v[118:119], v[150:151]
	v_pk_fma_f32 v[108:109], v[208:209], v[108:109], v[126:127] op_sel_hi:[0,1,1]
	v_pk_fma_f32 v[110:111], v[110:111], v[134:135], v[118:119]
	v_pk_mul_f32 v[106:107], v[106:107], v[114:115]
	v_pk_fma_f32 v[108:109], v[142:143], v[108:109], v[110:111]
	v_cvt_pk_bf16_f32 v104, v104, v105
	v_pk_mul_f32 v[106:107], v[108:109], v[106:107]
	s_nop 0
	v_cvt_pk_bf16_f32 v105, v106, v107
	v_lshl_add_u64 v[106:107], v[184:185], 0, 32
	v_mad_u64_u32 v[122:123], s[2:3], v106, s4, v[216:217]
	v_mad_i32_i24 v123, v107, s4, v123
	global_store_dwordx2 v[122:123], v[104:105], off nt
	v_mov_b32_dpp v106, v96 row_shr:1 row_mask:0xf bank_mask:0xf bound_ctrl:1
	v_mov_b32_dpp v107, v97 row_shr:1 row_mask:0xf bank_mask:0xf bound_ctrl:1
	v_pk_fma_f32 v[106:107], v[136:137], v[186:187], v[106:107] op_sel_hi:[0,1,1]
	v_mov_b32_dpp v108, v96 row_shl:1 row_mask:0xf bank_mask:0xf bound_ctrl:1
	v_mov_b32_dpp v109, v97 row_shl:1 row_mask:0xf bank_mask:0xf bound_ctrl:1
	v_pk_fma_f32 v[106:107], v[152:153], v[106:107], v[164:165]
	v_pk_fma_f32 v[108:109], v[208:209], v[180:181], v[108:109] op_sel_hi:[0,1,1]
	v_pk_fma_f32 v[96:97], v[96:97], v[156:157], v[106:107]
	v_mov_b32_dpp v104, v100 row_shr:1 row_mask:0xf bank_mask:0xf bound_ctrl:1
	v_pk_fma_f32 v[96:97], v[160:161], v[108:109], v[96:97]
	v_mov_b32_dpp v106, v100 row_shl:1 row_mask:0xf bank_mask:0xf bound_ctrl:1
	v_mul_f32_e32 v105, 0xbfb8aa3b, v96
	v_mul_f32_e32 v109, 0xbfb8aa3b, v97
	v_exp_f32_e32 v108, v105
	v_exp_f32_e32 v109, v109
	v_mov_b32_dpp v105, v101 row_shr:1 row_mask:0xf bank_mask:0xf bound_ctrl:1
	v_pk_fma_f32 v[104:105], v[136:137], v[124:125], v[104:105] op_sel_hi:[0,1,1]
	v_add_f32_e32 v108, 1.0, v108
	v_add_f32_e32 v109, 1.0, v109
	v_pk_fma_f32 v[104:105], v[128:129], v[104:105], v[148:149]
	v_mov_b32_dpp v107, v101 row_shl:1 row_mask:0xf bank_mask:0xf bound_ctrl:1
	v_rcp_f32_e32 v108, v108
	v_rcp_f32_e32 v109, v109
	v_pk_fma_f32 v[100:101], v[100:101], v[132:133], v[104:105]
	v_mov_b32_dpp v104, v98 row_shr:1 row_mask:0xf bank_mask:0xf bound_ctrl:1
	v_mov_b32_dpp v105, v99 row_shr:1 row_mask:0xf bank_mask:0xf bound_ctrl:1
	v_pk_fma_f32 v[106:107], v[208:209], v[176:177], v[106:107] op_sel_hi:[0,1,1]
	v_pk_fma_f32 v[104:105], v[136:137], v[116:117], v[104:105] op_sel_hi:[0,1,1]
	v_pk_fma_f32 v[100:101], v[140:141], v[106:107], v[100:101]
	v_mov_b32_dpp v106, v98 row_shl:1 row_mask:0xf bank_mask:0xf bound_ctrl:1
	v_mov_b32_dpp v107, v99 row_shl:1 row_mask:0xf bank_mask:0xf bound_ctrl:1
	v_pk_fma_f32 v[104:105], v[154:155], v[104:105], v[166:167]
	v_pk_fma_f32 v[106:107], v[208:209], v[182:183], v[106:107] op_sel_hi:[0,1,1]
	v_pk_fma_f32 v[98:99], v[98:99], v[158:159], v[104:105]
	v_pk_mul_f32 v[96:97], v[96:97], v[108:109]
	v_pk_fma_f32 v[98:99], v[162:163], v[106:107], v[98:99]
	v_pk_mul_f32 v[96:97], v[100:101], v[96:97]
	v_mul_f32_e32 v101, 0xbfb8aa3b, v98
	v_mul_f32_e32 v107, 0xbfb8aa3b, v99
	v_exp_f32_e32 v106, v101
	v_exp_f32_e32 v107, v107
	v_mov_b32_dpp v100, v102 row_shr:1 row_mask:0xf bank_mask:0xf bound_ctrl:1
	v_mov_b32_dpp v101, v103 row_shr:1 row_mask:0xf bank_mask:0xf bound_ctrl:1
	v_add_f32_e32 v106, 1.0, v106
	v_add_f32_e32 v107, 1.0, v107
	v_rcp_f32_e32 v106, v106
	v_rcp_f32_e32 v107, v107
	v_pk_fma_f32 v[100:101], v[136:137], v[112:113], v[100:101] op_sel_hi:[0,1,1]
	v_mov_b32_dpp v104, v102 row_shl:1 row_mask:0xf bank_mask:0xf bound_ctrl:1
	v_mov_b32_dpp v105, v103 row_shl:1 row_mask:0xf bank_mask:0xf bound_ctrl:1
	v_pk_fma_f32 v[100:101], v[130:131], v[100:101], v[150:151]
	v_pk_fma_f32 v[104:105], v[208:209], v[178:179], v[104:105] op_sel_hi:[0,1,1]
	v_pk_fma_f32 v[100:101], v[102:103], v[134:135], v[100:101]
	v_pk_mul_f32 v[98:99], v[98:99], v[106:107]
	v_pk_fma_f32 v[100:101], v[142:143], v[104:105], v[100:101]
	v_cvt_pk_bf16_f32 v96, v96, v97
	v_pk_mul_f32 v[98:99], v[100:101], v[98:99]
	s_nop 0
	v_cvt_pk_bf16_f32 v97, v98, v99
	v_lshl_add_u64 v[98:99], v[184:185], 0, 48
	v_mad_u64_u32 v[124:125], s[2:3], v98, s4, v[216:217]
	v_mad_i32_i24 v125, v99, s4, v125
	global_store_dwordx2 v[124:125], v[96:97], off nt
	v_cndmask_b32_e64 v96, 0, 1, s[12:13]
	v_cmp_ne_u32_e64 s[4:5], 1, v96
	s_andn2_b64 vcc, exec, s[12:13]
	s_mov_b64 s[2:3], -1
	s_cbranch_vccnz .LBB0_734
	v_mov_b64_e32 v[96:97], v[168:169]
	v_mov_b64_e32 v[100:101], v[172:173]
	s_mov_b64 s[2:3], 0
	v_mov_b64_e32 v[98:99], v[170:171]
	v_mov_b64_e32 v[102:103], v[174:175]

.LBB0_740:
	v_mov_b32_e32 v137, v136
	v_mov_b32_dpp v110, v88 row_shr:1 row_mask:0xf bank_mask:0xf bound_ctrl:1
	v_mov_b32_dpp v111, v89 row_shr:1 row_mask:0xf bank_mask:0xf bound_ctrl:1
	s_waitcnt lgkmcnt(0)
	v_pk_fma_f32 v[100:101], v[136:137], v[100:101], v[110:111]
	v_mov_b32_e32 v209, v208
	v_mov_b32_dpp v106, v80 row_mirror row_mask:0xf bank_mask:0xf bound_ctrl:1
	v_mov_b32_dpp v114, v88 row_shl:1 row_mask:0xf bank_mask:0xf bound_ctrl:1
	v_mov_b32_dpp v107, v81 row_mirror row_mask:0xf bank_mask:0xf bound_ctrl:1
	v_mov_b32_dpp v115, v89 row_shl:1 row_mask:0xf bank_mask:0xf bound_ctrl:1
	v_pk_fma_f32 v[100:101], v[152:153], v[100:101], v[164:165]
	v_pk_fma_f32 v[110:111], v[208:209], v[106:107], v[114:115]
	v_pk_fma_f32 v[100:101], v[88:89], v[156:157], v[100:101]
	v_mov_b32_dpp v108, v92 row_shr:1 row_mask:0xf bank_mask:0xf bound_ctrl:1
	v_pk_fma_f32 v[100:101], v[160:161], v[110:111], v[100:101]
	v_mov_b32_dpp v109, v93 row_shr:1 row_mask:0xf bank_mask:0xf bound_ctrl:1
	v_mul_f32_e32 v105, 0xbfb8aa3b, v100
	v_mul_f32_e32 v111, 0xbfb8aa3b, v101
	v_exp_f32_e32 v110, v105
	v_exp_f32_e32 v111, v111
	v_pk_fma_f32 v[96:97], v[136:137], v[96:97], v[108:109]
	v_mov_b32_dpp v104, v84 row_mirror row_mask:0xf bank_mask:0xf bound_ctrl:1
	v_add_f32_e32 v110, 1.0, v110
	v_add_f32_e32 v111, 1.0, v111
	v_rcp_f32_e32 v110, v110
	v_rcp_f32_e32 v111, v111
	v_mov_b32_dpp v112, v92 row_shl:1 row_mask:0xf bank_mask:0xf bound_ctrl:1
	v_mov_b32_dpp v105, v85 row_mirror row_mask:0xf bank_mask:0xf bound_ctrl:1
	v_mov_b32_dpp v113, v93 row_shl:1 row_mask:0xf bank_mask:0xf bound_ctrl:1
	v_pk_fma_f32 v[96:97], v[128:129], v[96:97], v[148:149]
	v_pk_fma_f32 v[108:109], v[208:209], v[104:105], v[112:113]
	v_pk_fma_f32 v[96:97], v[92:93], v[132:133], v[96:97]
	v_mov_b32_dpp v112, v90 row_shr:1 row_mask:0xf bank_mask:0xf bound_ctrl:1
	v_mov_b32_dpp v113, v91 row_shr:1 row_mask:0xf bank_mask:0xf bound_ctrl:1
	v_pk_fma_f32 v[96:97], v[140:141], v[108:109], v[96:97]
	v_pk_mul_f32 v[100:101], v[100:101], v[110:111]
	v_pk_fma_f32 v[102:103], v[136:137], v[102:103], v[112:113]
	v_pk_mul_f32 v[108:109], v[96:97], v[100:101]
	v_mov_b32_dpp v100, v82 row_mirror row_mask:0xf bank_mask:0xf bound_ctrl:1
	v_mov_b32_dpp v116, v90 row_shl:1 row_mask:0xf bank_mask:0xf bound_ctrl:1
	v_mov_b32_dpp v101, v83 row_mirror row_mask:0xf bank_mask:0xf bound_ctrl:1
	v_mov_b32_dpp v117, v91 row_shl:1 row_mask:0xf bank_mask:0xf bound_ctrl:1
	v_pk_fma_f32 v[102:103], v[154:155], v[102:103], v[166:167]
	v_pk_fma_f32 v[112:113], v[208:209], v[100:101], v[116:117]
	v_pk_fma_f32 v[102:103], v[90:91], v[158:159], v[102:103]
	v_mov_b32_dpp v110, v94 row_shr:1 row_mask:0xf bank_mask:0xf bound_ctrl:1
	v_pk_fma_f32 v[102:103], v[162:163], v[112:113], v[102:103]
	v_mov_b32_dpp v111, v95 row_shr:1 row_mask:0xf bank_mask:0xf bound_ctrl:1
	v_mul_f32_e32 v97, 0xbfb8aa3b, v102
	v_mul_f32_e32 v113, 0xbfb8aa3b, v103
	v_exp_f32_e32 v112, v97
	v_exp_f32_e32 v113, v113
	v_pk_fma_f32 v[98:99], v[136:137], v[98:99], v[110:111]
	v_mov_b32_dpp v96, v86 row_mirror row_mask:0xf bank_mask:0xf bound_ctrl:1
	v_add_f32_e32 v112, 1.0, v112
	v_add_f32_e32 v113, 1.0, v113
	v_rcp_f32_e32 v112, v112
	v_rcp_f32_e32 v113, v113
	v_mov_b32_dpp v114, v94 row_shl:1 row_mask:0xf bank_mask:0xf bound_ctrl:1
	v_mov_b32_dpp v97, v87 row_mirror row_mask:0xf bank_mask:0xf bound_ctrl:1
	v_mov_b32_dpp v115, v95 row_shl:1 row_mask:0xf bank_mask:0xf bound_ctrl:1
	v_pk_fma_f32 v[98:99], v[130:131], v[98:99], v[150:151]
	v_pk_fma_f32 v[110:111], v[208:209], v[96:97], v[114:115]
	v_pk_fma_f32 v[98:99], v[94:95], v[134:135], v[98:99]
	v_pk_mul_f32 v[102:103], v[102:103], v[112:113]
	v_pk_fma_f32 v[98:99], v[142:143], v[110:111], v[98:99]
	s_movk_i32 s10, 0x1600
	v_pk_mul_f32 v[98:99], v[98:99], v[102:103]
	v_cvt_pk_bf16_f32 v102, v108, v109
	v_cvt_pk_bf16_f32 v103, v98, v99
	v_lshl_add_u64 v[98:99], v[184:185], 0, s[38:39]
	v_mad_u64_u32 v[126:127], s[2:3], v98, s10, v[216:217]
	v_mov_b32_e32 v98, v127
	v_mad_u64_u32 v[98:99], s[2:3], v99, s10, v[98:99]
	v_mov_b32_e32 v127, v98
	global_store_dwordx2 v[126:127], v[102:103], off nt
	v_mov_b32_dpp v102, v88 row_mirror row_mask:0xf bank_mask:0xf bound_ctrl:1
	v_mov_b32_dpp v110, v80 row_shr:1 row_mask:0xf bank_mask:0xf bound_ctrl:1
	v_mov_b32_dpp v103, v89 row_mirror row_mask:0xf bank_mask:0xf bound_ctrl:1
	v_mov_b32_dpp v111, v81 row_shr:1 row_mask:0xf bank_mask:0xf bound_ctrl:1
	v_pk_fma_f32 v[102:103], v[136:137], v[102:103], v[110:111]
	v_mov_b32_dpp v98, v92 row_mirror row_mask:0xf bank_mask:0xf bound_ctrl:1
	v_mov_b32_dpp v92, v72 row_mirror row_mask:0xf bank_mask:0xf bound_ctrl:1
	v_mov_b32_dpp v114, v80 row_shl:1 row_mask:0xf bank_mask:0xf bound_ctrl:1
	v_mov_b32_dpp v99, v93 row_mirror row_mask:0xf bank_mask:0xf bound_ctrl:1
	v_mov_b32_dpp v93, v73 row_mirror row_mask:0xf bank_mask:0xf bound_ctrl:1
	v_mov_b32_dpp v115, v81 row_shl:1 row_mask:0xf bank_mask:0xf bound_ctrl:1
	v_pk_fma_f32 v[102:103], v[152:153], v[102:103], v[164:165]
	v_pk_fma_f32 v[110:111], v[208:209], v[92:93], v[114:115]
	v_pk_fma_f32 v[80:81], v[80:81], v[156:157], v[102:103]
	v_mov_b32_dpp v108, v84 row_shr:1 row_mask:0xf bank_mask:0xf bound_ctrl:1
	v_pk_fma_f32 v[80:81], v[160:161], v[110:111], v[80:81]
	v_mov_b32_dpp v109, v85 row_shr:1 row_mask:0xf bank_mask:0xf bound_ctrl:1
	v_mul_f32_e32 v89, 0xbfb8aa3b, v80
	v_mul_f32_e32 v103, 0xbfb8aa3b, v81
	v_exp_f32_e32 v102, v89
	v_exp_f32_e32 v103, v103
	v_pk_fma_f32 v[98:99], v[136:137], v[98:99], v[108:109]
	v_mov_b32_dpp v88, v76 row_mirror row_mask:0xf bank_mask:0xf bound_ctrl:1
	v_add_f32_e32 v102, 1.0, v102
	v_add_f32_e32 v103, 1.0, v103
	v_rcp_f32_e32 v102, v102
	v_rcp_f32_e32 v103, v103
	v_mov_b32_dpp v112, v84 row_shl:1 row_mask:0xf bank_mask:0xf bound_ctrl:1
	v_mov_b32_dpp v89, v77 row_mirror row_mask:0xf bank_mask:0xf bound_ctrl:1
	v_mov_b32_dpp v113, v85 row_shl:1 row_mask:0xf bank_mask:0xf bound_ctrl:1
	v_pk_fma_f32 v[98:99], v[128:129], v[98:99], v[148:149]
	v_pk_fma_f32 v[108:109], v[208:209], v[88:89], v[112:113]
	v_pk_fma_f32 v[84:85], v[84:85], v[132:133], v[98:99]
	v_mov_b32_dpp v90, v90 row_mirror row_mask:0xf bank_mask:0xf bound_ctrl:1
	v_pk_fma_f32 v[84:85], v[140:141], v[108:109], v[84:85]
	v_mov_b32_dpp v108, v82 row_shr:1 row_mask:0xf bank_mask:0xf bound_ctrl:1
	v_mov_b32_dpp v91, v91 row_mirror row_mask:0xf bank_mask:0xf bound_ctrl:1
	v_mov_b32_dpp v109, v83 row_shr:1 row_mask:0xf bank_mask:0xf bound_ctrl:1
	v_pk_mul_f32 v[80:81], v[80:81], v[102:103]
	v_pk_fma_f32 v[90:91], v[136:137], v[90:91], v[108:109]
	v_pk_mul_f32 v[98:99], v[84:85], v[80:81]
	v_mov_b32_dpp v84, v74 row_mirror row_mask:0xf bank_mask:0xf bound_ctrl:1
	v_mov_b32_dpp v112, v82 row_shl:1 row_mask:0xf bank_mask:0xf bound_ctrl:1
	v_mov_b32_dpp v85, v75 row_mirror row_mask:0xf bank_mask:0xf bound_ctrl:1
	v_mov_b32_dpp v113, v83 row_shl:1 row_mask:0xf bank_mask:0xf bound_ctrl:1
	v_pk_fma_f32 v[90:91], v[154:155], v[90:91], v[166:167]
	v_pk_fma_f32 v[108:109], v[208:209], v[84:85], v[112:113]
	v_pk_fma_f32 v[82:83], v[82:83], v[158:159], v[90:91]
	v_mov_b32_dpp v94, v94 row_mirror row_mask:0xf bank_mask:0xf bound_ctrl:1
	v_pk_fma_f32 v[82:83], v[162:163], v[108:109], v[82:83]
	v_mov_b32_dpp v102, v86 row_shr:1 row_mask:0xf bank_mask:0xf bound_ctrl:1
	v_mul_f32_e32 v81, 0xbfb8aa3b, v82
	v_mul_f32_e32 v91, 0xbfb8aa3b, v83
	v_exp_f32_e32 v90, v81
	v_exp_f32_e32 v91, v91
	v_mov_b32_dpp v95, v95 row_mirror row_mask:0xf bank_mask:0xf bound_ctrl:1
	v_mov_b32_dpp v103, v87 row_shr:1 row_mask:0xf bank_mask:0xf bound_ctrl:1
	v_add_f32_e32 v90, 1.0, v90
	v_add_f32_e32 v91, 1.0, v91
	v_rcp_f32_e32 v90, v90
	v_rcp_f32_e32 v91, v91
	v_pk_fma_f32 v[94:95], v[136:137], v[94:95], v[102:103]
	v_mov_b32_dpp v80, v78 row_mirror row_mask:0xf bank_mask:0xf bound_ctrl:1
	v_mov_b32_dpp v110, v86 row_shl:1 row_mask:0xf bank_mask:0xf bound_ctrl:1
	v_mov_b32_dpp v81, v79 row_mirror row_mask:0xf bank_mask:0xf bound_ctrl:1
	v_mov_b32_dpp v111, v87 row_shl:1 row_mask:0xf bank_mask:0xf bound_ctrl:1
	v_pk_fma_f32 v[94:95], v[130:131], v[94:95], v[150:151]
	v_pk_fma_f32 v[102:103], v[208:209], v[80:81], v[110:111]
	v_pk_fma_f32 v[86:87], v[86:87], v[134:135], v[94:95]
	v_pk_mul_f32 v[82:83], v[82:83], v[90:91]
	v_pk_fma_f32 v[86:87], v[142:143], v[102:103], v[86:87]
	s_mov_b64 s[2:3], 0x90
	v_pk_mul_f32 v[82:83], v[86:87], v[82:83]
	v_cvt_pk_bf16_f32 v86, v98, v99
	v_cvt_pk_bf16_f32 v87, v82, v83
	v_lshl_add_u64 v[82:83], v[184:185], 0, s[2:3]
	v_mad_u64_u32 v[176:177], s[2:3], v82, s10, v[216:217]
	v_mov_b32_e32 v82, v177
	v_mad_u64_u32 v[82:83], s[2:3], v83, s10, v[82:83]
	v_mov_b32_e32 v177, v82
	global_store_dwordx2 v[176:177], v[86:87], off nt
	v_mov_b32_dpp v94, v72 row_shr:1 row_mask:0xf bank_mask:0xf bound_ctrl:1
	v_mov_b32_dpp v95, v73 row_shr:1 row_mask:0xf bank_mask:0xf bound_ctrl:1
	v_pk_fma_f32 v[94:95], v[136:137], v[106:107], v[94:95]
	v_mov_b32_dpp v86, v64 row_mirror row_mask:0xf bank_mask:0xf bound_ctrl:1
	v_mov_b32_dpp v102, v72 row_shl:1 row_mask:0xf bank_mask:0xf bound_ctrl:1
	v_mov_b32_dpp v87, v65 row_mirror row_mask:0xf bank_mask:0xf bound_ctrl:1
	v_mov_b32_dpp v103, v73 row_shl:1 row_mask:0xf bank_mask:0xf bound_ctrl:1
	v_pk_fma_f32 v[94:95], v[152:153], v[94:95], v[164:165]
	v_pk_fma_f32 v[86:87], v[208:209], v[86:87], v[102:103]
	v_pk_fma_f32 v[72:73], v[72:73], v[156:157], v[94:95]
	v_mov_b32_dpp v90, v76 row_shr:1 row_mask:0xf bank_mask:0xf bound_ctrl:1
	v_pk_fma_f32 v[72:73], v[160:161], v[86:87], v[72:73]
	v_mov_b32_dpp v91, v77 row_shr:1 row_mask:0xf bank_mask:0xf bound_ctrl:1
	v_mul_f32_e32 v83, 0xbfb8aa3b, v72
	v_mul_f32_e32 v87, 0xbfb8aa3b, v73
	v_exp_f32_e32 v86, v83
	v_exp_f32_e32 v87, v87
	v_pk_fma_f32 v[90:91], v[136:137], v[104:105], v[90:91]
	v_mov_b32_dpp v82, v68 row_mirror row_mask:0xf bank_mask:0xf bound_ctrl:1
	v_add_f32_e32 v86, 1.0, v86
	v_add_f32_e32 v87, 1.0, v87
	v_pk_fma_f32 v[90:91], v[128:129], v[90:91], v[148:149]
	v_mov_b32_dpp v98, v76 row_shl:1 row_mask:0xf bank_mask:0xf bound_ctrl:1
	v_mov_b32_dpp v83, v69 row_mirror row_mask:0xf bank_mask:0xf bound_ctrl:1
	v_mov_b32_dpp v99, v77 row_shl:1 row_mask:0xf bank_mask:0xf bound_ctrl:1
	v_rcp_f32_e32 v86, v86
	v_rcp_f32_e32 v87, v87
	v_pk_fma_f32 v[76:77], v[76:77], v[132:133], v[90:91]
	v_mov_b32_dpp v90, v74 row_shr:1 row_mask:0xf bank_mask:0xf bound_ctrl:1
	v_mov_b32_dpp v91, v75 row_shr:1 row_mask:0xf bank_mask:0xf bound_ctrl:1
	v_pk_fma_f32 v[82:83], v[208:209], v[82:83], v[98:99]
	v_pk_fma_f32 v[90:91], v[136:137], v[100:101], v[90:91]
	v_pk_fma_f32 v[76:77], v[140:141], v[82:83], v[76:77]
	v_mov_b32_dpp v82, v66 row_mirror row_mask:0xf bank_mask:0xf bound_ctrl:1
	v_mov_b32_dpp v98, v74 row_shl:1 row_mask:0xf bank_mask:0xf bound_ctrl:1
	v_mov_b32_dpp v83, v67 row_mirror row_mask:0xf bank_mask:0xf bound_ctrl:1
	v_mov_b32_dpp v99, v75 row_shl:1 row_mask:0xf bank_mask:0xf bound_ctrl:1
	v_pk_fma_f32 v[90:91], v[154:155], v[90:91], v[166:167]
	v_pk_fma_f32 v[82:83], v[208:209], v[82:83], v[98:99]
	v_pk_fma_f32 v[74:75], v[74:75], v[158:159], v[90:91]
	v_pk_mul_f32 v[72:73], v[72:73], v[86:87]
	v_pk_fma_f32 v[74:75], v[162:163], v[82:83], v[74:75]
	v_pk_mul_f32 v[72:73], v[76:77], v[72:73]
	v_mul_f32_e32 v77, 0xbfb8aa3b, v74
	v_mul_f32_e32 v83, 0xbfb8aa3b, v75
	v_exp_f32_e32 v82, v77
	v_exp_f32_e32 v83, v83
	v_mov_b32_dpp v86, v78 row_shr:1 row_mask:0xf bank_mask:0xf bound_ctrl:1
	v_mov_b32_dpp v87, v79 row_shr:1 row_mask:0xf bank_mask:0xf bound_ctrl:1
	v_add_f32_e32 v82, 1.0, v82
	v_add_f32_e32 v83, 1.0, v83
	v_rcp_f32_e32 v82, v82
	v_rcp_f32_e32 v83, v83
	v_pk_fma_f32 v[86:87], v[136:137], v[96:97], v[86:87]
	v_mov_b32_dpp v76, v70 row_mirror row_mask:0xf bank_mask:0xf bound_ctrl:1
	v_mov_b32_dpp v94, v78 row_shl:1 row_mask:0xf bank_mask:0xf bound_ctrl:1
	v_mov_b32_dpp v77, v71 row_mirror row_mask:0xf bank_mask:0xf bound_ctrl:1
	v_mov_b32_dpp v95, v79 row_shl:1 row_mask:0xf bank_mask:0xf bound_ctrl:1
	v_pk_fma_f32 v[86:87], v[130:131], v[86:87], v[150:151]
	v_pk_fma_f32 v[76:77], v[208:209], v[76:77], v[94:95]
	v_pk_fma_f32 v[78:79], v[78:79], v[134:135], v[86:87]
	v_pk_mul_f32 v[74:75], v[74:75], v[82:83]
	v_pk_fma_f32 v[76:77], v[142:143], v[76:77], v[78:79]
	s_mov_b64 s[2:3], 0xa0
	v_pk_mul_f32 v[74:75], v[76:77], v[74:75]
	v_cvt_pk_bf16_f32 v72, v72, v73
	v_cvt_pk_bf16_f32 v73, v74, v75
	v_lshl_add_u64 v[74:75], v[184:185], 0, s[2:3]
	v_mad_u64_u32 v[178:179], s[2:3], v74, s10, v[216:217]
	v_mov_b32_e32 v74, v179
	v_mad_u64_u32 v[74:75], s[2:3], v75, s10, v[74:75]
	v_mov_b32_e32 v179, v74
	global_store_dwordx2 v[178:179], v[72:73], off nt
	v_mov_b32_dpp v74, v64 row_shr:1 row_mask:0xf bank_mask:0xf bound_ctrl:1
	v_mov_b32_dpp v75, v65 row_shr:1 row_mask:0xf bank_mask:0xf bound_ctrl:1
	v_pk_fma_f32 v[74:75], v[136:137], v[92:93], v[74:75]
	v_mov_b32_dpp v76, v64 row_shl:1 row_mask:0xf bank_mask:0xf bound_ctrl:1
	v_mov_b32_dpp v77, v65 row_shl:1 row_mask:0xf bank_mask:0xf bound_ctrl:1
	v_pk_fma_f32 v[74:75], v[152:153], v[74:75], v[164:165]
	v_pk_fma_f32 v[76:77], v[208:209], v[172:173], v[76:77]
	v_pk_fma_f32 v[64:65], v[64:65], v[156:157], v[74:75]
	v_mov_b32_dpp v72, v68 row_shr:1 row_mask:0xf bank_mask:0xf bound_ctrl:1
	v_pk_fma_f32 v[64:65], v[160:161], v[76:77], v[64:65]
	v_mov_b32_dpp v74, v68 row_shl:1 row_mask:0xf bank_mask:0xf bound_ctrl:1
	v_mul_f32_e32 v73, 0xbfb8aa3b, v64
	v_mul_f32_e32 v77, 0xbfb8aa3b, v65
	v_exp_f32_e32 v76, v73
	v_exp_f32_e32 v77, v77
	v_mov_b32_dpp v73, v69 row_shr:1 row_mask:0xf bank_mask:0xf bound_ctrl:1
	v_pk_fma_f32 v[72:73], v[136:137], v[88:89], v[72:73]
	v_add_f32_e32 v76, 1.0, v76
	v_add_f32_e32 v77, 1.0, v77
	v_pk_fma_f32 v[72:73], v[128:129], v[72:73], v[148:149]
	v_mov_b32_dpp v75, v69 row_shl:1 row_mask:0xf bank_mask:0xf bound_ctrl:1
	v_rcp_f32_e32 v76, v76
	v_rcp_f32_e32 v77, v77
	v_pk_fma_f32 v[68:69], v[68:69], v[132:133], v[72:73]
	v_mov_b32_dpp v72, v66 row_shr:1 row_mask:0xf bank_mask:0xf bound_ctrl:1
	v_mov_b32_dpp v73, v67 row_shr:1 row_mask:0xf bank_mask:0xf bound_ctrl:1
	v_pk_fma_f32 v[74:75], v[208:209], v[168:169], v[74:75]
	v_pk_fma_f32 v[72:73], v[136:137], v[84:85], v[72:73]
	v_pk_fma_f32 v[68:69], v[140:141], v[74:75], v[68:69]
	v_mov_b32_dpp v74, v66 row_shl:1 row_mask:0xf bank_mask:0xf bound_ctrl:1
	v_mov_b32_dpp v75, v67 row_shl:1 row_mask:0xf bank_mask:0xf bound_ctrl:1
	v_pk_fma_f32 v[72:73], v[154:155], v[72:73], v[166:167]
	v_pk_fma_f32 v[74:75], v[208:209], v[174:175], v[74:75]
	v_pk_fma_f32 v[66:67], v[66:67], v[158:159], v[72:73]
	v_pk_mul_f32 v[64:65], v[64:65], v[76:77]
	v_pk_fma_f32 v[66:67], v[162:163], v[74:75], v[66:67]
	v_pk_mul_f32 v[64:65], v[68:69], v[64:65]
	v_mul_f32_e32 v69, 0xbfb8aa3b, v66
	v_mul_f32_e32 v75, 0xbfb8aa3b, v67
	v_exp_f32_e32 v74, v69
	v_exp_f32_e32 v75, v75
	v_mov_b32_dpp v68, v70 row_shr:1 row_mask:0xf bank_mask:0xf bound_ctrl:1
	v_mov_b32_dpp v69, v71 row_shr:1 row_mask:0xf bank_mask:0xf bound_ctrl:1
	v_add_f32_e32 v74, 1.0, v74
	v_add_f32_e32 v75, 1.0, v75
	v_rcp_f32_e32 v74, v74
	v_rcp_f32_e32 v75, v75
	v_pk_fma_f32 v[68:69], v[136:137], v[80:81], v[68:69]
	v_mov_b32_dpp v72, v70 row_shl:1 row_mask:0xf bank_mask:0xf bound_ctrl:1
	v_mov_b32_dpp v73, v71 row_shl:1 row_mask:0xf bank_mask:0xf bound_ctrl:1
	v_pk_fma_f32 v[68:69], v[130:131], v[68:69], v[150:151]
	v_pk_fma_f32 v[72:73], v[208:209], v[170:171], v[72:73]
	v_pk_fma_f32 v[68:69], v[70:71], v[134:135], v[68:69]
	v_pk_mul_f32 v[66:67], v[66:67], v[74:75]
	v_pk_fma_f32 v[68:69], v[142:143], v[72:73], v[68:69]
	s_mov_b64 s[2:3], 0xb0
	v_pk_mul_f32 v[66:67], v[68:69], v[66:67]
	v_cvt_pk_bf16_f32 v64, v64, v65
	v_cvt_pk_bf16_f32 v65, v66, v67
	v_lshl_add_u64 v[66:67], v[184:185], 0, s[2:3]
	v_mad_u64_u32 v[128:129], s[2:3], v66, s10, v[216:217]
	v_mov_b32_e32 v66, v129
	v_mad_u64_u32 v[66:67], s[2:3], v67, s10, v[66:67]
	v_mov_b32_e32 v129, v66
	global_store_dwordx2 v[128:129], v[64:65], off nt
	v_or_b32_e32 v64, 4, v212
	v_ashrrev_i32_e32 v65, 31, v64
	v_lshlrev_b64 v[76:77], 2, v[64:65]
	v_lshl_add_u64 v[68:69], s[80:81], 0, v[76:77]
	global_load_dwordx4 v[64:67], v[214:215], off offset:16
	global_load_dwordx4 v[84:87], v[68:69], off
	v_lshl_add_u64 v[68:69], s[78:79], 0, v[76:77]
	v_lshl_add_u64 v[70:71], s[70:71], 0, v[76:77]
	global_load_dwordx4 v[88:91], v[68:69], off
	global_load_dwordx4 v[92:95], v[70:71], off
	v_lshl_add_u64 v[68:69], s[74:75], 0, v[76:77]
	v_lshl_add_u64 v[70:71], s[76:77], 0, v[76:77]
	global_load_dwordx4 v[96:99], v[68:69], off
	s_nop 0
	global_load_dwordx4 v[68:71], v[70:71], off
	s_nop 0
	global_load_dwordx4 v[72:75], v[210:211], off offset:16
	v_lshl_add_u64 v[76:77], s[72:73], 0, v[76:77]
	global_load_dwordx4 v[76:79], v[76:77], off
	s_mov_b64 s[2:3], -1
	s_andn2_b64 vcc, exec, s[58:59]
	v_lshlrev_b32_e32 v80, 16, v146
	v_and_b32_e32 v81, 0xffff0000, v146
	v_lshlrev_b32_e32 v82, 16, v147
	v_and_b32_e32 v83, 0xffff0000, v147
	v_lshlrev_b32_e32 v100, 16, v138
	v_and_b32_e32 v101, 0xffff0000, v138
	v_lshlrev_b32_e32 v102, 16, v139
	v_and_b32_e32 v103, 0xffff0000, v139
	s_cbranch_vccnz .LBB0_742
	v_mov_b64_e32 v[114:115], v[82:83]
	v_mov_b64_e32 v[118:119], v[102:103]
	v_mov_b64_e32 v[112:113], v[80:81]
	v_mov_b64_e32 v[116:117], v[100:101]
	s_cbranch_execnz .LBB0_744
	s_branch .LBB0_743

.LBB0_748:
	v_mov_b32_dpp v138, v56 row_shr:1 row_mask:0xf bank_mask:0xf bound_ctrl:1
	v_mov_b32_dpp v139, v57 row_shr:1 row_mask:0xf bank_mask:0xf bound_ctrl:1
	s_waitcnt lgkmcnt(0)
	v_pk_fma_f32 v[116:117], v[136:137], v[116:117], v[138:139]
	v_mov_b32_dpp v132, v48 row_mirror row_mask:0xf bank_mask:0xf bound_ctrl:1
	v_mov_b32_dpp v142, v56 row_shl:1 row_mask:0xf bank_mask:0xf bound_ctrl:1
	v_mov_b32_dpp v133, v49 row_mirror row_mask:0xf bank_mask:0xf bound_ctrl:1
	v_mov_b32_dpp v143, v57 row_shl:1 row_mask:0xf bank_mask:0xf bound_ctrl:1
	s_waitcnt vmcnt(4)
	v_pk_fma_f32 v[116:117], v[92:93], v[116:117], v[84:85]
	v_pk_fma_f32 v[138:139], v[208:209], v[132:133], v[142:143]
	s_waitcnt vmcnt(3)
	v_pk_fma_f32 v[116:117], v[56:57], v[96:97], v[116:117]
	v_mov_b32_dpp v134, v60 row_shr:1 row_mask:0xf bank_mask:0xf bound_ctrl:1
	v_pk_fma_f32 v[116:117], v[88:89], v[138:139], v[116:117]
	v_mov_b32_dpp v135, v61 row_shr:1 row_mask:0xf bank_mask:0xf bound_ctrl:1
	v_mul_f32_e32 v131, 0xbfb8aa3b, v116
	v_mul_f32_e32 v139, 0xbfb8aa3b, v117
	v_exp_f32_e32 v138, v131
	v_exp_f32_e32 v139, v139
	v_pk_fma_f32 v[112:113], v[136:137], v[112:113], v[134:135]
	v_mov_b32_dpp v130, v52 row_mirror row_mask:0xf bank_mask:0xf bound_ctrl:1
	v_add_f32_e32 v138, 1.0, v138
	v_add_f32_e32 v139, 1.0, v139
	v_rcp_f32_e32 v138, v138
	v_rcp_f32_e32 v139, v139
	v_mov_b32_dpp v140, v60 row_shl:1 row_mask:0xf bank_mask:0xf bound_ctrl:1
	v_mov_b32_dpp v131, v53 row_mirror row_mask:0xf bank_mask:0xf bound_ctrl:1
	v_mov_b32_dpp v141, v61 row_shl:1 row_mask:0xf bank_mask:0xf bound_ctrl:1
	s_waitcnt vmcnt(1)
	v_pk_fma_f32 v[112:113], v[72:73], v[112:113], v[64:65]
	v_pk_fma_f32 v[134:135], v[208:209], v[130:131], v[140:141]
	s_waitcnt vmcnt(0)
	v_pk_fma_f32 v[112:113], v[60:61], v[76:77], v[112:113]
	v_mov_b32_dpp v140, v58 row_shr:1 row_mask:0xf bank_mask:0xf bound_ctrl:1
	v_mov_b32_dpp v141, v59 row_shr:1 row_mask:0xf bank_mask:0xf bound_ctrl:1
	v_pk_fma_f32 v[112:113], v[68:69], v[134:135], v[112:113]
	v_pk_mul_f32 v[116:117], v[116:117], v[138:139]
	v_pk_fma_f32 v[118:119], v[136:137], v[118:119], v[140:141]
	v_pk_mul_f32 v[134:135], v[112:113], v[116:117]
	v_mov_b32_dpp v116, v50 row_mirror row_mask:0xf bank_mask:0xf bound_ctrl:1
	v_mov_b32_dpp v146, v58 row_shl:1 row_mask:0xf bank_mask:0xf bound_ctrl:1
	v_mov_b32_dpp v117, v51 row_mirror row_mask:0xf bank_mask:0xf bound_ctrl:1
	v_mov_b32_dpp v147, v59 row_shl:1 row_mask:0xf bank_mask:0xf bound_ctrl:1
	v_pk_fma_f32 v[118:119], v[94:95], v[118:119], v[86:87]
	v_pk_fma_f32 v[140:141], v[208:209], v[116:117], v[146:147]
	v_pk_fma_f32 v[118:119], v[58:59], v[98:99], v[118:119]
	v_mov_b32_dpp v138, v62 row_shr:1 row_mask:0xf bank_mask:0xf bound_ctrl:1
	v_pk_fma_f32 v[118:119], v[90:91], v[140:141], v[118:119]
	v_mov_b32_dpp v139, v63 row_shr:1 row_mask:0xf bank_mask:0xf bound_ctrl:1
	v_mul_f32_e32 v113, 0xbfb8aa3b, v118
	v_mul_f32_e32 v141, 0xbfb8aa3b, v119
	v_exp_f32_e32 v140, v113
	v_exp_f32_e32 v141, v141
	v_pk_fma_f32 v[114:115], v[136:137], v[114:115], v[138:139]
	v_mov_b32_dpp v112, v54 row_mirror row_mask:0xf bank_mask:0xf bound_ctrl:1
	v_add_f32_e32 v140, 1.0, v140
	v_add_f32_e32 v141, 1.0, v141
	v_rcp_f32_e32 v140, v140
	v_rcp_f32_e32 v141, v141
	v_mov_b32_dpp v142, v62 row_shl:1 row_mask:0xf bank_mask:0xf bound_ctrl:1
	v_mov_b32_dpp v113, v55 row_mirror row_mask:0xf bank_mask:0xf bound_ctrl:1
	v_mov_b32_dpp v143, v63 row_shl:1 row_mask:0xf bank_mask:0xf bound_ctrl:1
	v_pk_fma_f32 v[114:115], v[74:75], v[114:115], v[66:67]
	v_pk_fma_f32 v[138:139], v[208:209], v[112:113], v[142:143]
	v_pk_fma_f32 v[114:115], v[62:63], v[78:79], v[114:115]
	v_pk_mul_f32 v[118:119], v[118:119], v[140:141]
	v_pk_fma_f32 v[114:115], v[70:71], v[138:139], v[114:115]
	s_nop 0
	v_pk_mul_f32 v[114:115], v[114:115], v[118:119]
	v_cvt_pk_bf16_f32 v118, v134, v135
	v_cvt_pk_bf16_f32 v119, v114, v115
	global_store_dwordx2 v[144:145], v[118:119], off offset:8 nt
	v_mov_b32_dpp v118, v56 row_mirror row_mask:0xf bank_mask:0xf bound_ctrl:1
	v_mov_b32_dpp v138, v48 row_shr:1 row_mask:0xf bank_mask:0xf bound_ctrl:1
	v_mov_b32_dpp v119, v57 row_mirror row_mask:0xf bank_mask:0xf bound_ctrl:1
	v_mov_b32_dpp v139, v49 row_shr:1 row_mask:0xf bank_mask:0xf bound_ctrl:1
	v_pk_fma_f32 v[118:119], v[136:137], v[118:119], v[138:139]
	v_mov_b32_dpp v114, v60 row_mirror row_mask:0xf bank_mask:0xf bound_ctrl:1
	v_mov_b32_dpp v60, v40 row_mirror row_mask:0xf bank_mask:0xf bound_ctrl:1
	v_mov_b32_dpp v142, v48 row_shl:1 row_mask:0xf bank_mask:0xf bound_ctrl:1
	v_mov_b32_dpp v115, v61 row_mirror row_mask:0xf bank_mask:0xf bound_ctrl:1
	v_mov_b32_dpp v61, v41 row_mirror row_mask:0xf bank_mask:0xf bound_ctrl:1
	v_mov_b32_dpp v143, v49 row_shl:1 row_mask:0xf bank_mask:0xf bound_ctrl:1
	v_pk_fma_f32 v[118:119], v[92:93], v[118:119], v[84:85]
	v_pk_fma_f32 v[138:139], v[208:209], v[60:61], v[142:143]
	v_pk_fma_f32 v[48:49], v[48:49], v[96:97], v[118:119]
	v_mov_b32_dpp v134, v52 row_shr:1 row_mask:0xf bank_mask:0xf bound_ctrl:1
	v_pk_fma_f32 v[48:49], v[88:89], v[138:139], v[48:49]
	v_mov_b32_dpp v135, v53 row_shr:1 row_mask:0xf bank_mask:0xf bound_ctrl:1
	v_mul_f32_e32 v57, 0xbfb8aa3b, v48
	v_mul_f32_e32 v119, 0xbfb8aa3b, v49
	v_exp_f32_e32 v118, v57
	v_exp_f32_e32 v119, v119
	v_pk_fma_f32 v[114:115], v[136:137], v[114:115], v[134:135]
	v_mov_b32_dpp v56, v44 row_mirror row_mask:0xf bank_mask:0xf bound_ctrl:1
	v_mov_b32_dpp v140, v52 row_shl:1 row_mask:0xf bank_mask:0xf bound_ctrl:1
	v_mov_b32_dpp v57, v45 row_mirror row_mask:0xf bank_mask:0xf bound_ctrl:1
	v_mov_b32_dpp v141, v53 row_shl:1 row_mask:0xf bank_mask:0xf bound_ctrl:1
	v_pk_fma_f32 v[114:115], v[72:73], v[114:115], v[64:65]
	v_add_f32_e32 v118, 1.0, v118
	v_pk_fma_f32 v[134:135], v[208:209], v[56:57], v[140:141]
	v_add_f32_e32 v119, 1.0, v119
	v_pk_fma_f32 v[52:53], v[52:53], v[76:77], v[114:115]
	v_rcp_f32_e32 v118, v118
	v_rcp_f32_e32 v119, v119
	v_pk_fma_f32 v[52:53], v[68:69], v[134:135], v[52:53]
	v_mov_b32_dpp v58, v58 row_mirror row_mask:0xf bank_mask:0xf bound_ctrl:1
	v_mov_b32_dpp v134, v50 row_shr:1 row_mask:0xf bank_mask:0xf bound_ctrl:1
	v_mov_b32_dpp v59, v59 row_mirror row_mask:0xf bank_mask:0xf bound_ctrl:1
	v_mov_b32_dpp v135, v51 row_shr:1 row_mask:0xf bank_mask:0xf bound_ctrl:1
	v_pk_fma_f32 v[58:59], v[136:137], v[58:59], v[134:135]
	v_mov_b32_dpp v114, v42 row_mirror row_mask:0xf bank_mask:0xf bound_ctrl:1
	v_mov_b32_dpp v140, v50 row_shl:1 row_mask:0xf bank_mask:0xf bound_ctrl:1
	v_mov_b32_dpp v115, v43 row_mirror row_mask:0xf bank_mask:0xf bound_ctrl:1
	v_mov_b32_dpp v141, v51 row_shl:1 row_mask:0xf bank_mask:0xf bound_ctrl:1
	v_pk_fma_f32 v[58:59], v[94:95], v[58:59], v[86:87]
	v_pk_fma_f32 v[134:135], v[208:209], v[114:115], v[140:141]
	v_pk_fma_f32 v[50:51], v[50:51], v[98:99], v[58:59]
	v_pk_mul_f32 v[48:49], v[48:49], v[118:119]
	v_pk_fma_f32 v[50:51], v[90:91], v[134:135], v[50:51]
	v_pk_mul_f32 v[52:53], v[52:53], v[48:49]
	v_mul_f32_e32 v49, 0xbfb8aa3b, v50
	v_mul_f32_e32 v59, 0xbfb8aa3b, v51
	v_exp_f32_e32 v58, v49
	v_exp_f32_e32 v59, v59
	v_mov_b32_dpp v62, v62 row_mirror row_mask:0xf bank_mask:0xf bound_ctrl:1
	v_mov_b32_dpp v118, v54 row_shr:1 row_mask:0xf bank_mask:0xf bound_ctrl:1
	v_add_f32_e32 v58, 1.0, v58
	v_add_f32_e32 v59, 1.0, v59
	v_mov_b32_dpp v63, v63 row_mirror row_mask:0xf bank_mask:0xf bound_ctrl:1
	v_mov_b32_dpp v119, v55 row_shr:1 row_mask:0xf bank_mask:0xf bound_ctrl:1
	v_rcp_f32_e32 v58, v58
	v_rcp_f32_e32 v59, v59
	v_pk_fma_f32 v[62:63], v[136:137], v[62:63], v[118:119]
	v_mov_b32_dpp v48, v46 row_mirror row_mask:0xf bank_mask:0xf bound_ctrl:1
	v_mov_b32_dpp v138, v54 row_shl:1 row_mask:0xf bank_mask:0xf bound_ctrl:1
	v_mov_b32_dpp v49, v47 row_mirror row_mask:0xf bank_mask:0xf bound_ctrl:1
	v_mov_b32_dpp v139, v55 row_shl:1 row_mask:0xf bank_mask:0xf bound_ctrl:1
	v_pk_fma_f32 v[62:63], v[74:75], v[62:63], v[66:67]
	v_pk_fma_f32 v[118:119], v[208:209], v[48:49], v[138:139]
	v_pk_fma_f32 v[54:55], v[54:55], v[78:79], v[62:63]
	v_pk_mul_f32 v[50:51], v[50:51], v[58:59]
	v_pk_fma_f32 v[54:55], v[70:71], v[118:119], v[54:55]
	v_cvt_pk_bf16_f32 v52, v52, v53
	v_pk_mul_f32 v[50:51], v[54:55], v[50:51]
	s_nop 0
	v_cvt_pk_bf16_f32 v53, v50, v51
	global_store_dwordx2 v[120:121], v[52:53], off offset:8 nt
	v_mov_b32_dpp v58, v40 row_shr:1 row_mask:0xf bank_mask:0xf bound_ctrl:1
	v_mov_b32_dpp v59, v41 row_shr:1 row_mask:0xf bank_mask:0xf bound_ctrl:1
	v_pk_fma_f32 v[58:59], v[136:137], v[132:133], v[58:59]
	v_mov_b32_dpp v52, v32 row_mirror row_mask:0xf bank_mask:0xf bound_ctrl:1
	v_mov_b32_dpp v118, v40 row_shl:1 row_mask:0xf bank_mask:0xf bound_ctrl:1
	v_mov_b32_dpp v53, v33 row_mirror row_mask:0xf bank_mask:0xf bound_ctrl:1
	v_mov_b32_dpp v119, v41 row_shl:1 row_mask:0xf bank_mask:0xf bound_ctrl:1
	v_pk_fma_f32 v[58:59], v[92:93], v[58:59], v[84:85]
	v_pk_fma_f32 v[52:53], v[208:209], v[52:53], v[118:119]
	v_pk_fma_f32 v[40:41], v[40:41], v[96:97], v[58:59]
	v_mov_b32_dpp v54, v44 row_shr:1 row_mask:0xf bank_mask:0xf bound_ctrl:1
	v_pk_fma_f32 v[40:41], v[88:89], v[52:53], v[40:41]
	v_mov_b32_dpp v55, v45 row_shr:1 row_mask:0xf bank_mask:0xf bound_ctrl:1
	v_mul_f32_e32 v51, 0xbfb8aa3b, v40
	v_mul_f32_e32 v53, 0xbfb8aa3b, v41
	v_exp_f32_e32 v52, v51
	v_exp_f32_e32 v53, v53
	v_pk_fma_f32 v[54:55], v[136:137], v[130:131], v[54:55]
	v_mov_b32_dpp v50, v36 row_mirror row_mask:0xf bank_mask:0xf bound_ctrl:1
	v_add_f32_e32 v52, 1.0, v52
	v_add_f32_e32 v53, 1.0, v53
	v_pk_fma_f32 v[54:55], v[72:73], v[54:55], v[64:65]
	v_mov_b32_dpp v62, v44 row_shl:1 row_mask:0xf bank_mask:0xf bound_ctrl:1
	v_mov_b32_dpp v51, v37 row_mirror row_mask:0xf bank_mask:0xf bound_ctrl:1
	v_mov_b32_dpp v63, v45 row_shl:1 row_mask:0xf bank_mask:0xf bound_ctrl:1
	v_rcp_f32_e32 v52, v52
	v_rcp_f32_e32 v53, v53
	v_pk_fma_f32 v[44:45], v[44:45], v[76:77], v[54:55]
	v_mov_b32_dpp v54, v42 row_shr:1 row_mask:0xf bank_mask:0xf bound_ctrl:1
	v_mov_b32_dpp v55, v43 row_shr:1 row_mask:0xf bank_mask:0xf bound_ctrl:1
	v_pk_fma_f32 v[50:51], v[208:209], v[50:51], v[62:63]
	v_pk_fma_f32 v[54:55], v[136:137], v[116:117], v[54:55]
	v_pk_fma_f32 v[44:45], v[68:69], v[50:51], v[44:45]
	v_mov_b32_dpp v50, v34 row_mirror row_mask:0xf bank_mask:0xf bound_ctrl:1
	v_mov_b32_dpp v62, v42 row_shl:1 row_mask:0xf bank_mask:0xf bound_ctrl:1
	v_mov_b32_dpp v51, v35 row_mirror row_mask:0xf bank_mask:0xf bound_ctrl:1
	v_mov_b32_dpp v63, v43 row_shl:1 row_mask:0xf bank_mask:0xf bound_ctrl:1
	v_pk_fma_f32 v[54:55], v[94:95], v[54:55], v[86:87]
	v_pk_fma_f32 v[50:51], v[208:209], v[50:51], v[62:63]
	v_pk_fma_f32 v[42:43], v[42:43], v[98:99], v[54:55]
	v_pk_mul_f32 v[40:41], v[40:41], v[52:53]
	v_pk_fma_f32 v[42:43], v[90:91], v[50:51], v[42:43]
	v_pk_mul_f32 v[40:41], v[44:45], v[40:41]
	v_mul_f32_e32 v45, 0xbfb8aa3b, v42
	v_mul_f32_e32 v51, 0xbfb8aa3b, v43
	v_exp_f32_e32 v50, v45
	v_exp_f32_e32 v51, v51
	v_mov_b32_dpp v52, v46 row_shr:1 row_mask:0xf bank_mask:0xf bound_ctrl:1
	v_mov_b32_dpp v53, v47 row_shr:1 row_mask:0xf bank_mask:0xf bound_ctrl:1
	v_add_f32_e32 v50, 1.0, v50
	v_add_f32_e32 v51, 1.0, v51
	v_rcp_f32_e32 v50, v50
	v_rcp_f32_e32 v51, v51
	v_pk_fma_f32 v[52:53], v[136:137], v[112:113], v[52:53]
	v_mov_b32_dpp v44, v38 row_mirror row_mask:0xf bank_mask:0xf bound_ctrl:1
	v_mov_b32_dpp v58, v46 row_shl:1 row_mask:0xf bank_mask:0xf bound_ctrl:1
	v_mov_b32_dpp v45, v39 row_mirror row_mask:0xf bank_mask:0xf bound_ctrl:1
	v_mov_b32_dpp v59, v47 row_shl:1 row_mask:0xf bank_mask:0xf bound_ctrl:1
	v_pk_fma_f32 v[52:53], v[74:75], v[52:53], v[66:67]
	v_pk_fma_f32 v[44:45], v[208:209], v[44:45], v[58:59]
	v_pk_fma_f32 v[46:47], v[46:47], v[78:79], v[52:53]
	v_pk_mul_f32 v[42:43], v[42:43], v[50:51]
	v_pk_fma_f32 v[44:45], v[70:71], v[44:45], v[46:47]
	v_cvt_pk_bf16_f32 v40, v40, v41
	v_pk_mul_f32 v[42:43], v[44:45], v[42:43]
	s_nop 0
	v_cvt_pk_bf16_f32 v41, v42, v43
	global_store_dwordx2 v[122:123], v[40:41], off offset:8 nt
	v_mov_b32_dpp v42, v32 row_shr:1 row_mask:0xf bank_mask:0xf bound_ctrl:1
	v_mov_b32_dpp v43, v33 row_shr:1 row_mask:0xf bank_mask:0xf bound_ctrl:1
	v_pk_fma_f32 v[42:43], v[136:137], v[60:61], v[42:43]
	v_mov_b32_dpp v44, v32 row_shl:1 row_mask:0xf bank_mask:0xf bound_ctrl:1
	v_mov_b32_dpp v45, v33 row_shl:1 row_mask:0xf bank_mask:0xf bound_ctrl:1
	v_pk_fma_f32 v[42:43], v[92:93], v[42:43], v[84:85]
	v_pk_fma_f32 v[44:45], v[208:209], v[108:109], v[44:45]
	v_pk_fma_f32 v[32:33], v[32:33], v[96:97], v[42:43]
	v_mov_b32_dpp v40, v36 row_shr:1 row_mask:0xf bank_mask:0xf bound_ctrl:1
	v_pk_fma_f32 v[32:33], v[88:89], v[44:45], v[32:33]
	v_mov_b32_dpp v42, v36 row_shl:1 row_mask:0xf bank_mask:0xf bound_ctrl:1
	v_mul_f32_e32 v41, 0xbfb8aa3b, v32
	v_mul_f32_e32 v45, 0xbfb8aa3b, v33
	v_exp_f32_e32 v44, v41
	v_exp_f32_e32 v45, v45
	v_mov_b32_dpp v41, v37 row_shr:1 row_mask:0xf bank_mask:0xf bound_ctrl:1
	v_pk_fma_f32 v[40:41], v[136:137], v[56:57], v[40:41]
	v_add_f32_e32 v44, 1.0, v44
	v_add_f32_e32 v45, 1.0, v45
	v_pk_fma_f32 v[40:41], v[72:73], v[40:41], v[64:65]
	v_mov_b32_dpp v43, v37 row_shl:1 row_mask:0xf bank_mask:0xf bound_ctrl:1
	v_rcp_f32_e32 v44, v44
	v_rcp_f32_e32 v45, v45
	v_pk_fma_f32 v[36:37], v[36:37], v[76:77], v[40:41]
	v_mov_b32_dpp v40, v34 row_shr:1 row_mask:0xf bank_mask:0xf bound_ctrl:1
	v_mov_b32_dpp v41, v35 row_shr:1 row_mask:0xf bank_mask:0xf bound_ctrl:1
	v_pk_fma_f32 v[42:43], v[208:209], v[104:105], v[42:43]
	v_pk_fma_f32 v[40:41], v[136:137], v[114:115], v[40:41]
	v_pk_fma_f32 v[36:37], v[68:69], v[42:43], v[36:37]
	v_mov_b32_dpp v42, v34 row_shl:1 row_mask:0xf bank_mask:0xf bound_ctrl:1
	v_mov_b32_dpp v43, v35 row_shl:1 row_mask:0xf bank_mask:0xf bound_ctrl:1
	v_pk_fma_f32 v[40:41], v[94:95], v[40:41], v[86:87]
	v_pk_fma_f32 v[42:43], v[208:209], v[110:111], v[42:43]
	v_pk_fma_f32 v[34:35], v[34:35], v[98:99], v[40:41]
	v_pk_mul_f32 v[32:33], v[32:33], v[44:45]
	v_pk_fma_f32 v[34:35], v[90:91], v[42:43], v[34:35]
	v_pk_mul_f32 v[32:33], v[36:37], v[32:33]
	v_mul_f32_e32 v37, 0xbfb8aa3b, v34
	v_mul_f32_e32 v43, 0xbfb8aa3b, v35
	v_exp_f32_e32 v42, v37
	v_exp_f32_e32 v43, v43
	v_mov_b32_dpp v36, v38 row_shr:1 row_mask:0xf bank_mask:0xf bound_ctrl:1
	v_mov_b32_dpp v37, v39 row_shr:1 row_mask:0xf bank_mask:0xf bound_ctrl:1
	v_add_f32_e32 v42, 1.0, v42
	v_add_f32_e32 v43, 1.0, v43
	v_rcp_f32_e32 v42, v42
	v_rcp_f32_e32 v43, v43
	v_pk_fma_f32 v[36:37], v[136:137], v[48:49], v[36:37]
	v_mov_b32_dpp v40, v38 row_shl:1 row_mask:0xf bank_mask:0xf bound_ctrl:1
	v_mov_b32_dpp v41, v39 row_shl:1 row_mask:0xf bank_mask:0xf bound_ctrl:1
	v_pk_fma_f32 v[36:37], v[74:75], v[36:37], v[66:67]
	v_pk_fma_f32 v[40:41], v[208:209], v[106:107], v[40:41]
	v_pk_fma_f32 v[36:37], v[38:39], v[78:79], v[36:37]
	v_pk_mul_f32 v[34:35], v[34:35], v[42:43]
	v_pk_fma_f32 v[36:37], v[70:71], v[40:41], v[36:37]
	v_cvt_pk_bf16_f32 v32, v32, v33
	v_pk_mul_f32 v[34:35], v[36:37], v[34:35]
	s_nop 0
	v_cvt_pk_bf16_f32 v33, v34, v35
	global_store_dwordx2 v[124:125], v[32:33], off offset:8 nt
	s_and_b64 vcc, exec, s[4:5]
	s_mov_b64 s[2:3], -1
	s_cbranch_vccnz .LBB0_752
	v_mov_b64_e32 v[32:33], v[80:81]
	v_mov_b64_e32 v[36:37], v[100:101]
	v_mov_b64_e32 v[34:35], v[82:83]
	v_mov_b64_e32 v[38:39], v[102:103]
	s_cbranch_execz .LBB0_753

.LBB0_756:
	v_mov_b32_dpp v46, v24 row_shr:1 row_mask:0xf bank_mask:0xf bound_ctrl:1
	v_mov_b32_dpp v47, v25 row_shr:1 row_mask:0xf bank_mask:0xf bound_ctrl:1
	s_waitcnt lgkmcnt(0)
	v_pk_fma_f32 v[36:37], v[136:137], v[36:37], v[46:47]
	v_mov_b32_dpp v42, v16 row_mirror row_mask:0xf bank_mask:0xf bound_ctrl:1
	v_mov_b32_dpp v50, v24 row_shl:1 row_mask:0xf bank_mask:0xf bound_ctrl:1
	v_mov_b32_dpp v43, v17 row_mirror row_mask:0xf bank_mask:0xf bound_ctrl:1
	v_mov_b32_dpp v51, v25 row_shl:1 row_mask:0xf bank_mask:0xf bound_ctrl:1
	v_pk_fma_f32 v[36:37], v[92:93], v[36:37], v[84:85]
	v_pk_fma_f32 v[46:47], v[208:209], v[42:43], v[50:51]
	v_pk_fma_f32 v[36:37], v[24:25], v[96:97], v[36:37]
	v_mov_b32_dpp v44, v28 row_shr:1 row_mask:0xf bank_mask:0xf bound_ctrl:1
	v_pk_fma_f32 v[36:37], v[88:89], v[46:47], v[36:37]
	v_mov_b32_dpp v45, v29 row_shr:1 row_mask:0xf bank_mask:0xf bound_ctrl:1
	v_mul_f32_e32 v41, 0xbfb8aa3b, v36
	v_mul_f32_e32 v47, 0xbfb8aa3b, v37
	v_exp_f32_e32 v46, v41
	v_exp_f32_e32 v47, v47
	v_pk_fma_f32 v[32:33], v[136:137], v[32:33], v[44:45]
	v_mov_b32_dpp v40, v20 row_mirror row_mask:0xf bank_mask:0xf bound_ctrl:1
	v_add_f32_e32 v46, 1.0, v46
	v_add_f32_e32 v47, 1.0, v47
	v_rcp_f32_e32 v46, v46
	v_rcp_f32_e32 v47, v47
	v_mov_b32_dpp v48, v28 row_shl:1 row_mask:0xf bank_mask:0xf bound_ctrl:1
	v_mov_b32_dpp v41, v21 row_mirror row_mask:0xf bank_mask:0xf bound_ctrl:1
	v_mov_b32_dpp v49, v29 row_shl:1 row_mask:0xf bank_mask:0xf bound_ctrl:1
	v_pk_fma_f32 v[32:33], v[72:73], v[32:33], v[64:65]
	v_pk_fma_f32 v[44:45], v[208:209], v[40:41], v[48:49]
	v_pk_fma_f32 v[32:33], v[28:29], v[76:77], v[32:33]
	v_mov_b32_dpp v48, v26 row_shr:1 row_mask:0xf bank_mask:0xf bound_ctrl:1
	v_mov_b32_dpp v49, v27 row_shr:1 row_mask:0xf bank_mask:0xf bound_ctrl:1
	v_pk_fma_f32 v[32:33], v[68:69], v[44:45], v[32:33]
	v_pk_mul_f32 v[36:37], v[36:37], v[46:47]
	v_pk_fma_f32 v[38:39], v[136:137], v[38:39], v[48:49]
	v_pk_mul_f32 v[44:45], v[32:33], v[36:37]
	v_mov_b32_dpp v36, v18 row_mirror row_mask:0xf bank_mask:0xf bound_ctrl:1
	v_mov_b32_dpp v52, v26 row_shl:1 row_mask:0xf bank_mask:0xf bound_ctrl:1
	v_mov_b32_dpp v37, v19 row_mirror row_mask:0xf bank_mask:0xf bound_ctrl:1
	v_mov_b32_dpp v53, v27 row_shl:1 row_mask:0xf bank_mask:0xf bound_ctrl:1
	v_pk_fma_f32 v[38:39], v[94:95], v[38:39], v[86:87]
	v_pk_fma_f32 v[48:49], v[208:209], v[36:37], v[52:53]
	v_pk_fma_f32 v[38:39], v[26:27], v[98:99], v[38:39]
	v_mov_b32_dpp v46, v30 row_shr:1 row_mask:0xf bank_mask:0xf bound_ctrl:1
	v_pk_fma_f32 v[38:39], v[90:91], v[48:49], v[38:39]
	v_mov_b32_dpp v47, v31 row_shr:1 row_mask:0xf bank_mask:0xf bound_ctrl:1
	v_mul_f32_e32 v33, 0xbfb8aa3b, v38
	v_mul_f32_e32 v49, 0xbfb8aa3b, v39
	v_exp_f32_e32 v48, v33
	v_exp_f32_e32 v49, v49
	v_pk_fma_f32 v[34:35], v[136:137], v[34:35], v[46:47]
	v_mov_b32_dpp v32, v22 row_mirror row_mask:0xf bank_mask:0xf bound_ctrl:1
	v_add_f32_e32 v48, 1.0, v48
	v_add_f32_e32 v49, 1.0, v49
	v_rcp_f32_e32 v48, v48
	v_rcp_f32_e32 v49, v49
	v_mov_b32_dpp v50, v30 row_shl:1 row_mask:0xf bank_mask:0xf bound_ctrl:1
	v_mov_b32_dpp v33, v23 row_mirror row_mask:0xf bank_mask:0xf bound_ctrl:1
	v_mov_b32_dpp v51, v31 row_shl:1 row_mask:0xf bank_mask:0xf bound_ctrl:1
	v_pk_fma_f32 v[34:35], v[74:75], v[34:35], v[66:67]
	v_pk_fma_f32 v[46:47], v[208:209], v[32:33], v[50:51]
	v_pk_fma_f32 v[34:35], v[30:31], v[78:79], v[34:35]
	v_pk_mul_f32 v[38:39], v[38:39], v[48:49]
	v_pk_fma_f32 v[34:35], v[70:71], v[46:47], v[34:35]
	s_nop 0
	v_pk_mul_f32 v[34:35], v[34:35], v[38:39]
	v_cvt_pk_bf16_f32 v38, v44, v45
	v_cvt_pk_bf16_f32 v39, v34, v35
	global_store_dwordx2 v[126:127], v[38:39], off offset:8 nt
	v_mov_b32_dpp v38, v24 row_mirror row_mask:0xf bank_mask:0xf bound_ctrl:1
	v_mov_b32_dpp v46, v16 row_shr:1 row_mask:0xf bank_mask:0xf bound_ctrl:1
	v_mov_b32_dpp v39, v25 row_mirror row_mask:0xf bank_mask:0xf bound_ctrl:1
	v_mov_b32_dpp v47, v17 row_shr:1 row_mask:0xf bank_mask:0xf bound_ctrl:1
	v_pk_fma_f32 v[38:39], v[136:137], v[38:39], v[46:47]
	v_mov_b32_dpp v34, v28 row_mirror row_mask:0xf bank_mask:0xf bound_ctrl:1
	v_mov_b32_dpp v28, v8 row_mirror row_mask:0xf bank_mask:0xf bound_ctrl:1
	v_mov_b32_dpp v50, v16 row_shl:1 row_mask:0xf bank_mask:0xf bound_ctrl:1
	v_mov_b32_dpp v35, v29 row_mirror row_mask:0xf bank_mask:0xf bound_ctrl:1
	v_mov_b32_dpp v29, v9 row_mirror row_mask:0xf bank_mask:0xf bound_ctrl:1
	v_mov_b32_dpp v51, v17 row_shl:1 row_mask:0xf bank_mask:0xf bound_ctrl:1
	v_pk_fma_f32 v[38:39], v[92:93], v[38:39], v[84:85]
	v_pk_fma_f32 v[46:47], v[208:209], v[28:29], v[50:51]
	v_pk_fma_f32 v[16:17], v[16:17], v[96:97], v[38:39]
	v_mov_b32_dpp v44, v20 row_shr:1 row_mask:0xf bank_mask:0xf bound_ctrl:1
	v_pk_fma_f32 v[16:17], v[88:89], v[46:47], v[16:17]
	v_mov_b32_dpp v45, v21 row_shr:1 row_mask:0xf bank_mask:0xf bound_ctrl:1
	v_mul_f32_e32 v25, 0xbfb8aa3b, v16
	v_mul_f32_e32 v39, 0xbfb8aa3b, v17
	v_exp_f32_e32 v38, v25
	v_exp_f32_e32 v39, v39
	v_pk_fma_f32 v[34:35], v[136:137], v[34:35], v[44:45]
	v_mov_b32_dpp v24, v12 row_mirror row_mask:0xf bank_mask:0xf bound_ctrl:1
	v_mov_b32_dpp v48, v20 row_shl:1 row_mask:0xf bank_mask:0xf bound_ctrl:1
	v_mov_b32_dpp v25, v13 row_mirror row_mask:0xf bank_mask:0xf bound_ctrl:1
	v_mov_b32_dpp v49, v21 row_shl:1 row_mask:0xf bank_mask:0xf bound_ctrl:1
	v_pk_fma_f32 v[34:35], v[72:73], v[34:35], v[64:65]
	v_add_f32_e32 v38, 1.0, v38
	v_pk_fma_f32 v[44:45], v[208:209], v[24:25], v[48:49]
	v_add_f32_e32 v39, 1.0, v39
	v_pk_fma_f32 v[20:21], v[20:21], v[76:77], v[34:35]
	v_rcp_f32_e32 v38, v38
	v_rcp_f32_e32 v39, v39
	v_pk_fma_f32 v[20:21], v[68:69], v[44:45], v[20:21]
	v_mov_b32_dpp v26, v26 row_mirror row_mask:0xf bank_mask:0xf bound_ctrl:1
	v_mov_b32_dpp v44, v18 row_shr:1 row_mask:0xf bank_mask:0xf bound_ctrl:1
	v_mov_b32_dpp v27, v27 row_mirror row_mask:0xf bank_mask:0xf bound_ctrl:1
	v_mov_b32_dpp v45, v19 row_shr:1 row_mask:0xf bank_mask:0xf bound_ctrl:1
	v_pk_fma_f32 v[26:27], v[136:137], v[26:27], v[44:45]
	v_mov_b32_dpp v34, v10 row_mirror row_mask:0xf bank_mask:0xf bound_ctrl:1
	v_mov_b32_dpp v48, v18 row_shl:1 row_mask:0xf bank_mask:0xf bound_ctrl:1
	v_mov_b32_dpp v35, v11 row_mirror row_mask:0xf bank_mask:0xf bound_ctrl:1
	v_mov_b32_dpp v49, v19 row_shl:1 row_mask:0xf bank_mask:0xf bound_ctrl:1
	v_pk_fma_f32 v[26:27], v[94:95], v[26:27], v[86:87]
	v_pk_fma_f32 v[44:45], v[208:209], v[34:35], v[48:49]
	v_pk_fma_f32 v[18:19], v[18:19], v[98:99], v[26:27]
	v_pk_mul_f32 v[16:17], v[16:17], v[38:39]
	v_pk_fma_f32 v[18:19], v[90:91], v[44:45], v[18:19]
	v_pk_mul_f32 v[20:21], v[20:21], v[16:17]
	v_mul_f32_e32 v17, 0xbfb8aa3b, v18
	v_mul_f32_e32 v27, 0xbfb8aa3b, v19
	v_exp_f32_e32 v26, v17
	v_exp_f32_e32 v27, v27
	v_mov_b32_dpp v30, v30 row_mirror row_mask:0xf bank_mask:0xf bound_ctrl:1
	v_mov_b32_dpp v38, v22 row_shr:1 row_mask:0xf bank_mask:0xf bound_ctrl:1
	v_add_f32_e32 v26, 1.0, v26
	v_add_f32_e32 v27, 1.0, v27
	v_mov_b32_dpp v31, v31 row_mirror row_mask:0xf bank_mask:0xf bound_ctrl:1
	v_mov_b32_dpp v39, v23 row_shr:1 row_mask:0xf bank_mask:0xf bound_ctrl:1
	v_rcp_f32_e32 v26, v26
	v_rcp_f32_e32 v27, v27
	v_pk_fma_f32 v[30:31], v[136:137], v[30:31], v[38:39]
	v_mov_b32_dpp v16, v14 row_mirror row_mask:0xf bank_mask:0xf bound_ctrl:1
	v_mov_b32_dpp v46, v22 row_shl:1 row_mask:0xf bank_mask:0xf bound_ctrl:1
	v_mov_b32_dpp v17, v15 row_mirror row_mask:0xf bank_mask:0xf bound_ctrl:1
	v_mov_b32_dpp v47, v23 row_shl:1 row_mask:0xf bank_mask:0xf bound_ctrl:1
	v_pk_fma_f32 v[30:31], v[74:75], v[30:31], v[66:67]
	v_pk_fma_f32 v[38:39], v[208:209], v[16:17], v[46:47]
	v_pk_fma_f32 v[22:23], v[22:23], v[78:79], v[30:31]
	v_pk_mul_f32 v[18:19], v[18:19], v[26:27]
	v_pk_fma_f32 v[22:23], v[70:71], v[38:39], v[22:23]
	v_cvt_pk_bf16_f32 v20, v20, v21
	v_pk_mul_f32 v[18:19], v[22:23], v[18:19]
	s_nop 0
	v_cvt_pk_bf16_f32 v21, v18, v19
	global_store_dwordx2 v[176:177], v[20:21], off offset:8 nt
	v_mov_b32_dpp v26, v8 row_shr:1 row_mask:0xf bank_mask:0xf bound_ctrl:1
	v_mov_b32_dpp v27, v9 row_shr:1 row_mask:0xf bank_mask:0xf bound_ctrl:1
	v_pk_fma_f32 v[26:27], v[136:137], v[42:43], v[26:27]
	v_mov_b32_dpp v20, v0 row_mirror row_mask:0xf bank_mask:0xf bound_ctrl:1
	v_mov_b32_dpp v38, v8 row_shl:1 row_mask:0xf bank_mask:0xf bound_ctrl:1
	v_mov_b32_dpp v21, v1 row_mirror row_mask:0xf bank_mask:0xf bound_ctrl:1
	v_mov_b32_dpp v39, v9 row_shl:1 row_mask:0xf bank_mask:0xf bound_ctrl:1
	v_pk_fma_f32 v[26:27], v[92:93], v[26:27], v[84:85]
	v_pk_fma_f32 v[20:21], v[208:209], v[20:21], v[38:39]
	v_pk_fma_f32 v[8:9], v[8:9], v[96:97], v[26:27]
	v_mov_b32_dpp v22, v12 row_shr:1 row_mask:0xf bank_mask:0xf bound_ctrl:1
	v_pk_fma_f32 v[8:9], v[88:89], v[20:21], v[8:9]
	v_mov_b32_dpp v23, v13 row_shr:1 row_mask:0xf bank_mask:0xf bound_ctrl:1
	v_mul_f32_e32 v19, 0xbfb8aa3b, v8
	v_mul_f32_e32 v21, 0xbfb8aa3b, v9
	v_exp_f32_e32 v20, v19
	v_exp_f32_e32 v21, v21
	v_pk_fma_f32 v[22:23], v[136:137], v[40:41], v[22:23]
	v_mov_b32_dpp v18, v4 row_mirror row_mask:0xf bank_mask:0xf bound_ctrl:1
	v_add_f32_e32 v20, 1.0, v20
	v_add_f32_e32 v21, 1.0, v21
	v_pk_fma_f32 v[22:23], v[72:73], v[22:23], v[64:65]
	v_mov_b32_dpp v30, v12 row_shl:1 row_mask:0xf bank_mask:0xf bound_ctrl:1
	v_mov_b32_dpp v19, v5 row_mirror row_mask:0xf bank_mask:0xf bound_ctrl:1
	v_mov_b32_dpp v31, v13 row_shl:1 row_mask:0xf bank_mask:0xf bound_ctrl:1
	v_rcp_f32_e32 v20, v20
	v_rcp_f32_e32 v21, v21
	v_pk_fma_f32 v[12:13], v[12:13], v[76:77], v[22:23]
	v_mov_b32_dpp v22, v10 row_shr:1 row_mask:0xf bank_mask:0xf bound_ctrl:1
	v_mov_b32_dpp v23, v11 row_shr:1 row_mask:0xf bank_mask:0xf bound_ctrl:1
	v_pk_fma_f32 v[18:19], v[208:209], v[18:19], v[30:31]
	v_pk_fma_f32 v[22:23], v[136:137], v[36:37], v[22:23]
	v_pk_fma_f32 v[12:13], v[68:69], v[18:19], v[12:13]
	v_mov_b32_dpp v18, v2 row_mirror row_mask:0xf bank_mask:0xf bound_ctrl:1
	v_mov_b32_dpp v30, v10 row_shl:1 row_mask:0xf bank_mask:0xf bound_ctrl:1
	v_mov_b32_dpp v19, v3 row_mirror row_mask:0xf bank_mask:0xf bound_ctrl:1
	v_mov_b32_dpp v31, v11 row_shl:1 row_mask:0xf bank_mask:0xf bound_ctrl:1
	v_pk_fma_f32 v[22:23], v[94:95], v[22:23], v[86:87]
	v_pk_fma_f32 v[18:19], v[208:209], v[18:19], v[30:31]
	v_pk_fma_f32 v[10:11], v[10:11], v[98:99], v[22:23]
	v_pk_mul_f32 v[8:9], v[8:9], v[20:21]
	v_pk_fma_f32 v[10:11], v[90:91], v[18:19], v[10:11]
	v_pk_mul_f32 v[8:9], v[12:13], v[8:9]
	v_mul_f32_e32 v13, 0xbfb8aa3b, v10
	v_mul_f32_e32 v19, 0xbfb8aa3b, v11
	v_exp_f32_e32 v18, v13
	v_exp_f32_e32 v19, v19
	v_mov_b32_dpp v20, v14 row_shr:1 row_mask:0xf bank_mask:0xf bound_ctrl:1
	v_mov_b32_dpp v21, v15 row_shr:1 row_mask:0xf bank_mask:0xf bound_ctrl:1
	v_add_f32_e32 v18, 1.0, v18
	v_add_f32_e32 v19, 1.0, v19
	v_rcp_f32_e32 v18, v18
	v_rcp_f32_e32 v19, v19
	v_pk_fma_f32 v[20:21], v[136:137], v[32:33], v[20:21]
	v_mov_b32_dpp v12, v6 row_mirror row_mask:0xf bank_mask:0xf bound_ctrl:1
	v_mov_b32_dpp v26, v14 row_shl:1 row_mask:0xf bank_mask:0xf bound_ctrl:1
	v_mov_b32_dpp v13, v7 row_mirror row_mask:0xf bank_mask:0xf bound_ctrl:1
	v_mov_b32_dpp v27, v15 row_shl:1 row_mask:0xf bank_mask:0xf bound_ctrl:1
	v_pk_fma_f32 v[20:21], v[74:75], v[20:21], v[66:67]
	v_pk_fma_f32 v[12:13], v[208:209], v[12:13], v[26:27]
	v_pk_fma_f32 v[14:15], v[14:15], v[78:79], v[20:21]
	v_pk_mul_f32 v[10:11], v[10:11], v[18:19]
	v_pk_fma_f32 v[12:13], v[70:71], v[12:13], v[14:15]
	v_cvt_pk_bf16_f32 v8, v8, v9
	v_pk_mul_f32 v[10:11], v[12:13], v[10:11]
	s_nop 0
	v_cvt_pk_bf16_f32 v9, v10, v11
	global_store_dwordx2 v[178:179], v[8:9], off offset:8 nt
	v_mov_b32_dpp v10, v0 row_shr:1 row_mask:0xf bank_mask:0xf bound_ctrl:1
	v_mov_b32_dpp v11, v1 row_shr:1 row_mask:0xf bank_mask:0xf bound_ctrl:1
	v_pk_fma_f32 v[10:11], v[136:137], v[28:29], v[10:11]
	v_mov_b32_dpp v14, v0 row_shl:1 row_mask:0xf bank_mask:0xf bound_ctrl:1
	v_mov_b32_dpp v15, v1 row_shl:1 row_mask:0xf bank_mask:0xf bound_ctrl:1
	v_pk_fma_f32 v[10:11], v[92:93], v[10:11], v[84:85]
	v_mov_b32_dpp v8, v4 row_shr:1 row_mask:0xf bank_mask:0xf bound_ctrl:1
	v_pk_fma_f32 v[0:1], v[0:1], v[96:97], v[10:11]
	v_pk_fma_f32 v[10:11], v[208:209], v[100:101], v[14:15]
	v_mov_b32_dpp v9, v5 row_shr:1 row_mask:0xf bank_mask:0xf bound_ctrl:1
	v_pk_fma_f32 v[0:1], v[88:89], v[10:11], v[0:1]
	v_pk_fma_f32 v[8:9], v[136:137], v[24:25], v[8:9]
	v_mul_f32_e32 v10, 0xbfb8aa3b, v0
	v_exp_f32_e32 v11, v10
	v_mul_f32_e32 v15, 0xbfb8aa3b, v1
	v_exp_f32_e32 v15, v15
	v_mov_b32_dpp v12, v4 row_shl:1 row_mask:0xf bank_mask:0xf bound_ctrl:1
	v_add_f32_e32 v11, 1.0, v11
	v_mov_b32_dpp v13, v5 row_shl:1 row_mask:0xf bank_mask:0xf bound_ctrl:1
	v_rcp_f32_e32 v22, v11
	v_pk_fma_f32 v[8:9], v[72:73], v[8:9], v[64:65]
	v_add_f32_e32 v11, 1.0, v15
	v_mov_b32_dpp v10, v2 row_shr:1 row_mask:0xf bank_mask:0xf bound_ctrl:1
	v_rcp_f32_e32 v23, v11
	v_pk_fma_f32 v[4:5], v[4:5], v[76:77], v[8:9]
	v_pk_fma_f32 v[8:9], v[208:209], v[80:81], v[12:13]
	v_mov_b32_dpp v11, v3 row_shr:1 row_mask:0xf bank_mask:0xf bound_ctrl:1
	v_pk_fma_f32 v[4:5], v[68:69], v[8:9], v[4:5]
	v_pk_fma_f32 v[8:9], v[136:137], v[34:35], v[10:11]
	v_mov_b32_dpp v20, v2 row_shl:1 row_mask:0xf bank_mask:0xf bound_ctrl:1
	v_mov_b32_dpp v21, v3 row_shl:1 row_mask:0xf bank_mask:0xf bound_ctrl:1
	v_pk_fma_f32 v[8:9], v[94:95], v[8:9], v[86:87]
	v_pk_fma_f32 v[10:11], v[208:209], v[102:103], v[20:21]
	v_pk_fma_f32 v[2:3], v[2:3], v[98:99], v[8:9]
	v_pk_mul_f32 v[0:1], v[0:1], v[22:23]
	v_pk_fma_f32 v[2:3], v[90:91], v[10:11], v[2:3]
	v_pk_mul_f32 v[0:1], v[4:5], v[0:1]
	v_mul_f32_e32 v8, 0xbfb8aa3b, v2
	v_mul_f32_e32 v5, 0xbfb8aa3b, v3
	v_exp_f32_e32 v8, v8
	v_exp_f32_e32 v5, v5
	v_mov_b32_dpp v18, v6 row_shr:1 row_mask:0xf bank_mask:0xf bound_ctrl:1
	v_mov_b32_dpp v19, v7 row_shr:1 row_mask:0xf bank_mask:0xf bound_ctrl:1
	v_add_f32_e32 v4, 1.0, v8
	v_add_f32_e32 v5, 1.0, v5
	v_rcp_f32_e32 v4, v4
	v_rcp_f32_e32 v5, v5
	v_pk_fma_f32 v[8:9], v[136:137], v[16:17], v[18:19]
	v_mov_b32_dpp v14, v6 row_shl:1 row_mask:0xf bank_mask:0xf bound_ctrl:1
	v_mov_b32_dpp v15, v7 row_shl:1 row_mask:0xf bank_mask:0xf bound_ctrl:1
	v_pk_fma_f32 v[8:9], v[74:75], v[8:9], v[66:67]
	v_pk_fma_f32 v[10:11], v[208:209], v[82:83], v[14:15]
	v_pk_fma_f32 v[6:7], v[6:7], v[78:79], v[8:9]
	v_pk_mul_f32 v[2:3], v[2:3], v[4:5]
	v_pk_fma_f32 v[6:7], v[70:71], v[10:11], v[6:7]
	v_cvt_pk_bf16_f32 v0, v0, v1
	v_pk_mul_f32 v[2:3], v[6:7], v[2:3]
	s_nop 0
	v_cvt_pk_bf16_f32 v1, v2, v3
	global_store_dwordx2 v[128:129], v[0:1], off offset:8 nt
	s_and_b64 vcc, exec, s[42:43]
	s_mov_b64 s[2:3], -1
	s_cbranch_vccnz .LBB0_673
	s_branch .LBB0_849

.LBB0_770:
	s_cmp_lg_u64 s[46:47], 0
	s_cselect_b64 s[94:95], -1, 0
	s_cmp_eq_u64 s[46:47], 0
	v_or_b32_e32 v188, s57, v192
	v_mov_b32_e32 v189, s35
	v_lshl_add_u64 v[156:157], v[152:153], 2, s[46:47]
	v_readlane_b32 s46, v254, 51
	v_lshl_add_u64 v[154:155], s[96:97], 0, v[188:189]
	v_or_b32_e32 v186, s57, v192
	v_readlane_b32 s47, v254, 52
	v_or_b32_e32 v184, 16, v186
	v_or_b32_e32 v182, 32, v186
	v_lshl_add_u64 v[172:173], v[152:153], 1, s[46:47]
	v_lshlrev_b64 v[152:153], 12, v[154:155]
	v_or_b32_e32 v180, 48, v186
	v_add_u32_e32 v178, 0x80, v186
	v_readlane_b32 s62, v255, 36
	v_readlane_b32 s60, v254, 53
	v_ashrrev_i32_e32 v187, 31, v186
	v_lshl_add_u64 v[190:191], v[156:157], 0, v[152:153]
	v_ashrrev_i32_e32 v185, 31, v184
	v_ashrrev_i32_e32 v183, 31, v182
	v_ashrrev_i32_e32 v181, 31, v180
	v_ashrrev_i32_e32 v179, 31, v178
	v_add_u32_e32 v176, 0x90, v186
	v_add_u32_e32 v174, 0xa0, v186
	v_readlane_b32 s63, v255, 37
	v_readlane_b32 s61, v254, 54
	s_cbranch_scc1 .LBB0_772
	global_load_dwordx4 v[214:217], v[190:191], off
	global_load_dwordx4 v[218:221], v[190:191], off offset:16
	v_add_co_u32_e32 v154, vcc, 0x10000, v190
	s_mov_b64 s[46:47], 0x10000
	s_nop 0
	v_addc_co_u32_e32 v155, vcc, 0, v191, vcc
	v_lshl_add_u64 v[152:153], v[190:191], 0, s[46:47]
	global_load_dwordx4 v[168:171], v[154:155], off
	global_load_dwordx4 v[232:235], v[152:153], off offset:16
	s_mov_b32 s7, 0x20000
	v_add_co_u32_e32 v154, vcc, s7, v190
	s_mov_b64 s[46:47], 0x20000
	s_nop 0
	v_addc_co_u32_e32 v155, vcc, 0, v191, vcc
	v_lshl_add_u64 v[152:153], v[190:191], 0, s[46:47]
	global_load_dwordx4 v[160:163], v[154:155], off
	global_load_dwordx4 v[164:167], v[152:153], off offset:16
	s_mov_b32 s7, 0x30000
	s_mov_b64 s[46:47], 0x30000
	v_add_co_u32_e32 v152, vcc, s7, v190
	v_lshl_add_u64 v[156:157], v[190:191], 0, s[46:47]
	s_nop 0
	v_addc_co_u32_e32 v153, vcc, 0, v191, vcc
	global_load_dwordx4 v[152:155], v[152:153], off
	s_nop 0
	global_load_dwordx4 v[156:159], v[156:157], off offset:16
	s_mov_b32 s96, 0x3fb504f3
	s_ashr_i32 s7, s6, 31
	s_mov_b64 s[46:47], 0x80000
	v_ashrrev_i32_e32 v177, 31, v176
	v_ashrrev_i32_e32 v175, 31, v174
	s_waitcnt vmcnt(0)
	v_pk_fma_f32 v[222:223], v[146:147], v[216:217], v[150:151]
	v_pk_fma_f32 v[250:251], v[144:145], v[214:215], v[148:149]
	v_pk_fma_f32 v[242:243], v[136:137], v[218:219], v[140:141]
	v_cndmask_b32_e64 v217, v223, v217, s[40:41]
	v_cndmask_b32_e64 v219, v243, v219, s[40:41]
	v_cndmask_b32_e64 v218, v242, v218, s[40:41]
	v_cndmask_b32_e64 v216, v222, v216, s[40:41]
	v_cndmask_b32_e64 v215, v251, v215, s[40:41]
	v_cndmask_b32_e64 v214, v250, v214, s[40:41]
	v_pk_fma_f32 v[236:237], v[138:139], v[220:221], v[142:143]
	v_pk_mul_f32 v[214:215], v[214:215], s[96:97] op_sel_hi:[1,0]
	v_pk_mul_f32 v[216:217], v[216:217], s[96:97] op_sel_hi:[1,0]
	v_pk_mul_f32 v[218:219], v[218:219], s[96:97] op_sel_hi:[1,0]
	v_cndmask_b32_e64 v221, v237, v221, s[40:41]
	v_cndmask_b32_e64 v220, v236, v220, s[40:41]
	v_pk_fma_f32 v[216:217], v[134:135], v[126:127], v[216:217]
	v_pk_fma_f32 v[214:215], v[132:133], v[124:125], v[214:215]
	v_pk_fma_f32 v[218:219], v[128:129], v[60:61], v[218:219]
	v_pk_mul_f32 v[220:221], v[220:221], s[96:97] op_sel_hi:[1,0]
	v_cvt_pk_bf16_f32 v214, v214, v215
	v_cvt_pk_bf16_f32 v215, v216, v217
	v_cvt_pk_bf16_f32 v216, v218, v219
	v_lshl_add_u64 v[218:219], v[186:187], 0, s[6:7]
	v_pk_fma_f32 v[220:221], v[130:131], v[62:63], v[220:221]
	v_lshlrev_b64 v[218:219], 11, v[218:219]
	v_cvt_pk_bf16_f32 v217, v220, v221
	v_lshl_add_u64 v[218:219], v[172:173], 0, v[218:219]
	global_store_dwordx4 v[218:219], v[214:217], off nt
	v_pk_fma_f32 v[220:221], v[136:137], v[232:233], v[140:141]
	v_pk_fma_f32 v[218:219], v[138:139], v[234:235], v[142:143]
	v_pk_fma_f32 v[214:215], v[146:147], v[170:171], v[150:151]
	v_pk_fma_f32 v[216:217], v[144:145], v[168:169], v[148:149]
	v_cndmask_b32_e64 v221, v221, v233, s[40:41]
	v_cndmask_b32_e64 v220, v220, v232, s[40:41]
	v_cndmask_b32_e64 v171, v215, v171, s[40:41]
	v_cndmask_b32_e64 v170, v214, v170, s[40:41]
	v_cndmask_b32_e64 v169, v217, v169, s[40:41]
	v_cndmask_b32_e64 v168, v216, v168, s[40:41]
	v_pk_mul_f32 v[168:169], v[168:169], s[96:97] op_sel_hi:[1,0]
	v_pk_mul_f32 v[170:171], v[170:171], s[96:97] op_sel_hi:[1,0]
	v_pk_mul_f32 v[214:215], v[220:221], s[96:97] op_sel_hi:[1,0]
	v_cndmask_b32_e64 v219, v219, v235, s[40:41]
	v_cndmask_b32_e64 v218, v218, v234, s[40:41]
	v_pk_fma_f32 v[170:171], v[134:135], v[118:119], v[170:171]
	v_pk_fma_f32 v[168:169], v[132:133], v[116:117], v[168:169]
	v_pk_fma_f32 v[214:215], v[128:129], v[52:53], v[214:215]
	v_pk_mul_f32 v[216:217], v[218:219], s[96:97] op_sel_hi:[1,0]
	v_cvt_pk_bf16_f32 v168, v168, v169
	v_cvt_pk_bf16_f32 v169, v170, v171
	v_cvt_pk_bf16_f32 v170, v214, v215
	v_lshl_add_u64 v[214:215], v[184:185], 0, s[6:7]
	v_pk_fma_f32 v[216:217], v[130:131], v[54:55], v[216:217]
	v_lshlrev_b64 v[214:215], 11, v[214:215]
	v_cvt_pk_bf16_f32 v171, v216, v217
	v_lshl_add_u64 v[214:215], v[172:173], 0, v[214:215]
	global_store_dwordx4 v[214:215], v[168:171], off nt
	v_pk_fma_f32 v[216:217], v[136:137], v[164:165], v[140:141]
	v_pk_fma_f32 v[214:215], v[138:139], v[166:167], v[142:143]
	v_pk_fma_f32 v[168:169], v[146:147], v[162:163], v[150:151]
	v_pk_fma_f32 v[170:171], v[144:145], v[160:161], v[148:149]
	v_cndmask_b32_e64 v165, v217, v165, s[40:41]
	v_cndmask_b32_e64 v164, v216, v164, s[40:41]
	v_cndmask_b32_e64 v163, v169, v163, s[40:41]
	v_cndmask_b32_e64 v162, v168, v162, s[40:41]
	v_cndmask_b32_e64 v161, v171, v161, s[40:41]
	v_cndmask_b32_e64 v160, v170, v160, s[40:41]
	v_pk_mul_f32 v[160:161], v[160:161], s[96:97] op_sel_hi:[1,0]
	v_pk_mul_f32 v[162:163], v[162:163], s[96:97] op_sel_hi:[1,0]
	v_pk_mul_f32 v[164:165], v[164:165], s[96:97] op_sel_hi:[1,0]
	v_cndmask_b32_e64 v167, v215, v167, s[40:41]
	v_cndmask_b32_e64 v166, v214, v166, s[40:41]
	v_pk_fma_f32 v[162:163], v[134:135], v[110:111], v[162:163]
	v_pk_fma_f32 v[160:161], v[132:133], v[108:109], v[160:161]
	v_pk_fma_f32 v[164:165], v[128:129], v[44:45], v[164:165]
	v_pk_mul_f32 v[166:167], v[166:167], s[96:97] op_sel_hi:[1,0]
	v_cvt_pk_bf16_f32 v160, v160, v161
	v_cvt_pk_bf16_f32 v161, v162, v163
	v_cvt_pk_bf16_f32 v162, v164, v165
	v_lshl_add_u64 v[164:165], v[182:183], 0, s[6:7]
	v_pk_fma_f32 v[166:167], v[130:131], v[46:47], v[166:167]
	v_lshlrev_b64 v[164:165], 11, v[164:165]
	v_cvt_pk_bf16_f32 v163, v166, v167
	v_lshl_add_u64 v[164:165], v[172:173], 0, v[164:165]
	global_store_dwordx4 v[164:165], v[160:163], off nt
	v_pk_fma_f32 v[166:167], v[136:137], v[156:157], v[140:141]
	v_pk_fma_f32 v[164:165], v[138:139], v[158:159], v[142:143]
	v_pk_fma_f32 v[160:161], v[146:147], v[154:155], v[150:151]
	v_pk_fma_f32 v[162:163], v[144:145], v[152:153], v[148:149]
	v_cndmask_b32_e64 v157, v167, v157, s[40:41]
	v_cndmask_b32_e64 v156, v166, v156, s[40:41]
	v_cndmask_b32_e64 v155, v161, v155, s[40:41]
	v_cndmask_b32_e64 v154, v160, v154, s[40:41]
	v_cndmask_b32_e64 v153, v163, v153, s[40:41]
	v_cndmask_b32_e64 v152, v162, v152, s[40:41]
	v_pk_mul_f32 v[152:153], v[152:153], s[96:97] op_sel_hi:[1,0]
	v_pk_mul_f32 v[154:155], v[154:155], s[96:97] op_sel_hi:[1,0]
	v_pk_mul_f32 v[156:157], v[156:157], s[96:97] op_sel_hi:[1,0]
	v_cndmask_b32_e64 v159, v165, v159, s[40:41]
	v_cndmask_b32_e64 v158, v164, v158, s[40:41]
	v_pk_fma_f32 v[154:155], v[134:135], v[102:103], v[154:155]
	v_pk_fma_f32 v[152:153], v[132:133], v[100:101], v[152:153]
	v_pk_fma_f32 v[156:157], v[128:129], v[36:37], v[156:157]
	v_pk_mul_f32 v[158:159], v[158:159], s[96:97] op_sel_hi:[1,0]
	v_cvt_pk_bf16_f32 v152, v152, v153
	v_cvt_pk_bf16_f32 v153, v154, v155
	v_cvt_pk_bf16_f32 v154, v156, v157
	v_lshl_add_u64 v[156:157], v[180:181], 0, s[6:7]
	v_pk_fma_f32 v[158:159], v[130:131], v[38:39], v[158:159]
	v_lshlrev_b64 v[156:157], 11, v[156:157]
	v_cvt_pk_bf16_f32 v155, v158, v159
	v_lshl_add_u64 v[156:157], v[172:173], 0, v[156:157]
	global_store_dwordx4 v[156:157], v[152:155], off nt
	v_lshl_add_u64 v[156:157], v[190:191], 0, s[46:47]
	s_mov_b32 s46, 0x80000
	v_add_co_u32_e32 v152, vcc, s46, v190
	s_mov_b64 s[46:47], 0x90000
	s_nop 0
	v_addc_co_u32_e32 v153, vcc, 0, v191, vcc
	global_load_dwordx4 v[152:155], v[152:153], off
	s_nop 0
	global_load_dwordx4 v[156:159], v[156:157], off offset:16
	v_lshl_add_u64 v[164:165], v[190:191], 0, s[46:47]
	s_mov_b32 s46, 0x90000
	v_add_co_u32_e32 v160, vcc, s46, v190
	s_mov_b64 s[46:47], 0xa0000
	s_nop 0
	v_addc_co_u32_e32 v161, vcc, 0, v191, vcc
	global_load_dwordx4 v[160:163], v[160:161], off
	s_nop 0
	global_load_dwordx4 v[164:167], v[164:165], off offset:16
	v_lshl_add_u64 v[214:215], v[190:191], 0, s[46:47]
	s_mov_b32 s46, 0xa0000
	v_add_co_u32_e32 v168, vcc, s46, v190
	s_mov_b64 s[46:47], 0xb0000
	s_nop 0
	v_addc_co_u32_e32 v169, vcc, 0, v191, vcc
	global_load_dwordx4 v[168:171], v[168:169], off
	s_nop 0
	global_load_dwordx4 v[214:217], v[214:215], off offset:16
	v_lshl_add_u64 v[222:223], v[190:191], 0, s[46:47]
	s_mov_b32 s46, 0xb0000
	v_add_co_u32_e32 v218, vcc, s46, v190
	s_mov_b64 s[46:47], 0
	s_nop 0
	v_addc_co_u32_e32 v219, vcc, 0, v191, vcc
	global_load_dwordx4 v[218:221], v[218:219], off
	s_nop 0
	global_load_dwordx4 v[232:235], v[222:223], off offset:16
	s_waitcnt vmcnt(7)
	v_pk_fma_f32 v[222:223], v[146:147], v[154:155], v[150:151]
	v_pk_fma_f32 v[236:237], v[144:145], v[152:153], v[148:149]
	s_waitcnt vmcnt(6)
	v_pk_fma_f32 v[250:251], v[136:137], v[156:157], v[140:141]
	v_cndmask_b32_e64 v155, v223, v155, s[40:41]
	v_cndmask_b32_e64 v157, v251, v157, s[40:41]
	v_cndmask_b32_e64 v156, v250, v156, s[40:41]
	v_cndmask_b32_e64 v154, v222, v154, s[40:41]
	v_cndmask_b32_e64 v153, v237, v153, s[40:41]
	v_cndmask_b32_e64 v152, v236, v152, s[40:41]
	v_pk_fma_f32 v[242:243], v[138:139], v[158:159], v[142:143]
	v_pk_mul_f32 v[152:153], v[152:153], s[96:97] op_sel_hi:[1,0]
	v_pk_mul_f32 v[154:155], v[154:155], s[96:97] op_sel_hi:[1,0]
	v_pk_mul_f32 v[156:157], v[156:157], s[96:97] op_sel_hi:[1,0]
	v_cndmask_b32_e64 v159, v243, v159, s[40:41]
	v_cndmask_b32_e64 v158, v242, v158, s[40:41]
	v_pk_fma_f32 v[154:155], v[134:135], v[94:95], v[154:155]
	v_pk_fma_f32 v[152:153], v[132:133], v[92:93], v[152:153]
	v_pk_fma_f32 v[156:157], v[128:129], v[28:29], v[156:157]
	v_pk_mul_f32 v[158:159], v[158:159], s[96:97] op_sel_hi:[1,0]
	v_cvt_pk_bf16_f32 v152, v152, v153
	v_cvt_pk_bf16_f32 v153, v154, v155
	v_cvt_pk_bf16_f32 v154, v156, v157
	v_lshl_add_u64 v[156:157], v[178:179], 0, s[6:7]
	v_pk_fma_f32 v[158:159], v[130:131], v[30:31], v[158:159]
	v_lshlrev_b64 v[156:157], 11, v[156:157]
	v_cvt_pk_bf16_f32 v155, v158, v159
	v_lshl_add_u64 v[156:157], v[172:173], 0, v[156:157]
	global_store_dwordx4 v[156:157], v[152:155], off nt
	s_waitcnt vmcnt(5)
	v_pk_fma_f32 v[156:157], v[138:139], v[166:167], v[142:143]
	v_pk_fma_f32 v[158:159], v[136:137], v[164:165], v[140:141]
	v_pk_fma_f32 v[152:153], v[146:147], v[162:163], v[150:151]
	v_pk_fma_f32 v[154:155], v[144:145], v[160:161], v[148:149]
	v_cndmask_b32_e64 v153, v153, v163, s[40:41]
	v_cndmask_b32_e64 v152, v152, v162, s[40:41]
	v_cndmask_b32_e64 v155, v155, v161, s[40:41]
	v_cndmask_b32_e64 v154, v154, v160, s[40:41]
	v_cndmask_b32_e64 v157, v157, v167, s[40:41]
	v_cndmask_b32_e64 v156, v156, v166, s[40:41]
	v_cndmask_b32_e64 v159, v159, v165, s[40:41]
	v_cndmask_b32_e64 v158, v158, v164, s[40:41]
	v_pk_mul_f32 v[154:155], v[154:155], s[96:97] op_sel_hi:[1,0]
	v_pk_mul_f32 v[152:153], v[152:153], s[96:97] op_sel_hi:[1,0]
	v_pk_mul_f32 v[156:157], v[156:157], s[96:97] op_sel_hi:[1,0]
	v_pk_fma_f32 v[160:161], v[134:135], v[86:87], v[152:153]
	v_pk_fma_f32 v[152:153], v[132:133], v[84:85], v[154:155]
	v_pk_mul_f32 v[154:155], v[158:159], s[96:97] op_sel_hi:[1,0]
	v_pk_fma_f32 v[156:157], v[130:131], v[22:23], v[156:157]
	v_pk_fma_f32 v[154:155], v[128:129], v[20:21], v[154:155]
	v_cvt_pk_bf16_f32 v152, v152, v153
	v_cvt_pk_bf16_f32 v154, v154, v155
	v_cvt_pk_bf16_f32 v155, v156, v157
	v_lshl_add_u64 v[156:157], v[176:177], 0, s[6:7]
	v_lshlrev_b64 v[156:157], 11, v[156:157]
	v_cvt_pk_bf16_f32 v153, v160, v161
	v_lshl_add_u64 v[156:157], v[172:173], 0, v[156:157]
	global_store_dwordx4 v[156:157], v[152:155], off nt
	s_waitcnt vmcnt(4)
	v_pk_fma_f32 v[156:157], v[138:139], v[216:217], v[142:143]
	v_pk_fma_f32 v[158:159], v[136:137], v[214:215], v[140:141]
	v_pk_fma_f32 v[152:153], v[146:147], v[170:171], v[150:151]
	v_pk_fma_f32 v[154:155], v[144:145], v[168:169], v[148:149]
	v_cndmask_b32_e64 v153, v153, v171, s[40:41]
	v_cndmask_b32_e64 v152, v152, v170, s[40:41]
	v_cndmask_b32_e64 v155, v155, v169, s[40:41]
	v_cndmask_b32_e64 v154, v154, v168, s[40:41]
	v_cndmask_b32_e64 v157, v157, v217, s[40:41]
	v_cndmask_b32_e64 v156, v156, v216, s[40:41]
	v_cndmask_b32_e64 v159, v159, v215, s[40:41]
	v_cndmask_b32_e64 v158, v158, v214, s[40:41]
	v_pk_mul_f32 v[154:155], v[154:155], s[96:97] op_sel_hi:[1,0]
	v_pk_mul_f32 v[152:153], v[152:153], s[96:97] op_sel_hi:[1,0]
	v_pk_mul_f32 v[156:157], v[156:157], s[96:97] op_sel_hi:[1,0]
	v_pk_fma_f32 v[160:161], v[134:135], v[78:79], v[152:153]
	v_pk_fma_f32 v[152:153], v[132:133], v[76:77], v[154:155]
	v_pk_mul_f32 v[154:155], v[158:159], s[96:97] op_sel_hi:[1,0]
	v_pk_fma_f32 v[156:157], v[130:131], v[14:15], v[156:157]
	v_pk_fma_f32 v[154:155], v[128:129], v[12:13], v[154:155]
	v_cvt_pk_bf16_f32 v152, v152, v153
	v_cvt_pk_bf16_f32 v154, v154, v155
	v_cvt_pk_bf16_f32 v155, v156, v157
	v_lshl_add_u64 v[156:157], v[174:175], 0, s[6:7]
	v_lshlrev_b64 v[156:157], 11, v[156:157]
	v_cvt_pk_bf16_f32 v153, v160, v161
	v_lshl_add_u64 v[156:157], v[172:173], 0, v[156:157]
	global_store_dwordx4 v[156:157], v[152:155], off nt
	s_waitcnt vmcnt(4)
	v_pk_fma_f32 v[158:159], v[146:147], v[220:221], v[150:151]
	v_pk_fma_f32 v[156:157], v[144:145], v[218:219], v[148:149]
	s_waitcnt vmcnt(3)
	v_pk_fma_f32 v[154:155], v[138:139], v[234:235], v[142:143]
	v_pk_fma_f32 v[152:153], v[136:137], v[232:233], v[140:141]
	v_cndmask_b32_e64 v155, v155, v235, s[40:41]
	v_cndmask_b32_e64 v153, v153, v233, s[40:41]
	v_cndmask_b32_e64 v152, v152, v232, s[40:41]
	v_cndmask_b32_e64 v154, v154, v234, s[40:41]
	v_cndmask_b32_e64 v157, v157, v219, s[40:41]
	v_cndmask_b32_e64 v156, v156, v218, s[40:41]
	v_cndmask_b32_e64 v159, v159, v221, s[40:41]
	v_cndmask_b32_e64 v158, v158, v220, s[40:41]
	s_branch .LBB0_773

.LBB0_773:
	v_readlane_b32 s96, v254, 36
	v_readlane_b32 s97, v254, 37
	s_andn2_b64 vcc, exec, s[46:47]
	s_cbranch_vccnz .LBB0_806
	s_and_b64 vcc, exec, s[4:5]
	s_cbranch_vccnz .Lres_old_774
	s_ashr_i32 s7, s6, 31
	s_mov_b64 s[98:99], 0x8000
	s_mov_b64 s[100:101], 0x28000
	v_readlane_b32 s46, v254, 47
	v_readlane_b32 s47, v254, 48
	v_lshl_add_u64 v[184:185], v[188:189], 0, s[6:7]
	v_lshlrev_b64 v[248:249], 11, v[184:185]
	v_lshl_add_u64 v[248:249], v[172:173], 0, v[248:249]
	v_lshl_add_u64 v[186:187], v[184:185], 3, s[46:47]
	v_mov_b32_e32 v242, v248
	v_mov_b32_e32 v243, v249
	global_load_dwordx4 v[152:155], v[248:249], off
	global_load_dwordx2 v[214:215], v[186:187], off
	v_lshl_add_u64 v[248:249], v[248:249], 0, s[98:99]
	global_load_dwordx4 v[156:159], v[248:249], off
	global_load_dwordx2 v[216:217], v[186:187], off offset:128
	v_lshl_add_u64 v[248:249], v[248:249], 0, s[98:99]
	global_load_dwordx4 v[160:163], v[248:249], off
	global_load_dwordx2 v[218:219], v[186:187], off offset:256
	v_lshl_add_u64 v[248:249], v[248:249], 0, s[98:99]
	global_load_dwordx4 v[164:167], v[248:249], off
	global_load_dwordx2 v[220:221], v[186:187], off offset:384
	v_lshl_add_u64 v[248:249], v[248:249], 0, s[100:101]
	global_load_dwordx4 v[168:171], v[248:249], off
	global_load_dwordx2 v[222:223], v[186:187], off offset:1024
	v_lshl_add_u64 v[248:249], v[248:249], 0, s[98:99]
	global_load_dwordx4 v[172:175], v[248:249], off
	global_load_dwordx2 v[232:233], v[186:187], off offset:1152
	v_lshl_add_u64 v[248:249], v[248:249], 0, s[98:99]
	global_load_dwordx4 v[176:179], v[248:249], off
	global_load_dwordx2 v[234:235], v[186:187], off offset:1280
	v_lshl_add_u64 v[248:249], v[248:249], 0, s[98:99]
	global_load_dwordx4 v[180:183], v[248:249], off
	global_load_dwordx2 v[250:251], v[186:187], off offset:1408
	v_mov_b32_e32 v248, v242
	v_mov_b32_e32 v249, v243
	s_waitcnt vmcnt(0)
	v_lshlrev_b32_e32 v184, 16, v152
	v_and_b32_e32 v185, 0xffff0000, v152
	v_lshlrev_b32_e32 v186, 16, v153
	v_and_b32_e32 v187, 0xffff0000, v153
	v_lshlrev_b32_e32 v188, 16, v154
	v_and_b32_e32 v189, 0xffff0000, v154
	v_lshlrev_b32_e32 v190, 16, v155
	v_and_b32_e32 v191, 0xffff0000, v155
	v_sub_f32_e32 v184, v184, v214
	v_sub_f32_e32 v185, v185, v214
	v_sub_f32_e32 v186, v186, v214
	v_sub_f32_e32 v187, v187, v214
	v_sub_f32_e32 v188, v188, v214
	v_sub_f32_e32 v189, v189, v214
	v_sub_f32_e32 v190, v190, v214
	v_sub_f32_e32 v191, v191, v214
	v_mul_f32_e32 v184, v215, v184
	v_mul_f32_e32 v185, v215, v185
	v_mul_f32_e32 v186, v215, v186
	v_mul_f32_e32 v187, v215, v187
	v_mul_f32_e32 v188, v215, v188
	v_mul_f32_e32 v189, v215, v189
	v_mul_f32_e32 v190, v215, v190
	v_mul_f32_e32 v191, v215, v191
	v_pk_fma_f32 v[184:185], v[144:145], v[184:185], v[148:149]
	v_pk_fma_f32 v[186:187], v[146:147], v[186:187], v[150:151]
	v_pk_fma_f32 v[188:189], v[136:137], v[188:189], v[140:141]
	v_pk_fma_f32 v[190:191], v[138:139], v[190:191], v[142:143]
	v_mul_f32_e32 v184, 0x3fb504f3, v184
	v_mul_f32_e32 v185, 0x3fb504f3, v185
	v_mul_f32_e32 v186, 0x3fb504f3, v186
	v_mul_f32_e32 v187, 0x3fb504f3, v187
	v_mul_f32_e32 v188, 0x3fb504f3, v188
	v_mul_f32_e32 v189, 0x3fb504f3, v189
	v_mul_f32_e32 v190, 0x3fb504f3, v190
	v_mul_f32_e32 v191, 0x3fb504f3, v191
	v_pk_fma_f32 v[184:185], v[132:133], v[124:125], v[184:185]
	v_pk_fma_f32 v[186:187], v[134:135], v[126:127], v[186:187]
	v_pk_fma_f32 v[188:189], v[128:129], v[60:61], v[188:189]
	v_pk_fma_f32 v[190:191], v[130:131], v[62:63], v[190:191]
	v_cvt_pk_bf16_f32 v152, v184, v185
	v_cvt_pk_bf16_f32 v153, v186, v187
	v_cvt_pk_bf16_f32 v154, v188, v189
	v_cvt_pk_bf16_f32 v155, v190, v191
	global_load_dwordx4 v[124:127], v[248:249], off offset:256
	v_lshl_add_u64 v[248:249], v[248:249], 0, s[98:99]
	v_lshlrev_b32_e32 v184, 16, v156
	v_and_b32_e32 v185, 0xffff0000, v156
	v_lshlrev_b32_e32 v186, 16, v157
	v_and_b32_e32 v187, 0xffff0000, v157
	v_lshlrev_b32_e32 v188, 16, v158
	v_and_b32_e32 v189, 0xffff0000, v158
	v_lshlrev_b32_e32 v190, 16, v159
	v_and_b32_e32 v191, 0xffff0000, v159
	v_sub_f32_e32 v184, v184, v216
	v_sub_f32_e32 v185, v185, v216
	v_sub_f32_e32 v186, v186, v216
	v_sub_f32_e32 v187, v187, v216
	v_sub_f32_e32 v188, v188, v216
	v_sub_f32_e32 v189, v189, v216
	v_sub_f32_e32 v190, v190, v216
	v_sub_f32_e32 v191, v191, v216
	v_mul_f32_e32 v184, v217, v184
	v_mul_f32_e32 v185, v217, v185
	v_mul_f32_e32 v186, v217, v186
	v_mul_f32_e32 v187, v217, v187
	v_mul_f32_e32 v188, v217, v188
	v_mul_f32_e32 v189, v217, v189
	v_mul_f32_e32 v190, v217, v190
	v_mul_f32_e32 v191, v217, v191
	v_pk_fma_f32 v[184:185], v[144:145], v[184:185], v[148:149]
	v_pk_fma_f32 v[186:187], v[146:147], v[186:187], v[150:151]
	v_pk_fma_f32 v[188:189], v[136:137], v[188:189], v[140:141]
	v_pk_fma_f32 v[190:191], v[138:139], v[190:191], v[142:143]
	v_mul_f32_e32 v184, 0x3fb504f3, v184
	v_mul_f32_e32 v185, 0x3fb504f3, v185
	v_mul_f32_e32 v186, 0x3fb504f3, v186
	v_mul_f32_e32 v187, 0x3fb504f3, v187
	v_mul_f32_e32 v188, 0x3fb504f3, v188
	v_mul_f32_e32 v189, 0x3fb504f3, v189
	v_mul_f32_e32 v190, 0x3fb504f3, v190
	v_mul_f32_e32 v191, 0x3fb504f3, v191
	v_pk_fma_f32 v[184:185], v[132:133], v[116:117], v[184:185]
	v_pk_fma_f32 v[186:187], v[134:135], v[118:119], v[186:187]
	v_pk_fma_f32 v[188:189], v[128:129], v[52:53], v[188:189]
	v_pk_fma_f32 v[190:191], v[130:131], v[54:55], v[190:191]
	v_cvt_pk_bf16_f32 v156, v184, v185
	v_cvt_pk_bf16_f32 v157, v186, v187
	v_cvt_pk_bf16_f32 v158, v188, v189
	v_cvt_pk_bf16_f32 v159, v190, v191
	global_load_dwordx4 v[116:119], v[248:249], off offset:256
	v_lshl_add_u64 v[248:249], v[248:249], 0, s[98:99]
	v_lshlrev_b32_e32 v184, 16, v160
	v_and_b32_e32 v185, 0xffff0000, v160
	v_lshlrev_b32_e32 v186, 16, v161
	v_and_b32_e32 v187, 0xffff0000, v161
	v_lshlrev_b32_e32 v188, 16, v162
	v_and_b32_e32 v189, 0xffff0000, v162
	v_lshlrev_b32_e32 v190, 16, v163
	v_and_b32_e32 v191, 0xffff0000, v163
	v_sub_f32_e32 v184, v184, v218
	v_sub_f32_e32 v185, v185, v218
	v_sub_f32_e32 v186, v186, v218
	v_sub_f32_e32 v187, v187, v218
	v_sub_f32_e32 v188, v188, v218
	v_sub_f32_e32 v189, v189, v218
	v_sub_f32_e32 v190, v190, v218
	v_sub_f32_e32 v191, v191, v218
	v_mul_f32_e32 v184, v219, v184
	v_mul_f32_e32 v185, v219, v185
	v_mul_f32_e32 v186, v219, v186
	v_mul_f32_e32 v187, v219, v187
	v_mul_f32_e32 v188, v219, v188
	v_mul_f32_e32 v189, v219, v189
	v_mul_f32_e32 v190, v219, v190
	v_mul_f32_e32 v191, v219, v191
	v_pk_fma_f32 v[184:185], v[144:145], v[184:185], v[148:149]
	v_pk_fma_f32 v[186:187], v[146:147], v[186:187], v[150:151]
	v_pk_fma_f32 v[188:189], v[136:137], v[188:189], v[140:141]
	v_pk_fma_f32 v[190:191], v[138:139], v[190:191], v[142:143]
	v_mul_f32_e32 v184, 0x3fb504f3, v184
	v_mul_f32_e32 v185, 0x3fb504f3, v185
	v_mul_f32_e32 v186, 0x3fb504f3, v186
	v_mul_f32_e32 v187, 0x3fb504f3, v187
	v_mul_f32_e32 v188, 0x3fb504f3, v188
	v_mul_f32_e32 v189, 0x3fb504f3, v189
	v_mul_f32_e32 v190, 0x3fb504f3, v190
	v_mul_f32_e32 v191, 0x3fb504f3, v191
	v_pk_fma_f32 v[184:185], v[132:133], v[108:109], v[184:185]
	v_pk_fma_f32 v[186:187], v[134:135], v[110:111], v[186:187]
	v_pk_fma_f32 v[188:189], v[128:129], v[44:45], v[188:189]
	v_pk_fma_f32 v[190:191], v[130:131], v[46:47], v[190:191]
	v_cvt_pk_bf16_f32 v160, v184, v185
	v_cvt_pk_bf16_f32 v161, v186, v187
	v_cvt_pk_bf16_f32 v162, v188, v189
	v_cvt_pk_bf16_f32 v163, v190, v191
	global_load_dwordx4 v[108:111], v[248:249], off offset:256
	v_lshl_add_u64 v[248:249], v[248:249], 0, s[98:99]
	v_lshlrev_b32_e32 v184, 16, v164
	v_and_b32_e32 v185, 0xffff0000, v164
	v_lshlrev_b32_e32 v186, 16, v165
	v_and_b32_e32 v187, 0xffff0000, v165
	v_lshlrev_b32_e32 v188, 16, v166
	v_and_b32_e32 v189, 0xffff0000, v166
	v_lshlrev_b32_e32 v190, 16, v167
	v_and_b32_e32 v191, 0xffff0000, v167
	v_sub_f32_e32 v184, v184, v220
	v_sub_f32_e32 v185, v185, v220
	v_sub_f32_e32 v186, v186, v220
	v_sub_f32_e32 v187, v187, v220
	v_sub_f32_e32 v188, v188, v220
	v_sub_f32_e32 v189, v189, v220
	v_sub_f32_e32 v190, v190, v220
	v_sub_f32_e32 v191, v191, v220
	v_mul_f32_e32 v184, v221, v184
	v_mul_f32_e32 v185, v221, v185
	v_mul_f32_e32 v186, v221, v186
	v_mul_f32_e32 v187, v221, v187
	v_mul_f32_e32 v188, v221, v188
	v_mul_f32_e32 v189, v221, v189
	v_mul_f32_e32 v190, v221, v190
	v_mul_f32_e32 v191, v221, v191
	v_pk_fma_f32 v[184:185], v[144:145], v[184:185], v[148:149]
	v_pk_fma_f32 v[186:187], v[146:147], v[186:187], v[150:151]
	v_pk_fma_f32 v[188:189], v[136:137], v[188:189], v[140:141]
	v_pk_fma_f32 v[190:191], v[138:139], v[190:191], v[142:143]
	v_mul_f32_e32 v184, 0x3fb504f3, v184
	v_mul_f32_e32 v185, 0x3fb504f3, v185
	v_mul_f32_e32 v186, 0x3fb504f3, v186
	v_mul_f32_e32 v187, 0x3fb504f3, v187
	v_mul_f32_e32 v188, 0x3fb504f3, v188
	v_mul_f32_e32 v189, 0x3fb504f3, v189
	v_mul_f32_e32 v190, 0x3fb504f3, v190
	v_mul_f32_e32 v191, 0x3fb504f3, v191
	v_pk_fma_f32 v[184:185], v[132:133], v[100:101], v[184:185]
	v_pk_fma_f32 v[186:187], v[134:135], v[102:103], v[186:187]
	v_pk_fma_f32 v[188:189], v[128:129], v[36:37], v[188:189]
	v_pk_fma_f32 v[190:191], v[130:131], v[38:39], v[190:191]
	v_cvt_pk_bf16_f32 v164, v184, v185
	v_cvt_pk_bf16_f32 v165, v186, v187
	v_cvt_pk_bf16_f32 v166, v188, v189
	v_cvt_pk_bf16_f32 v167, v190, v191
	global_load_dwordx4 v[100:103], v[248:249], off offset:256
	v_lshl_add_u64 v[248:249], v[248:249], 0, s[100:101]
	v_lshlrev_b32_e32 v184, 16, v168
	v_and_b32_e32 v185, 0xffff0000, v168
	v_lshlrev_b32_e32 v186, 16, v169
	v_and_b32_e32 v187, 0xffff0000, v169
	v_lshlrev_b32_e32 v188, 16, v170
	v_and_b32_e32 v189, 0xffff0000, v170
	v_lshlrev_b32_e32 v190, 16, v171
	v_and_b32_e32 v191, 0xffff0000, v171
	v_sub_f32_e32 v184, v184, v222
	v_sub_f32_e32 v185, v185, v222
	v_sub_f32_e32 v186, v186, v222
	v_sub_f32_e32 v187, v187, v222
	v_sub_f32_e32 v188, v188, v222
	v_sub_f32_e32 v189, v189, v222
	v_sub_f32_e32 v190, v190, v222
	v_sub_f32_e32 v191, v191, v222
	v_mul_f32_e32 v184, v223, v184
	v_mul_f32_e32 v185, v223, v185
	v_mul_f32_e32 v186, v223, v186
	v_mul_f32_e32 v187, v223, v187
	v_mul_f32_e32 v188, v223, v188
	v_mul_f32_e32 v189, v223, v189
	v_mul_f32_e32 v190, v223, v190
	v_mul_f32_e32 v191, v223, v191
	v_pk_fma_f32 v[184:185], v[144:145], v[184:185], v[148:149]
	v_pk_fma_f32 v[186:187], v[146:147], v[186:187], v[150:151]
	v_pk_fma_f32 v[188:189], v[136:137], v[188:189], v[140:141]
	v_pk_fma_f32 v[190:191], v[138:139], v[190:191], v[142:143]
	v_mul_f32_e32 v184, 0x3fb504f3, v184
	v_mul_f32_e32 v185, 0x3fb504f3, v185
	v_mul_f32_e32 v186, 0x3fb504f3, v186
	v_mul_f32_e32 v187, 0x3fb504f3, v187
	v_mul_f32_e32 v188, 0x3fb504f3, v188
	v_mul_f32_e32 v189, 0x3fb504f3, v189
	v_mul_f32_e32 v190, 0x3fb504f3, v190
	v_mul_f32_e32 v191, 0x3fb504f3, v191
	v_pk_fma_f32 v[184:185], v[132:133], v[92:93], v[184:185]
	v_pk_fma_f32 v[186:187], v[134:135], v[94:95], v[186:187]
	v_pk_fma_f32 v[188:189], v[128:129], v[28:29], v[188:189]
	v_pk_fma_f32 v[190:191], v[130:131], v[30:31], v[190:191]
	v_cvt_pk_bf16_f32 v168, v184, v185
	v_cvt_pk_bf16_f32 v169, v186, v187
	v_cvt_pk_bf16_f32 v170, v188, v189
	v_cvt_pk_bf16_f32 v171, v190, v191
	global_load_dwordx4 v[92:95], v[248:249], off offset:256
	v_lshl_add_u64 v[248:249], v[248:249], 0, s[98:99]
	v_lshlrev_b32_e32 v184, 16, v172
	v_and_b32_e32 v185, 0xffff0000, v172
	v_lshlrev_b32_e32 v186, 16, v173
	v_and_b32_e32 v187, 0xffff0000, v173
	v_lshlrev_b32_e32 v188, 16, v174
	v_and_b32_e32 v189, 0xffff0000, v174
	v_lshlrev_b32_e32 v190, 16, v175
	v_and_b32_e32 v191, 0xffff0000, v175
	v_sub_f32_e32 v184, v184, v232
	v_sub_f32_e32 v185, v185, v232
	v_sub_f32_e32 v186, v186, v232
	v_sub_f32_e32 v187, v187, v232
	v_sub_f32_e32 v188, v188, v232
	v_sub_f32_e32 v189, v189, v232
	v_sub_f32_e32 v190, v190, v232
	v_sub_f32_e32 v191, v191, v232
	v_mul_f32_e32 v184, v233, v184
	v_mul_f32_e32 v185, v233, v185
	v_mul_f32_e32 v186, v233, v186
	v_mul_f32_e32 v187, v233, v187
	v_mul_f32_e32 v188, v233, v188
	v_mul_f32_e32 v189, v233, v189
	v_mul_f32_e32 v190, v233, v190
	v_mul_f32_e32 v191, v233, v191
	v_pk_fma_f32 v[184:185], v[144:145], v[184:185], v[148:149]
	v_pk_fma_f32 v[186:187], v[146:147], v[186:187], v[150:151]
	v_pk_fma_f32 v[188:189], v[136:137], v[188:189], v[140:141]
	v_pk_fma_f32 v[190:191], v[138:139], v[190:191], v[142:143]
	v_mul_f32_e32 v184, 0x3fb504f3, v184
	v_mul_f32_e32 v185, 0x3fb504f3, v185
	v_mul_f32_e32 v186, 0x3fb504f3, v186
	v_mul_f32_e32 v187, 0x3fb504f3, v187
	v_mul_f32_e32 v188, 0x3fb504f3, v188
	v_mul_f32_e32 v189, 0x3fb504f3, v189
	v_mul_f32_e32 v190, 0x3fb504f3, v190
	v_mul_f32_e32 v191, 0x3fb504f3, v191
	v_pk_fma_f32 v[184:185], v[132:133], v[84:85], v[184:185]
	v_pk_fma_f32 v[186:187], v[134:135], v[86:87], v[186:187]
	v_pk_fma_f32 v[188:189], v[128:129], v[20:21], v[188:189]
	v_pk_fma_f32 v[190:191], v[130:131], v[22:23], v[190:191]
	v_cvt_pk_bf16_f32 v172, v184, v185
	v_cvt_pk_bf16_f32 v173, v186, v187
	v_cvt_pk_bf16_f32 v174, v188, v189
	v_cvt_pk_bf16_f32 v175, v190, v191
	global_load_dwordx4 v[84:87], v[248:249], off offset:256
	v_lshl_add_u64 v[248:249], v[248:249], 0, s[98:99]
	v_lshlrev_b32_e32 v184, 16, v176
	v_and_b32_e32 v185, 0xffff0000, v176
	v_lshlrev_b32_e32 v186, 16, v177
	v_and_b32_e32 v187, 0xffff0000, v177
	v_lshlrev_b32_e32 v188, 16, v178
	v_and_b32_e32 v189, 0xffff0000, v178
	v_lshlrev_b32_e32 v190, 16, v179
	v_and_b32_e32 v191, 0xffff0000, v179
	v_sub_f32_e32 v184, v184, v234
	v_sub_f32_e32 v185, v185, v234
	v_sub_f32_e32 v186, v186, v234
	v_sub_f32_e32 v187, v187, v234
	v_sub_f32_e32 v188, v188, v234
	v_sub_f32_e32 v189, v189, v234
	v_sub_f32_e32 v190, v190, v234
	v_sub_f32_e32 v191, v191, v234
	v_mul_f32_e32 v184, v235, v184
	v_mul_f32_e32 v185, v235, v185
	v_mul_f32_e32 v186, v235, v186
	v_mul_f32_e32 v187, v235, v187
	v_mul_f32_e32 v188, v235, v188
	v_mul_f32_e32 v189, v235, v189
	v_mul_f32_e32 v190, v235, v190
	v_mul_f32_e32 v191, v235, v191
	v_pk_fma_f32 v[184:185], v[144:145], v[184:185], v[148:149]
	v_pk_fma_f32 v[186:187], v[146:147], v[186:187], v[150:151]
	v_pk_fma_f32 v[188:189], v[136:137], v[188:189], v[140:141]
	v_pk_fma_f32 v[190:191], v[138:139], v[190:191], v[142:143]
	v_mul_f32_e32 v184, 0x3fb504f3, v184
	v_mul_f32_e32 v185, 0x3fb504f3, v185
	v_mul_f32_e32 v186, 0x3fb504f3, v186
	v_mul_f32_e32 v187, 0x3fb504f3, v187
	v_mul_f32_e32 v188, 0x3fb504f3, v188
	v_mul_f32_e32 v189, 0x3fb504f3, v189
	v_mul_f32_e32 v190, 0x3fb504f3, v190
	v_mul_f32_e32 v191, 0x3fb504f3, v191
	v_pk_fma_f32 v[184:185], v[132:133], v[76:77], v[184:185]
	v_pk_fma_f32 v[186:187], v[134:135], v[78:79], v[186:187]
	v_pk_fma_f32 v[188:189], v[128:129], v[12:13], v[188:189]
	v_pk_fma_f32 v[190:191], v[130:131], v[14:15], v[190:191]
	v_cvt_pk_bf16_f32 v176, v184, v185
	v_cvt_pk_bf16_f32 v177, v186, v187
	v_cvt_pk_bf16_f32 v178, v188, v189
	v_cvt_pk_bf16_f32 v179, v190, v191
	global_load_dwordx4 v[76:79], v[248:249], off offset:256
	v_lshl_add_u64 v[248:249], v[248:249], 0, s[98:99]
	v_lshlrev_b32_e32 v184, 16, v180
	v_and_b32_e32 v185, 0xffff0000, v180
	v_lshlrev_b32_e32 v186, 16, v181
	v_and_b32_e32 v187, 0xffff0000, v181
	v_lshlrev_b32_e32 v188, 16, v182
	v_and_b32_e32 v189, 0xffff0000, v182
	v_lshlrev_b32_e32 v190, 16, v183
	v_and_b32_e32 v191, 0xffff0000, v183
	v_sub_f32_e32 v184, v184, v250
	v_sub_f32_e32 v185, v185, v250
	v_sub_f32_e32 v186, v186, v250
	v_sub_f32_e32 v187, v187, v250
	v_sub_f32_e32 v188, v188, v250
	v_sub_f32_e32 v189, v189, v250
	v_sub_f32_e32 v190, v190, v250
	v_sub_f32_e32 v191, v191, v250
	v_mul_f32_e32 v184, v251, v184
	v_mul_f32_e32 v185, v251, v185
	v_mul_f32_e32 v186, v251, v186
	v_mul_f32_e32 v187, v251, v187
	v_mul_f32_e32 v188, v251, v188
	v_mul_f32_e32 v189, v251, v189
	v_mul_f32_e32 v190, v251, v190
	v_mul_f32_e32 v191, v251, v191
	v_pk_fma_f32 v[184:185], v[144:145], v[184:185], v[148:149]
	v_pk_fma_f32 v[186:187], v[146:147], v[186:187], v[150:151]
	v_pk_fma_f32 v[188:189], v[136:137], v[188:189], v[140:141]
	v_pk_fma_f32 v[190:191], v[138:139], v[190:191], v[142:143]
	v_mul_f32_e32 v184, 0x3fb504f3, v184
	v_mul_f32_e32 v185, 0x3fb504f3, v185
	v_mul_f32_e32 v186, 0x3fb504f3, v186
	v_mul_f32_e32 v187, 0x3fb504f3, v187
	v_mul_f32_e32 v188, 0x3fb504f3, v188
	v_mul_f32_e32 v189, 0x3fb504f3, v189
	v_mul_f32_e32 v190, 0x3fb504f3, v190
	v_mul_f32_e32 v191, 0x3fb504f3, v191
	v_pk_fma_f32 v[184:185], v[132:133], v[68:69], v[184:185]
	v_pk_fma_f32 v[186:187], v[134:135], v[70:71], v[186:187]
	v_pk_fma_f32 v[188:189], v[128:129], v[4:5], v[188:189]
	v_pk_fma_f32 v[190:191], v[130:131], v[6:7], v[190:191]
	v_cvt_pk_bf16_f32 v180, v184, v185
	v_cvt_pk_bf16_f32 v181, v186, v187
	v_cvt_pk_bf16_f32 v182, v188, v189
	v_cvt_pk_bf16_f32 v183, v190, v191
	global_load_dwordx4 v[68:71], v[248:249], off offset:256
	global_load_dwordx4 v[128:131], v[210:211], off offset:528
	global_load_dwordx4 v[132:135], v[210:211], off offset:512
	global_load_dwordx4 v[136:139], v[212:213], off offset:528
	global_load_dwordx4 v[144:147], v[212:213], off offset:512
	global_load_dwordx4 v[140:143], v[208:209], off offset:528
	global_load_dwordx4 v[148:151], v[208:209], off offset:512
	v_mov_b32_e32 v248, v242
	v_mov_b32_e32 v249, v243
	global_store_dwordx4 v[248:249], v[152:155], off nt
	v_lshl_add_u64 v[248:249], v[248:249], 0, s[98:99]
	global_store_dwordx4 v[248:249], v[156:159], off nt
	v_lshl_add_u64 v[248:249], v[248:249], 0, s[98:99]
	global_store_dwordx4 v[248:249], v[160:163], off nt
	v_lshl_add_u64 v[248:249], v[248:249], 0, s[98:99]
	global_store_dwordx4 v[248:249], v[164:167], off nt
	v_lshl_add_u64 v[248:249], v[248:249], 0, s[100:101]
	global_store_dwordx4 v[248:249], v[168:171], off nt
	v_lshl_add_u64 v[248:249], v[248:249], 0, s[98:99]
	global_store_dwordx4 v[248:249], v[172:175], off nt
	v_lshl_add_u64 v[248:249], v[248:249], 0, s[98:99]
	global_store_dwordx4 v[248:249], v[176:179], off nt
	v_lshl_add_u64 v[248:249], v[248:249], 0, s[98:99]
	global_store_dwordx4 v[248:249], v[180:183], off nt
	s_waitcnt vmcnt(8)
	v_lshlrev_b32_e32 v184, 16, v124
	v_and_b32_e32 v185, 0xffff0000, v124
	v_lshlrev_b32_e32 v186, 16, v125
	v_and_b32_e32 v187, 0xffff0000, v125
	v_lshlrev_b32_e32 v188, 16, v126
	v_and_b32_e32 v189, 0xffff0000, v126
	v_lshlrev_b32_e32 v190, 16, v127
	v_and_b32_e32 v191, 0xffff0000, v127
	v_sub_f32_e32 v184, v184, v214
	v_sub_f32_e32 v185, v185, v214
	v_sub_f32_e32 v186, v186, v214
	v_sub_f32_e32 v187, v187, v214
	v_sub_f32_e32 v188, v188, v214
	v_sub_f32_e32 v189, v189, v214
	v_sub_f32_e32 v190, v190, v214
	v_sub_f32_e32 v191, v191, v214
	v_mul_f32_e32 v184, v215, v184
	v_mul_f32_e32 v185, v215, v185
	v_mul_f32_e32 v186, v215, v186
	v_mul_f32_e32 v187, v215, v187
	v_mul_f32_e32 v188, v215, v188
	v_mul_f32_e32 v189, v215, v189
	v_mul_f32_e32 v190, v215, v190
	v_mul_f32_e32 v191, v215, v191
	v_pk_fma_f32 v[184:185], v[144:145], v[184:185], v[148:149]
	v_pk_fma_f32 v[186:187], v[146:147], v[186:187], v[150:151]
	v_pk_fma_f32 v[188:189], v[136:137], v[188:189], v[140:141]
	v_pk_fma_f32 v[190:191], v[138:139], v[190:191], v[142:143]
	v_mul_f32_e32 v184, 0x3fb504f3, v184
	v_mul_f32_e32 v185, 0x3fb504f3, v185
	v_mul_f32_e32 v186, 0x3fb504f3, v186
	v_mul_f32_e32 v187, 0x3fb504f3, v187
	v_mul_f32_e32 v188, 0x3fb504f3, v188
	v_mul_f32_e32 v189, 0x3fb504f3, v189
	v_mul_f32_e32 v190, 0x3fb504f3, v190
	v_mul_f32_e32 v191, 0x3fb504f3, v191
	v_pk_fma_f32 v[184:185], v[132:133], v[120:121], v[184:185]
	v_pk_fma_f32 v[186:187], v[134:135], v[122:123], v[186:187]
	v_pk_fma_f32 v[188:189], v[128:129], v[56:57], v[188:189]
	v_pk_fma_f32 v[190:191], v[130:131], v[58:59], v[190:191]
	v_cvt_pk_bf16_f32 v124, v184, v185
	v_cvt_pk_bf16_f32 v125, v186, v187
	v_cvt_pk_bf16_f32 v126, v188, v189
	v_cvt_pk_bf16_f32 v127, v190, v191
	v_lshlrev_b32_e32 v184, 16, v116
	v_and_b32_e32 v185, 0xffff0000, v116
	v_lshlrev_b32_e32 v186, 16, v117
	v_and_b32_e32 v187, 0xffff0000, v117
	v_lshlrev_b32_e32 v188, 16, v118
	v_and_b32_e32 v189, 0xffff0000, v118
	v_lshlrev_b32_e32 v190, 16, v119
	v_and_b32_e32 v191, 0xffff0000, v119
	v_sub_f32_e32 v184, v184, v216
	v_sub_f32_e32 v185, v185, v216
	v_sub_f32_e32 v186, v186, v216
	v_sub_f32_e32 v187, v187, v216
	v_sub_f32_e32 v188, v188, v216
	v_sub_f32_e32 v189, v189, v216
	v_sub_f32_e32 v190, v190, v216
	v_sub_f32_e32 v191, v191, v216
	v_mul_f32_e32 v184, v217, v184
	v_mul_f32_e32 v185, v217, v185
	v_mul_f32_e32 v186, v217, v186
	v_mul_f32_e32 v187, v217, v187
	v_mul_f32_e32 v188, v217, v188
	v_mul_f32_e32 v189, v217, v189
	v_mul_f32_e32 v190, v217, v190
	v_mul_f32_e32 v191, v217, v191
	v_pk_fma_f32 v[184:185], v[144:145], v[184:185], v[148:149]
	v_pk_fma_f32 v[186:187], v[146:147], v[186:187], v[150:151]
	v_pk_fma_f32 v[188:189], v[136:137], v[188:189], v[140:141]
	v_pk_fma_f32 v[190:191], v[138:139], v[190:191], v[142:143]
	v_mul_f32_e32 v184, 0x3fb504f3, v184
	v_mul_f32_e32 v185, 0x3fb504f3, v185
	v_mul_f32_e32 v186, 0x3fb504f3, v186
	v_mul_f32_e32 v187, 0x3fb504f3, v187
	v_mul_f32_e32 v188, 0x3fb504f3, v188
	v_mul_f32_e32 v189, 0x3fb504f3, v189
	v_mul_f32_e32 v190, 0x3fb504f3, v190
	v_mul_f32_e32 v191, 0x3fb504f3, v191
	v_pk_fma_f32 v[184:185], v[132:133], v[112:113], v[184:185]
	v_pk_fma_f32 v[186:187], v[134:135], v[114:115], v[186:187]
	v_pk_fma_f32 v[188:189], v[128:129], v[48:49], v[188:189]
	v_pk_fma_f32 v[190:191], v[130:131], v[50:51], v[190:191]
	v_cvt_pk_bf16_f32 v116, v184, v185
	v_cvt_pk_bf16_f32 v117, v186, v187
	v_cvt_pk_bf16_f32 v118, v188, v189
	v_cvt_pk_bf16_f32 v119, v190, v191
	v_lshlrev_b32_e32 v184, 16, v108
	v_and_b32_e32 v185, 0xffff0000, v108
	v_lshlrev_b32_e32 v186, 16, v109
	v_and_b32_e32 v187, 0xffff0000, v109
	v_lshlrev_b32_e32 v188, 16, v110
	v_and_b32_e32 v189, 0xffff0000, v110
	v_lshlrev_b32_e32 v190, 16, v111
	v_and_b32_e32 v191, 0xffff0000, v111
	v_sub_f32_e32 v184, v184, v218
	v_sub_f32_e32 v185, v185, v218
	v_sub_f32_e32 v186, v186, v218
	v_sub_f32_e32 v187, v187, v218
	v_sub_f32_e32 v188, v188, v218
	v_sub_f32_e32 v189, v189, v218
	v_sub_f32_e32 v190, v190, v218
	v_sub_f32_e32 v191, v191, v218
	v_mul_f32_e32 v184, v219, v184
	v_mul_f32_e32 v185, v219, v185
	v_mul_f32_e32 v186, v219, v186
	v_mul_f32_e32 v187, v219, v187
	v_mul_f32_e32 v188, v219, v188
	v_mul_f32_e32 v189, v219, v189
	v_mul_f32_e32 v190, v219, v190
	v_mul_f32_e32 v191, v219, v191
	v_pk_fma_f32 v[184:185], v[144:145], v[184:185], v[148:149]
	v_pk_fma_f32 v[186:187], v[146:147], v[186:187], v[150:151]
	v_pk_fma_f32 v[188:189], v[136:137], v[188:189], v[140:141]
	v_pk_fma_f32 v[190:191], v[138:139], v[190:191], v[142:143]
	v_mul_f32_e32 v184, 0x3fb504f3, v184
	v_mul_f32_e32 v185, 0x3fb504f3, v185
	v_mul_f32_e32 v186, 0x3fb504f3, v186
	v_mul_f32_e32 v187, 0x3fb504f3, v187
	v_mul_f32_e32 v188, 0x3fb504f3, v188
	v_mul_f32_e32 v189, 0x3fb504f3, v189
	v_mul_f32_e32 v190, 0x3fb504f3, v190
	v_mul_f32_e32 v191, 0x3fb504f3, v191
	v_pk_fma_f32 v[184:185], v[132:133], v[104:105], v[184:185]
	v_pk_fma_f32 v[186:187], v[134:135], v[106:107], v[186:187]
	v_pk_fma_f32 v[188:189], v[128:129], v[40:41], v[188:189]
	v_pk_fma_f32 v[190:191], v[130:131], v[42:43], v[190:191]
	v_cvt_pk_bf16_f32 v108, v184, v185
	v_cvt_pk_bf16_f32 v109, v186, v187
	v_cvt_pk_bf16_f32 v110, v188, v189
	v_cvt_pk_bf16_f32 v111, v190, v191
	v_lshlrev_b32_e32 v184, 16, v100
	v_and_b32_e32 v185, 0xffff0000, v100
	v_lshlrev_b32_e32 v186, 16, v101
	v_and_b32_e32 v187, 0xffff0000, v101
	v_lshlrev_b32_e32 v188, 16, v102
	v_and_b32_e32 v189, 0xffff0000, v102
	v_lshlrev_b32_e32 v190, 16, v103
	v_and_b32_e32 v191, 0xffff0000, v103
	v_sub_f32_e32 v184, v184, v220
	v_sub_f32_e32 v185, v185, v220
	v_sub_f32_e32 v186, v186, v220
	v_sub_f32_e32 v187, v187, v220
	v_sub_f32_e32 v188, v188, v220
	v_sub_f32_e32 v189, v189, v220
	v_sub_f32_e32 v190, v190, v220
	v_sub_f32_e32 v191, v191, v220
	v_mul_f32_e32 v184, v221, v184
	v_mul_f32_e32 v185, v221, v185
	v_mul_f32_e32 v186, v221, v186
	v_mul_f32_e32 v187, v221, v187
	v_mul_f32_e32 v188, v221, v188
	v_mul_f32_e32 v189, v221, v189
	v_mul_f32_e32 v190, v221, v190
	v_mul_f32_e32 v191, v221, v191
	v_pk_fma_f32 v[184:185], v[144:145], v[184:185], v[148:149]
	v_pk_fma_f32 v[186:187], v[146:147], v[186:187], v[150:151]
	v_pk_fma_f32 v[188:189], v[136:137], v[188:189], v[140:141]
	v_pk_fma_f32 v[190:191], v[138:139], v[190:191], v[142:143]
	v_mul_f32_e32 v184, 0x3fb504f3, v184
	v_mul_f32_e32 v185, 0x3fb504f3, v185
	v_mul_f32_e32 v186, 0x3fb504f3, v186
	v_mul_f32_e32 v187, 0x3fb504f3, v187
	v_mul_f32_e32 v188, 0x3fb504f3, v188
	v_mul_f32_e32 v189, 0x3fb504f3, v189
	v_mul_f32_e32 v190, 0x3fb504f3, v190
	v_mul_f32_e32 v191, 0x3fb504f3, v191
	v_pk_fma_f32 v[184:185], v[132:133], v[96:97], v[184:185]
	v_pk_fma_f32 v[186:187], v[134:135], v[98:99], v[186:187]
	v_pk_fma_f32 v[188:189], v[128:129], v[32:33], v[188:189]
	v_pk_fma_f32 v[190:191], v[130:131], v[34:35], v[190:191]
	v_cvt_pk_bf16_f32 v100, v184, v185
	v_cvt_pk_bf16_f32 v101, v186, v187
	v_cvt_pk_bf16_f32 v102, v188, v189
	v_cvt_pk_bf16_f32 v103, v190, v191
	v_lshlrev_b32_e32 v184, 16, v92
	v_and_b32_e32 v185, 0xffff0000, v92
	v_lshlrev_b32_e32 v186, 16, v93
	v_and_b32_e32 v187, 0xffff0000, v93
	v_lshlrev_b32_e32 v188, 16, v94
	v_and_b32_e32 v189, 0xffff0000, v94
	v_lshlrev_b32_e32 v190, 16, v95
	v_and_b32_e32 v191, 0xffff0000, v95
	v_sub_f32_e32 v184, v184, v222
	v_sub_f32_e32 v185, v185, v222
	v_sub_f32_e32 v186, v186, v222
	v_sub_f32_e32 v187, v187, v222
	v_sub_f32_e32 v188, v188, v222
	v_sub_f32_e32 v189, v189, v222
	v_sub_f32_e32 v190, v190, v222
	v_sub_f32_e32 v191, v191, v222
	v_mul_f32_e32 v184, v223, v184
	v_mul_f32_e32 v185, v223, v185
	v_mul_f32_e32 v186, v223, v186
	v_mul_f32_e32 v187, v223, v187
	v_mul_f32_e32 v188, v223, v188
	v_mul_f32_e32 v189, v223, v189
	v_mul_f32_e32 v190, v223, v190
	v_mul_f32_e32 v191, v223, v191
	v_pk_fma_f32 v[184:185], v[144:145], v[184:185], v[148:149]
	v_pk_fma_f32 v[186:187], v[146:147], v[186:187], v[150:151]
	v_pk_fma_f32 v[188:189], v[136:137], v[188:189], v[140:141]
	v_pk_fma_f32 v[190:191], v[138:139], v[190:191], v[142:143]
	v_mul_f32_e32 v184, 0x3fb504f3, v184
	v_mul_f32_e32 v185, 0x3fb504f3, v185
	v_mul_f32_e32 v186, 0x3fb504f3, v186
	v_mul_f32_e32 v187, 0x3fb504f3, v187
	v_mul_f32_e32 v188, 0x3fb504f3, v188
	v_mul_f32_e32 v189, 0x3fb504f3, v189
	v_mul_f32_e32 v190, 0x3fb504f3, v190
	v_mul_f32_e32 v191, 0x3fb504f3, v191
	v_pk_fma_f32 v[184:185], v[132:133], v[88:89], v[184:185]
	v_pk_fma_f32 v[186:187], v[134:135], v[90:91], v[186:187]
	v_pk_fma_f32 v[188:189], v[128:129], v[24:25], v[188:189]
	v_pk_fma_f32 v[190:191], v[130:131], v[26:27], v[190:191]
	v_cvt_pk_bf16_f32 v92, v184, v185
	v_cvt_pk_bf16_f32 v93, v186, v187
	v_cvt_pk_bf16_f32 v94, v188, v189
	v_cvt_pk_bf16_f32 v95, v190, v191
	v_lshlrev_b32_e32 v184, 16, v84
	v_and_b32_e32 v185, 0xffff0000, v84
	v_lshlrev_b32_e32 v186, 16, v85
	v_and_b32_e32 v187, 0xffff0000, v85
	v_lshlrev_b32_e32 v188, 16, v86
	v_and_b32_e32 v189, 0xffff0000, v86
	v_lshlrev_b32_e32 v190, 16, v87
	v_and_b32_e32 v191, 0xffff0000, v87
	v_sub_f32_e32 v184, v184, v232
	v_sub_f32_e32 v185, v185, v232
	v_sub_f32_e32 v186, v186, v232
	v_sub_f32_e32 v187, v187, v232
	v_sub_f32_e32 v188, v188, v232
	v_sub_f32_e32 v189, v189, v232
	v_sub_f32_e32 v190, v190, v232
	v_sub_f32_e32 v191, v191, v232
	v_mul_f32_e32 v184, v233, v184
	v_mul_f32_e32 v185, v233, v185
	v_mul_f32_e32 v186, v233, v186
	v_mul_f32_e32 v187, v233, v187
	v_mul_f32_e32 v188, v233, v188
	v_mul_f32_e32 v189, v233, v189
	v_mul_f32_e32 v190, v233, v190
	v_mul_f32_e32 v191, v233, v191
	v_pk_fma_f32 v[184:185], v[144:145], v[184:185], v[148:149]
	v_pk_fma_f32 v[186:187], v[146:147], v[186:187], v[150:151]
	v_pk_fma_f32 v[188:189], v[136:137], v[188:189], v[140:141]
	v_pk_fma_f32 v[190:191], v[138:139], v[190:191], v[142:143]
	v_mul_f32_e32 v184, 0x3fb504f3, v184
	v_mul_f32_e32 v185, 0x3fb504f3, v185
	v_mul_f32_e32 v186, 0x3fb504f3, v186
	v_mul_f32_e32 v187, 0x3fb504f3, v187
	v_mul_f32_e32 v188, 0x3fb504f3, v188
	v_mul_f32_e32 v189, 0x3fb504f3, v189
	v_mul_f32_e32 v190, 0x3fb504f3, v190
	v_mul_f32_e32 v191, 0x3fb504f3, v191
	v_pk_fma_f32 v[184:185], v[132:133], v[80:81], v[184:185]
	v_pk_fma_f32 v[186:187], v[134:135], v[82:83], v[186:187]
	v_pk_fma_f32 v[188:189], v[128:129], v[16:17], v[188:189]
	v_pk_fma_f32 v[190:191], v[130:131], v[18:19], v[190:191]
	v_cvt_pk_bf16_f32 v84, v184, v185
	v_cvt_pk_bf16_f32 v85, v186, v187
	v_cvt_pk_bf16_f32 v86, v188, v189
	v_cvt_pk_bf16_f32 v87, v190, v191
	v_lshlrev_b32_e32 v184, 16, v76
	v_and_b32_e32 v185, 0xffff0000, v76
	v_lshlrev_b32_e32 v186, 16, v77
	v_and_b32_e32 v187, 0xffff0000, v77
	v_lshlrev_b32_e32 v188, 16, v78
	v_and_b32_e32 v189, 0xffff0000, v78
	v_lshlrev_b32_e32 v190, 16, v79
	v_and_b32_e32 v191, 0xffff0000, v79
	v_sub_f32_e32 v184, v184, v234
	v_sub_f32_e32 v185, v185, v234
	v_sub_f32_e32 v186, v186, v234
	v_sub_f32_e32 v187, v187, v234
	v_sub_f32_e32 v188, v188, v234
	v_sub_f32_e32 v189, v189, v234
	v_sub_f32_e32 v190, v190, v234
	v_sub_f32_e32 v191, v191, v234
	v_mul_f32_e32 v184, v235, v184
	v_mul_f32_e32 v185, v235, v185
	v_mul_f32_e32 v186, v235, v186
	v_mul_f32_e32 v187, v235, v187
	v_mul_f32_e32 v188, v235, v188
	v_mul_f32_e32 v189, v235, v189
	v_mul_f32_e32 v190, v235, v190
	v_mul_f32_e32 v191, v235, v191
	v_pk_fma_f32 v[184:185], v[144:145], v[184:185], v[148:149]
	v_pk_fma_f32 v[186:187], v[146:147], v[186:187], v[150:151]
	v_pk_fma_f32 v[188:189], v[136:137], v[188:189], v[140:141]
	v_pk_fma_f32 v[190:191], v[138:139], v[190:191], v[142:143]
	v_mul_f32_e32 v184, 0x3fb504f3, v184
	v_mul_f32_e32 v185, 0x3fb504f3, v185
	v_mul_f32_e32 v186, 0x3fb504f3, v186
	v_mul_f32_e32 v187, 0x3fb504f3, v187
	v_mul_f32_e32 v188, 0x3fb504f3, v188
	v_mul_f32_e32 v189, 0x3fb504f3, v189
	v_mul_f32_e32 v190, 0x3fb504f3, v190
	v_mul_f32_e32 v191, 0x3fb504f3, v191
	v_pk_fma_f32 v[184:185], v[132:133], v[72:73], v[184:185]
	v_pk_fma_f32 v[186:187], v[134:135], v[74:75], v[186:187]
	v_pk_fma_f32 v[188:189], v[128:129], v[8:9], v[188:189]
	v_pk_fma_f32 v[190:191], v[130:131], v[10:11], v[190:191]
	v_cvt_pk_bf16_f32 v76, v184, v185
	v_cvt_pk_bf16_f32 v77, v186, v187
	v_cvt_pk_bf16_f32 v78, v188, v189
	v_cvt_pk_bf16_f32 v79, v190, v191
	v_lshlrev_b32_e32 v184, 16, v68
	v_and_b32_e32 v185, 0xffff0000, v68
	v_lshlrev_b32_e32 v186, 16, v69
	v_and_b32_e32 v187, 0xffff0000, v69
	v_lshlrev_b32_e32 v188, 16, v70
	v_and_b32_e32 v189, 0xffff0000, v70
	v_lshlrev_b32_e32 v190, 16, v71
	v_and_b32_e32 v191, 0xffff0000, v71
	v_sub_f32_e32 v184, v184, v250
	v_sub_f32_e32 v185, v185, v250
	v_sub_f32_e32 v186, v186, v250
	v_sub_f32_e32 v187, v187, v250
	v_sub_f32_e32 v188, v188, v250
	v_sub_f32_e32 v189, v189, v250
	v_sub_f32_e32 v190, v190, v250
	v_sub_f32_e32 v191, v191, v250
	v_mul_f32_e32 v184, v251, v184
	v_mul_f32_e32 v185, v251, v185
	v_mul_f32_e32 v186, v251, v186
	v_mul_f32_e32 v187, v251, v187
	v_mul_f32_e32 v188, v251, v188
	v_mul_f32_e32 v189, v251, v189
	v_mul_f32_e32 v190, v251, v190
	v_mul_f32_e32 v191, v251, v191
	v_pk_fma_f32 v[184:185], v[144:145], v[184:185], v[148:149]
	v_pk_fma_f32 v[186:187], v[146:147], v[186:187], v[150:151]
	v_pk_fma_f32 v[188:189], v[136:137], v[188:189], v[140:141]
	v_pk_fma_f32 v[190:191], v[138:139], v[190:191], v[142:143]
	v_mul_f32_e32 v184, 0x3fb504f3, v184
	v_mul_f32_e32 v185, 0x3fb504f3, v185
	v_mul_f32_e32 v186, 0x3fb504f3, v186
	v_mul_f32_e32 v187, 0x3fb504f3, v187
	v_mul_f32_e32 v188, 0x3fb504f3, v188
	v_mul_f32_e32 v189, 0x3fb504f3, v189
	v_mul_f32_e32 v190, 0x3fb504f3, v190
	v_mul_f32_e32 v191, 0x3fb504f3, v191
	v_pk_fma_f32 v[184:185], v[132:133], v[64:65], v[184:185]
	v_pk_fma_f32 v[186:187], v[134:135], v[66:67], v[186:187]
	v_pk_fma_f32 v[188:189], v[128:129], v[0:1], v[188:189]
	v_pk_fma_f32 v[190:191], v[130:131], v[2:3], v[190:191]
	v_cvt_pk_bf16_f32 v68, v184, v185
	v_cvt_pk_bf16_f32 v69, v186, v187
	v_cvt_pk_bf16_f32 v70, v188, v189
	v_cvt_pk_bf16_f32 v71, v190, v191
	v_mov_b32_e32 v248, v242
	v_mov_b32_e32 v249, v243
	global_store_dwordx4 v[248:249], v[124:127], off offset:256 nt
	v_lshl_add_u64 v[248:249], v[248:249], 0, s[98:99]
	global_store_dwordx4 v[248:249], v[116:119], off offset:256 nt
	v_lshl_add_u64 v[248:249], v[248:249], 0, s[98:99]
	global_store_dwordx4 v[248:249], v[108:111], off offset:256 nt
	v_lshl_add_u64 v[248:249], v[248:249], 0, s[98:99]
	global_store_dwordx4 v[248:249], v[100:103], off offset:256 nt
	v_lshl_add_u64 v[248:249], v[248:249], 0, s[100:101]
	global_store_dwordx4 v[248:249], v[92:95], off offset:256 nt
	v_lshl_add_u64 v[248:249], v[248:249], 0, s[98:99]
	global_store_dwordx4 v[248:249], v[84:87], off offset:256 nt
	v_lshl_add_u64 v[248:249], v[248:249], 0, s[98:99]
	global_store_dwordx4 v[248:249], v[76:79], off offset:256 nt
	v_lshl_add_u64 v[248:249], v[248:249], 0, s[98:99]
	global_store_dwordx4 v[248:249], v[68:71], off offset:256 nt
	s_mov_b64 s[4:5], 0
	s_branch .LBB0_844

.LBB0_784:
	s_mov_b32 s46, 0x3fb504f3
	v_pk_mul_f32 v[218:219], v[222:223], s[46:47] op_sel_hi:[1,0]
	v_pk_mul_f32 v[166:167], v[166:167], s[46:47] op_sel_hi:[1,0]
	v_pk_fma_f32 v[218:219], v[134:135], v[126:127], v[218:219]
	v_pk_mul_f32 v[164:165], v[164:165], s[46:47] op_sel_hi:[1,0]
	v_pk_mul_f32 v[220:221], v[220:221], s[46:47] op_sel_hi:[1,0]
	v_pk_fma_f32 v[222:223], v[130:131], v[62:63], v[166:167]
	v_pk_fma_f32 v[166:167], v[128:129], v[60:61], v[164:165]
	v_cvt_pk_bf16_f32 v165, v218, v219
	v_lshl_add_u64 v[218:219], v[186:187], 0, s[6:7]
	v_pk_fma_f32 v[220:221], v[132:133], v[124:125], v[220:221]
	v_lshlrev_b64 v[218:219], 11, v[218:219]
	v_cvt_pk_bf16_f32 v164, v220, v221
	v_cvt_pk_bf16_f32 v166, v166, v167
	v_cvt_pk_bf16_f32 v167, v222, v223
	v_lshl_add_u64 v[218:219], v[172:173], 0, v[218:219]
	global_store_dwordx4 v[218:219], v[164:167], off nt
	s_and_b64 vcc, exec, s[4:5]
	s_nop 0
	v_lshlrev_b32_e32 v164, 16, v160
	v_and_b32_e32 v165, 0xffff0000, v160
	v_lshlrev_b32_e32 v166, 16, v161
	v_and_b32_e32 v167, 0xffff0000, v161
	v_lshlrev_b32_e32 v160, 16, v162
	v_and_b32_e32 v161, 0xffff0000, v162
	v_lshlrev_b32_e32 v162, 16, v163
	v_and_b32_e32 v163, 0xffff0000, v163
	s_cbranch_vccnz .LBB0_786
	v_sub_f32_e32 v167, v167, v216
	v_sub_f32_e32 v166, v166, v216
	v_sub_f32_e32 v165, v165, v216
	v_sub_f32_e32 v164, v164, v216
	v_mov_b32_e32 v218, v217
	v_sub_f32_e32 v163, v163, v216
	v_sub_f32_e32 v162, v162, v216
	v_sub_f32_e32 v161, v161, v216
	v_sub_f32_e32 v160, v160, v216
	v_pk_mul_f32 v[164:165], v[218:219], v[164:165] op_sel_hi:[0,1]
	v_pk_mul_f32 v[166:167], v[218:219], v[166:167] op_sel_hi:[0,1]
	v_pk_mul_f32 v[160:161], v[218:219], v[160:161] op_sel_hi:[0,1]
	v_pk_mul_f32 v[162:163], v[218:219], v[162:163] op_sel_hi:[0,1]
	v_pk_fma_f32 v[166:167], v[146:147], v[166:167], v[150:151]
	v_pk_fma_f32 v[164:165], v[144:145], v[164:165], v[148:149]
	v_pk_fma_f32 v[162:163], v[138:139], v[162:163], v[142:143]
	v_pk_fma_f32 v[160:161], v[136:137], v[160:161], v[140:141]
.LBB0_786:
	v_pk_mul_f32 v[164:165], v[164:165], s[46:47] op_sel_hi:[1,0]
	v_pk_mul_f32 v[162:163], v[162:163], s[46:47] op_sel_hi:[1,0]
	v_pk_fma_f32 v[164:165], v[132:133], v[116:117], v[164:165]
	v_pk_mul_f32 v[160:161], v[160:161], s[46:47] op_sel_hi:[1,0]
	v_pk_mul_f32 v[166:167], v[166:167], s[46:47] op_sel_hi:[1,0]
	v_pk_fma_f32 v[216:217], v[130:131], v[54:55], v[162:163]
	v_pk_fma_f32 v[162:163], v[128:129], v[52:53], v[160:161]
	v_cvt_pk_bf16_f32 v160, v164, v165
	v_lshl_add_u64 v[164:165], v[184:185], 0, s[6:7]
	v_pk_fma_f32 v[166:167], v[134:135], v[118:119], v[166:167]
	v_lshlrev_b64 v[164:165], 11, v[164:165]
	v_cvt_pk_bf16_f32 v161, v166, v167
	v_cvt_pk_bf16_f32 v162, v162, v163
	v_cvt_pk_bf16_f32 v163, v216, v217
	v_lshl_add_u64 v[164:165], v[172:173], 0, v[164:165]
	global_store_dwordx4 v[164:165], v[160:163], off nt
	s_and_b64 vcc, exec, s[4:5]
	s_nop 0
	v_lshlrev_b32_e32 v160, 16, v156
	v_and_b32_e32 v161, 0xffff0000, v156
	v_lshlrev_b32_e32 v162, 16, v157
	v_and_b32_e32 v163, 0xffff0000, v157
	v_lshlrev_b32_e32 v156, 16, v158
	v_and_b32_e32 v157, 0xffff0000, v158
	v_lshlrev_b32_e32 v158, 16, v159
	v_and_b32_e32 v159, 0xffff0000, v159
	s_cbranch_vccnz .LBB0_788
	v_sub_f32_e32 v163, v163, v214
	v_sub_f32_e32 v162, v162, v214
	v_sub_f32_e32 v161, v161, v214
	v_sub_f32_e32 v160, v160, v214
	v_mov_b32_e32 v164, v215
	v_sub_f32_e32 v159, v159, v214
	v_sub_f32_e32 v158, v158, v214
	v_sub_f32_e32 v157, v157, v214
	v_sub_f32_e32 v156, v156, v214
	v_pk_mul_f32 v[160:161], v[164:165], v[160:161] op_sel_hi:[0,1]
	v_pk_mul_f32 v[162:163], v[164:165], v[162:163] op_sel_hi:[0,1]
	v_pk_mul_f32 v[156:157], v[164:165], v[156:157] op_sel_hi:[0,1]
	v_pk_mul_f32 v[158:159], v[164:165], v[158:159] op_sel_hi:[0,1]
	v_pk_fma_f32 v[162:163], v[146:147], v[162:163], v[150:151]
	v_pk_fma_f32 v[160:161], v[144:145], v[160:161], v[148:149]
	v_pk_fma_f32 v[158:159], v[138:139], v[158:159], v[142:143]
	v_pk_fma_f32 v[156:157], v[136:137], v[156:157], v[140:141]
.LBB0_788:
	v_pk_mul_f32 v[160:161], v[160:161], s[46:47] op_sel_hi:[1,0]
	v_pk_mul_f32 v[158:159], v[158:159], s[46:47] op_sel_hi:[1,0]
	v_pk_fma_f32 v[160:161], v[132:133], v[108:109], v[160:161]
	v_pk_mul_f32 v[156:157], v[156:157], s[46:47] op_sel_hi:[1,0]
	v_pk_mul_f32 v[162:163], v[162:163], s[46:47] op_sel_hi:[1,0]
	v_pk_fma_f32 v[164:165], v[130:131], v[46:47], v[158:159]
	v_pk_fma_f32 v[158:159], v[128:129], v[44:45], v[156:157]
	v_cvt_pk_bf16_f32 v156, v160, v161
	v_lshl_add_u64 v[160:161], v[182:183], 0, s[6:7]
	v_pk_fma_f32 v[162:163], v[134:135], v[110:111], v[162:163]
	v_lshlrev_b64 v[160:161], 11, v[160:161]
	v_cvt_pk_bf16_f32 v157, v162, v163
	v_cvt_pk_bf16_f32 v158, v158, v159
	v_cvt_pk_bf16_f32 v159, v164, v165
	v_lshl_add_u64 v[160:161], v[172:173], 0, v[160:161]
	global_store_dwordx4 v[160:161], v[156:159], off nt
	s_and_b64 vcc, exec, s[4:5]
	s_nop 0
	v_lshlrev_b32_e32 v156, 16, v152
	v_and_b32_e32 v157, 0xffff0000, v152
	v_lshlrev_b32_e32 v158, 16, v153
	v_and_b32_e32 v159, 0xffff0000, v153
	v_lshlrev_b32_e32 v152, 16, v154
	v_and_b32_e32 v153, 0xffff0000, v154
	v_lshlrev_b32_e32 v154, 16, v155
	v_and_b32_e32 v155, 0xffff0000, v155
	s_cbranch_vccnz .LBB0_790
	v_sub_f32_e32 v159, v159, v170
	v_sub_f32_e32 v158, v158, v170
	v_sub_f32_e32 v157, v157, v170
	v_sub_f32_e32 v156, v156, v170
	v_mov_b32_e32 v160, v171
	v_sub_f32_e32 v155, v155, v170
	v_sub_f32_e32 v154, v154, v170
	v_sub_f32_e32 v153, v153, v170
	v_sub_f32_e32 v152, v152, v170
	v_pk_mul_f32 v[156:157], v[160:161], v[156:157] op_sel_hi:[0,1]
	v_pk_mul_f32 v[158:159], v[160:161], v[158:159] op_sel_hi:[0,1]
	v_pk_mul_f32 v[152:153], v[160:161], v[152:153] op_sel_hi:[0,1]
	v_pk_mul_f32 v[154:155], v[160:161], v[154:155] op_sel_hi:[0,1]
	v_pk_fma_f32 v[158:159], v[146:147], v[158:159], v[150:151]
	v_pk_fma_f32 v[156:157], v[144:145], v[156:157], v[148:149]
	v_pk_fma_f32 v[154:155], v[138:139], v[154:155], v[142:143]
	v_pk_fma_f32 v[152:153], v[136:137], v[152:153], v[140:141]
.LBB0_790:
	v_pk_mul_f32 v[156:157], v[156:157], s[46:47] op_sel_hi:[1,0]
	v_pk_mul_f32 v[154:155], v[154:155], s[46:47] op_sel_hi:[1,0]
	v_pk_fma_f32 v[156:157], v[132:133], v[100:101], v[156:157]
	v_pk_mul_f32 v[152:153], v[152:153], s[46:47] op_sel_hi:[1,0]
	v_pk_mul_f32 v[158:159], v[158:159], s[46:47] op_sel_hi:[1,0]
	v_pk_fma_f32 v[160:161], v[130:131], v[38:39], v[154:155]
	v_pk_fma_f32 v[154:155], v[128:129], v[36:37], v[152:153]
	v_cvt_pk_bf16_f32 v152, v156, v157
	v_lshl_add_u64 v[156:157], v[180:181], 0, s[6:7]
	v_pk_fma_f32 v[158:159], v[134:135], v[102:103], v[158:159]
	v_lshlrev_b64 v[156:157], 11, v[156:157]
	v_cvt_pk_bf16_f32 v153, v158, v159
	v_cvt_pk_bf16_f32 v154, v154, v155
	v_cvt_pk_bf16_f32 v155, v160, v161
	v_lshl_add_u64 v[156:157], v[172:173], 0, v[156:157]
	global_store_dwordx4 v[156:157], v[152:155], off nt
	v_mov_b32_e32 v215, 1.0
	v_mov_b32_e32 v214, 0
	v_lshl_add_u64 v[152:153], v[168:169], 0, s[38:39]
	v_lshlrev_b64 v[154:155], 11, v[152:153]
	v_lshl_add_u64 v[154:155], v[172:173], 0, v[154:155]
	global_load_dwordx4 v[164:167], v[154:155], off
	s_and_b64 vcc, exec, s[4:5]
	v_mov_b32_e32 v216, 0
	v_mov_b32_e32 v217, 1.0
	s_cbranch_vccnz .LBB0_792
	v_readlane_b32 s46, v254, 47
	v_readlane_b32 s47, v254, 48
	s_nop 1
	v_lshl_add_u64 v[154:155], v[152:153], 3, s[46:47]
	global_load_dwordx2 v[216:217], v[154:155], off

.LBB0_800:
	s_mov_b32 s46, 0x3fb504f3
	v_pk_mul_f32 v[216:217], v[220:221], s[46:47] op_sel_hi:[1,0]
	v_pk_mul_f32 v[166:167], v[166:167], s[46:47] op_sel_hi:[1,0]
	v_pk_fma_f32 v[216:217], v[134:135], v[94:95], v[216:217]
	v_pk_mul_f32 v[164:165], v[164:165], s[46:47] op_sel_hi:[1,0]
	v_pk_mul_f32 v[218:219], v[218:219], s[46:47] op_sel_hi:[1,0]
	v_pk_fma_f32 v[220:221], v[130:131], v[30:31], v[166:167]
	v_pk_fma_f32 v[166:167], v[128:129], v[28:29], v[164:165]
	v_cvt_pk_bf16_f32 v165, v216, v217
	v_lshl_add_u64 v[216:217], v[178:179], 0, s[6:7]
	v_pk_fma_f32 v[218:219], v[132:133], v[92:93], v[218:219]
	v_lshlrev_b64 v[216:217], 11, v[216:217]
	v_cvt_pk_bf16_f32 v164, v218, v219
	v_cvt_pk_bf16_f32 v166, v166, v167
	v_cvt_pk_bf16_f32 v167, v220, v221
	v_lshl_add_u64 v[216:217], v[172:173], 0, v[216:217]
	global_store_dwordx4 v[216:217], v[164:167], off nt
	s_and_b64 vcc, exec, s[4:5]
	s_waitcnt vmcnt(3)
	v_lshlrev_b32_e32 v164, 16, v160
	v_and_b32_e32 v165, 0xffff0000, v160
	v_lshlrev_b32_e32 v166, 16, v161
	v_and_b32_e32 v167, 0xffff0000, v161
	v_lshlrev_b32_e32 v160, 16, v162
	v_and_b32_e32 v161, 0xffff0000, v162
	v_lshlrev_b32_e32 v162, 16, v163
	v_and_b32_e32 v163, 0xffff0000, v163
	s_cbranch_vccnz .LBB0_802
	v_sub_f32_e32 v167, v167, v214
	v_sub_f32_e32 v166, v166, v214
	v_sub_f32_e32 v165, v165, v214
	v_sub_f32_e32 v164, v164, v214
	v_mov_b32_e32 v216, v215
	v_sub_f32_e32 v163, v163, v214
	v_sub_f32_e32 v162, v162, v214
	v_sub_f32_e32 v161, v161, v214
	v_sub_f32_e32 v160, v160, v214
	v_pk_mul_f32 v[164:165], v[216:217], v[164:165] op_sel_hi:[0,1]
	v_pk_mul_f32 v[166:167], v[216:217], v[166:167] op_sel_hi:[0,1]
	v_pk_mul_f32 v[160:161], v[216:217], v[160:161] op_sel_hi:[0,1]
	v_pk_mul_f32 v[162:163], v[216:217], v[162:163] op_sel_hi:[0,1]
	v_pk_fma_f32 v[166:167], v[146:147], v[166:167], v[150:151]
	v_pk_fma_f32 v[164:165], v[144:145], v[164:165], v[148:149]
	v_pk_fma_f32 v[162:163], v[138:139], v[162:163], v[142:143]
	v_pk_fma_f32 v[160:161], v[136:137], v[160:161], v[140:141]
.LBB0_802:
	v_pk_mul_f32 v[164:165], v[164:165], s[46:47] op_sel_hi:[1,0]
	v_pk_mul_f32 v[162:163], v[162:163], s[46:47] op_sel_hi:[1,0]
	v_pk_fma_f32 v[164:165], v[132:133], v[84:85], v[164:165]
	v_pk_mul_f32 v[160:161], v[160:161], s[46:47] op_sel_hi:[1,0]
	v_ashrrev_i32_e32 v177, 31, v176
	v_pk_mul_f32 v[166:167], v[166:167], s[46:47] op_sel_hi:[1,0]
	v_pk_fma_f32 v[214:215], v[130:131], v[22:23], v[162:163]
	v_pk_fma_f32 v[162:163], v[128:129], v[20:21], v[160:161]
	v_cvt_pk_bf16_f32 v160, v164, v165
	v_lshl_add_u64 v[164:165], v[176:177], 0, s[6:7]
	v_pk_fma_f32 v[166:167], v[134:135], v[86:87], v[166:167]
	v_lshlrev_b64 v[164:165], 11, v[164:165]
	v_cvt_pk_bf16_f32 v161, v166, v167
	v_cvt_pk_bf16_f32 v162, v162, v163
	v_cvt_pk_bf16_f32 v163, v214, v215
	v_lshl_add_u64 v[164:165], v[172:173], 0, v[164:165]
	global_store_dwordx4 v[164:165], v[160:163], off nt
	s_and_b64 vcc, exec, s[4:5]
	s_waitcnt vmcnt(3)
	v_lshlrev_b32_e32 v160, 16, v156
	v_and_b32_e32 v161, 0xffff0000, v156
	v_lshlrev_b32_e32 v162, 16, v157
	v_and_b32_e32 v163, 0xffff0000, v157
	v_lshlrev_b32_e32 v156, 16, v158
	v_and_b32_e32 v157, 0xffff0000, v158
	v_lshlrev_b32_e32 v158, 16, v159
	v_and_b32_e32 v159, 0xffff0000, v159
	s_cbranch_vccnz .LBB0_804
	v_sub_f32_e32 v163, v163, v170
	v_sub_f32_e32 v162, v162, v170
	v_sub_f32_e32 v161, v161, v170
	v_sub_f32_e32 v160, v160, v170
	v_mov_b32_e32 v164, v171
	v_sub_f32_e32 v159, v159, v170
	v_sub_f32_e32 v158, v158, v170
	v_sub_f32_e32 v157, v157, v170
	v_sub_f32_e32 v156, v156, v170
	v_pk_mul_f32 v[160:161], v[164:165], v[160:161] op_sel_hi:[0,1]
	v_pk_mul_f32 v[162:163], v[164:165], v[162:163] op_sel_hi:[0,1]
	v_pk_mul_f32 v[156:157], v[164:165], v[156:157] op_sel_hi:[0,1]
	v_pk_mul_f32 v[158:159], v[164:165], v[158:159] op_sel_hi:[0,1]
	v_pk_fma_f32 v[162:163], v[146:147], v[162:163], v[150:151]
	v_pk_fma_f32 v[160:161], v[144:145], v[160:161], v[148:149]
	v_pk_fma_f32 v[158:159], v[138:139], v[158:159], v[142:143]
	v_pk_fma_f32 v[156:157], v[136:137], v[156:157], v[140:141]
.LBB0_804:
	v_pk_mul_f32 v[160:161], v[160:161], s[46:47] op_sel_hi:[1,0]
	v_pk_mul_f32 v[158:159], v[158:159], s[46:47] op_sel_hi:[1,0]
	v_pk_fma_f32 v[160:161], v[132:133], v[76:77], v[160:161]
	v_pk_mul_f32 v[156:157], v[156:157], s[46:47] op_sel_hi:[1,0]
	v_ashrrev_i32_e32 v175, 31, v174
	v_pk_mul_f32 v[162:163], v[162:163], s[46:47] op_sel_hi:[1,0]
	v_pk_fma_f32 v[164:165], v[130:131], v[14:15], v[158:159]
	v_pk_fma_f32 v[158:159], v[128:129], v[12:13], v[156:157]
	v_cvt_pk_bf16_f32 v156, v160, v161
	v_lshl_add_u64 v[160:161], v[174:175], 0, s[6:7]
	v_pk_fma_f32 v[162:163], v[134:135], v[78:79], v[162:163]
	v_lshlrev_b64 v[160:161], 11, v[160:161]
	v_cvt_pk_bf16_f32 v157, v162, v163
	v_cvt_pk_bf16_f32 v158, v158, v159
	v_cvt_pk_bf16_f32 v159, v164, v165
	v_lshl_add_u64 v[160:161], v[172:173], 0, v[160:161]
	global_store_dwordx4 v[160:161], v[156:159], off nt
	s_and_b64 vcc, exec, s[4:5]
	s_waitcnt vmcnt(3)
	v_lshlrev_b32_e32 v156, 16, v152
	v_and_b32_e32 v157, 0xffff0000, v152
	v_lshlrev_b32_e32 v158, 16, v153
	v_and_b32_e32 v159, 0xffff0000, v153
	v_lshlrev_b32_e32 v152, 16, v154
	v_and_b32_e32 v153, 0xffff0000, v154
	v_lshlrev_b32_e32 v154, 16, v155
	v_and_b32_e32 v155, 0xffff0000, v155
	s_cbranch_vccnz .LBB0_806
	v_sub_f32_e32 v159, v159, v168
	v_sub_f32_e32 v158, v158, v168
	v_sub_f32_e32 v157, v157, v168
	v_sub_f32_e32 v156, v156, v168
	v_mov_b32_e32 v160, v169
	v_pk_mul_f32 v[156:157], v[160:161], v[156:157] op_sel_hi:[0,1]
	v_pk_mul_f32 v[158:159], v[160:161], v[158:159] op_sel_hi:[0,1]
	v_pk_fma_f32 v[158:159], v[146:147], v[158:159], v[150:151]
	v_pk_fma_f32 v[156:157], v[144:145], v[156:157], v[148:149]
	v_sub_f32_e32 v145, v155, v168
	v_sub_f32_e32 v144, v154, v168
	v_sub_f32_e32 v147, v153, v168
	v_sub_f32_e32 v146, v152, v168
	v_pk_mul_f32 v[146:147], v[160:161], v[146:147] op_sel_hi:[0,1]
	v_pk_mul_f32 v[144:145], v[160:161], v[144:145] op_sel_hi:[0,1]
	v_pk_fma_f32 v[154:155], v[138:139], v[144:145], v[142:143]
	v_pk_fma_f32 v[152:153], v[136:137], v[146:147], v[140:141]
.LBB0_806:
	s_mov_b32 s46, 0x3fb504f3
	s_waitcnt vmcnt(0)
	v_pk_mul_f32 v[136:137], v[158:159], s[46:47] op_sel_hi:[1,0]
	v_pk_mul_f32 v[138:139], v[156:157], s[46:47] op_sel_hi:[1,0]
	v_pk_fma_f32 v[134:135], v[134:135], v[70:71], v[136:137]
	v_add_u32_e32 v136, 0xb0, v186
	v_pk_fma_f32 v[132:133], v[132:133], v[68:69], v[138:139]
	v_pk_mul_f32 v[138:139], v[154:155], s[46:47] op_sel_hi:[1,0]
	v_pk_mul_f32 v[140:141], v[152:153], s[46:47] op_sel_hi:[1,0]
	v_ashrrev_i32_e32 v137, 31, v136
	v_pk_fma_f32 v[138:139], v[130:131], v[6:7], v[138:139]
	v_pk_fma_f32 v[130:131], v[128:129], v[4:5], v[140:141]
	v_cvt_pk_bf16_f32 v128, v132, v133
	v_lshl_add_u64 v[132:133], s[6:7], 0, v[136:137]
	v_lshlrev_b64 v[132:133], 11, v[132:133]
	v_cvt_pk_bf16_f32 v129, v134, v135
	v_cvt_pk_bf16_f32 v130, v130, v131
	v_cvt_pk_bf16_f32 v131, v138, v139
	v_lshl_add_u64 v[168:169], v[172:173], 0, v[132:133]
	global_store_dwordx4 v[168:169], v[128:131], off nt
	global_load_dwordx4 v[128:131], v[210:211], off offset:528
	s_nop 0
	global_load_dwordx4 v[132:135], v[210:211], off offset:512
	s_and_b64 vcc, exec, s[4:5]
	s_cbranch_vccnz .LBB0_809
	global_load_dwordx4 v[136:139], v[212:213], off offset:528
	global_load_dwordx4 v[144:147], v[212:213], off offset:512
	global_load_dwordx4 v[140:143], v[208:209], off offset:528
	global_load_dwordx4 v[148:151], v[208:209], off offset:512
	s_andn2_b64 vcc, exec, s[94:95]
	s_cbranch_vccz .LBB0_810

.LBB0_810:
	global_load_dwordx4 v[208:211], v[190:191], off offset:512
	global_load_dwordx4 v[212:215], v[190:191], off offset:528
	v_add_co_u32_e32 v154, vcc, 0x10000, v190
	s_mov_b64 s[46:47], 0x10200
	s_nop 0
	v_addc_co_u32_e32 v155, vcc, 0, v191, vcc
	v_lshl_add_u64 v[152:153], v[190:191], 0, s[46:47]
	global_load_dwordx4 v[216:219], v[154:155], off offset:512
	global_load_dwordx4 v[220:223], v[152:153], off offset:16
	s_mov_b64 s[46:47], 0x20200
	v_lshl_add_u64 v[152:153], v[190:191], 0, s[46:47]
	s_mov_b32 s46, 0x20000
	v_add_co_u32_e32 v154, vcc, s46, v190
	s_mov_b64 s[46:47], 0x30200
	s_nop 0
	v_addc_co_u32_e32 v155, vcc, 0, v191, vcc
	global_load_dwordx4 v[160:163], v[154:155], off offset:512
	global_load_dwordx4 v[164:167], v[152:153], off offset:16
	v_lshl_add_u64 v[156:157], v[190:191], 0, s[46:47]
	s_mov_b32 s46, 0x30000
	v_add_co_u32_e32 v152, vcc, s46, v190
	s_mov_b32 s94, 0x3fb504f3
	s_nop 0
	v_addc_co_u32_e32 v153, vcc, 0, v191, vcc
	global_load_dwordx4 v[152:155], v[152:153], off offset:512
	s_nop 0
	global_load_dwordx4 v[156:159], v[156:157], off offset:16
	s_mov_b64 s[46:47], 0x80200
	v_ashrrev_i32_e32 v177, 31, v176
	v_ashrrev_i32_e32 v175, 31, v174
	s_waitcnt vmcnt(7)
	v_pk_fma_f32 v[170:171], v[146:147], v[210:211], v[150:151]
	v_pk_fma_f32 v[232:233], v[144:145], v[208:209], v[148:149]
	v_cndmask_b32_e64 v171, v171, v211, s[40:41]
	v_cndmask_b32_e64 v170, v170, v210, s[40:41]
	v_cndmask_b32_e64 v209, v233, v209, s[40:41]
	v_cndmask_b32_e64 v208, v232, v208, s[40:41]
	s_waitcnt vmcnt(6)
	v_pk_fma_f32 v[234:235], v[138:139], v[214:215], v[142:143]
	v_pk_fma_f32 v[236:237], v[136:137], v[212:213], v[140:141]
	v_pk_mul_f32 v[208:209], v[208:209], s[94:95] op_sel_hi:[1,0]
	v_pk_mul_f32 v[170:171], v[170:171], s[94:95] op_sel_hi:[1,0]
	v_cndmask_b32_e64 v215, v235, v215, s[40:41]
	v_cndmask_b32_e64 v214, v234, v214, s[40:41]
	v_cndmask_b32_e64 v213, v237, v213, s[40:41]
	v_cndmask_b32_e64 v212, v236, v212, s[40:41]
	v_pk_fma_f32 v[170:171], v[134:135], v[122:123], v[170:171]
	v_pk_fma_f32 v[208:209], v[132:133], v[120:121], v[208:209]
	v_pk_mul_f32 v[210:211], v[212:213], s[94:95] op_sel_hi:[1,0]
	v_pk_mul_f32 v[212:213], v[214:215], s[94:95] op_sel_hi:[1,0]
	v_cvt_pk_bf16_f32 v208, v208, v209
	v_cvt_pk_bf16_f32 v209, v170, v171
	v_lshl_add_u64 v[170:171], s[6:7], 0, v[186:187]
	v_pk_fma_f32 v[212:213], v[130:131], v[58:59], v[212:213]
	v_pk_fma_f32 v[210:211], v[128:129], v[56:57], v[210:211]
	v_lshlrev_b64 v[170:171], 11, v[170:171]
	v_cvt_pk_bf16_f32 v210, v210, v211
	v_cvt_pk_bf16_f32 v211, v212, v213
	v_lshl_add_u64 v[170:171], v[172:173], 0, v[170:171]
	global_store_dwordx4 v[170:171], v[208:211], off offset:256 nt
	s_waitcnt vmcnt(6)
	v_pk_fma_f32 v[170:171], v[146:147], v[218:219], v[150:151]
	s_waitcnt vmcnt(5)
	v_pk_fma_f32 v[212:213], v[136:137], v[220:221], v[140:141]
	v_pk_fma_f32 v[208:209], v[144:145], v[216:217], v[148:149]
	v_cndmask_b32_e64 v171, v171, v219, s[40:41]
	v_cndmask_b32_e64 v170, v170, v218, s[40:41]
	v_cndmask_b32_e64 v209, v209, v217, s[40:41]
	v_cndmask_b32_e64 v208, v208, v216, s[40:41]
	v_pk_fma_f32 v[210:211], v[138:139], v[222:223], v[142:143]
	v_pk_mul_f32 v[208:209], v[208:209], s[94:95] op_sel_hi:[1,0]
	v_pk_mul_f32 v[170:171], v[170:171], s[94:95] op_sel_hi:[1,0]
	v_cndmask_b32_e64 v211, v211, v223, s[40:41]
	v_cndmask_b32_e64 v210, v210, v222, s[40:41]
	v_cndmask_b32_e64 v213, v213, v221, s[40:41]
	v_cndmask_b32_e64 v212, v212, v220, s[40:41]
	v_pk_fma_f32 v[170:171], v[134:135], v[114:115], v[170:171]
	v_pk_fma_f32 v[208:209], v[132:133], v[112:113], v[208:209]
	v_pk_mul_f32 v[212:213], v[212:213], s[94:95] op_sel_hi:[1,0]
	v_pk_mul_f32 v[210:211], v[210:211], s[94:95] op_sel_hi:[1,0]
	v_cvt_pk_bf16_f32 v208, v208, v209
	v_cvt_pk_bf16_f32 v209, v170, v171
	v_lshl_add_u64 v[170:171], s[6:7], 0, v[184:185]
	v_pk_fma_f32 v[214:215], v[130:131], v[50:51], v[210:211]
	v_pk_fma_f32 v[210:211], v[128:129], v[48:49], v[212:213]
	v_lshlrev_b64 v[170:171], 11, v[170:171]
	v_cvt_pk_bf16_f32 v210, v210, v211
	v_cvt_pk_bf16_f32 v211, v214, v215
	v_lshl_add_u64 v[170:171], v[172:173], 0, v[170:171]
	global_store_dwordx4 v[170:171], v[208:211], off offset:256 nt
	s_waitcnt vmcnt(5)
	v_pk_fma_f32 v[170:171], v[146:147], v[162:163], v[150:151]
	s_waitcnt vmcnt(4)
	v_pk_fma_f32 v[212:213], v[136:137], v[164:165], v[140:141]
	v_pk_fma_f32 v[208:209], v[144:145], v[160:161], v[148:149]
	v_cndmask_b32_e64 v165, v213, v165, s[40:41]
	v_cndmask_b32_e64 v164, v212, v164, s[40:41]
	v_cndmask_b32_e64 v163, v171, v163, s[40:41]
	v_cndmask_b32_e64 v162, v170, v162, s[40:41]
	v_cndmask_b32_e64 v161, v209, v161, s[40:41]
	v_cndmask_b32_e64 v160, v208, v160, s[40:41]
	v_pk_fma_f32 v[210:211], v[138:139], v[166:167], v[142:143]
	v_pk_mul_f32 v[160:161], v[160:161], s[94:95] op_sel_hi:[1,0]
	v_pk_mul_f32 v[162:163], v[162:163], s[94:95] op_sel_hi:[1,0]
	v_pk_mul_f32 v[164:165], v[164:165], s[94:95] op_sel_hi:[1,0]
	v_cndmask_b32_e64 v167, v211, v167, s[40:41]
	v_cndmask_b32_e64 v166, v210, v166, s[40:41]
	v_pk_fma_f32 v[162:163], v[134:135], v[106:107], v[162:163]
	v_pk_fma_f32 v[160:161], v[132:133], v[104:105], v[160:161]
	v_pk_fma_f32 v[164:165], v[128:129], v[40:41], v[164:165]
	v_pk_mul_f32 v[166:167], v[166:167], s[94:95] op_sel_hi:[1,0]
	v_cvt_pk_bf16_f32 v160, v160, v161
	v_cvt_pk_bf16_f32 v161, v162, v163
	v_cvt_pk_bf16_f32 v162, v164, v165
	v_lshl_add_u64 v[164:165], s[6:7], 0, v[182:183]
	v_pk_fma_f32 v[166:167], v[130:131], v[42:43], v[166:167]
	v_lshlrev_b64 v[164:165], 11, v[164:165]
	v_cvt_pk_bf16_f32 v163, v166, v167
	v_lshl_add_u64 v[164:165], v[172:173], 0, v[164:165]
	global_store_dwordx4 v[164:165], v[160:163], off offset:256 nt
	s_waitcnt vmcnt(3)
	v_pk_fma_f32 v[166:167], v[136:137], v[156:157], v[140:141]
	v_pk_fma_f32 v[164:165], v[138:139], v[158:159], v[142:143]
	v_pk_fma_f32 v[160:161], v[146:147], v[154:155], v[150:151]
	v_pk_fma_f32 v[162:163], v[144:145], v[152:153], v[148:149]
	v_cndmask_b32_e64 v157, v167, v157, s[40:41]
	v_cndmask_b32_e64 v156, v166, v156, s[40:41]
	v_cndmask_b32_e64 v155, v161, v155, s[40:41]
	v_cndmask_b32_e64 v154, v160, v154, s[40:41]
	v_cndmask_b32_e64 v153, v163, v153, s[40:41]
	v_cndmask_b32_e64 v152, v162, v152, s[40:41]
	v_pk_mul_f32 v[152:153], v[152:153], s[94:95] op_sel_hi:[1,0]
	v_pk_mul_f32 v[154:155], v[154:155], s[94:95] op_sel_hi:[1,0]
	v_pk_mul_f32 v[156:157], v[156:157], s[94:95] op_sel_hi:[1,0]
	v_cndmask_b32_e64 v159, v165, v159, s[40:41]
	v_cndmask_b32_e64 v158, v164, v158, s[40:41]
	v_pk_fma_f32 v[154:155], v[134:135], v[98:99], v[154:155]
	v_pk_fma_f32 v[152:153], v[132:133], v[96:97], v[152:153]
	v_pk_fma_f32 v[156:157], v[128:129], v[32:33], v[156:157]
	v_pk_mul_f32 v[158:159], v[158:159], s[94:95] op_sel_hi:[1,0]
	v_cvt_pk_bf16_f32 v152, v152, v153
	v_cvt_pk_bf16_f32 v153, v154, v155
	v_cvt_pk_bf16_f32 v154, v156, v157
	v_lshl_add_u64 v[156:157], s[6:7], 0, v[180:181]
	v_pk_fma_f32 v[158:159], v[130:131], v[34:35], v[158:159]
	v_lshlrev_b64 v[156:157], 11, v[156:157]
	v_cvt_pk_bf16_f32 v155, v158, v159
	v_lshl_add_u64 v[156:157], v[172:173], 0, v[156:157]
	global_store_dwordx4 v[156:157], v[152:155], off offset:256 nt
	v_lshl_add_u64 v[156:157], v[190:191], 0, s[46:47]
	s_mov_b32 s46, 0x80000
	v_add_co_u32_e32 v152, vcc, s46, v190
	s_mov_b64 s[46:47], 0x90200
	s_nop 0
	v_addc_co_u32_e32 v153, vcc, 0, v191, vcc
	global_load_dwordx4 v[152:155], v[152:153], off offset:512
	s_nop 0
	global_load_dwordx4 v[156:159], v[156:157], off offset:16
	v_lshl_add_u64 v[164:165], v[190:191], 0, s[46:47]
	s_mov_b32 s46, 0x90000
	v_add_co_u32_e32 v160, vcc, s46, v190
	s_mov_b64 s[46:47], 0xa0200
	s_nop 0
	v_addc_co_u32_e32 v161, vcc, 0, v191, vcc
	global_load_dwordx4 v[160:163], v[160:161], off offset:512
	s_nop 0
	global_load_dwordx4 v[164:167], v[164:165], off offset:16
	v_lshl_add_u64 v[170:171], v[190:191], 0, s[46:47]
	s_mov_b32 s46, 0xa0000
	v_add_co_u32_e32 v208, vcc, s46, v190
	s_mov_b64 s[46:47], 0xb0200
	s_nop 0
	v_addc_co_u32_e32 v209, vcc, 0, v191, vcc
	global_load_dwordx4 v[208:211], v[208:209], off offset:512
	s_nop 0
	global_load_dwordx4 v[212:215], v[170:171], off offset:16
	v_lshl_add_u64 v[170:171], v[190:191], 0, s[46:47]
	s_mov_b32 s46, 0xb0000
	v_add_co_u32_e32 v190, vcc, s46, v190
	s_nop 1
	v_addc_co_u32_e32 v191, vcc, 0, v191, vcc
	global_load_dwordx4 v[216:219], v[190:191], off offset:512
	global_load_dwordx4 v[220:223], v[170:171], off offset:16
	s_waitcnt vmcnt(7)
	v_pk_fma_f32 v[170:171], v[146:147], v[154:155], v[150:151]
	v_pk_fma_f32 v[190:191], v[144:145], v[152:153], v[148:149]
	s_waitcnt vmcnt(6)
	v_pk_fma_f32 v[234:235], v[136:137], v[156:157], v[140:141]
	v_cndmask_b32_e64 v155, v171, v155, s[40:41]
	v_cndmask_b32_e64 v157, v235, v157, s[40:41]
	v_cndmask_b32_e64 v156, v234, v156, s[40:41]
	v_cndmask_b32_e64 v154, v170, v154, s[40:41]
	v_cndmask_b32_e64 v153, v191, v153, s[40:41]
	v_cndmask_b32_e64 v152, v190, v152, s[40:41]
	v_pk_fma_f32 v[232:233], v[138:139], v[158:159], v[142:143]
	v_pk_mul_f32 v[152:153], v[152:153], s[94:95] op_sel_hi:[1,0]
	v_pk_mul_f32 v[154:155], v[154:155], s[94:95] op_sel_hi:[1,0]
	v_pk_mul_f32 v[156:157], v[156:157], s[94:95] op_sel_hi:[1,0]
	v_cndmask_b32_e64 v159, v233, v159, s[40:41]
	v_cndmask_b32_e64 v158, v232, v158, s[40:41]
	v_pk_fma_f32 v[154:155], v[134:135], v[90:91], v[154:155]
	v_pk_fma_f32 v[152:153], v[132:133], v[88:89], v[152:153]
	v_pk_fma_f32 v[156:157], v[128:129], v[24:25], v[156:157]
	v_pk_mul_f32 v[158:159], v[158:159], s[94:95] op_sel_hi:[1,0]
	v_cvt_pk_bf16_f32 v152, v152, v153
	v_cvt_pk_bf16_f32 v153, v154, v155
	v_cvt_pk_bf16_f32 v154, v156, v157
	v_lshl_add_u64 v[156:157], s[6:7], 0, v[178:179]
	v_pk_fma_f32 v[158:159], v[130:131], v[26:27], v[158:159]
	v_lshlrev_b64 v[156:157], 11, v[156:157]
	v_cvt_pk_bf16_f32 v155, v158, v159
	v_lshl_add_u64 v[156:157], v[172:173], 0, v[156:157]
	global_store_dwordx4 v[156:157], v[152:155], off offset:256 nt
	s_waitcnt vmcnt(5)
	v_pk_fma_f32 v[156:157], v[138:139], v[166:167], v[142:143]
	v_pk_fma_f32 v[158:159], v[136:137], v[164:165], v[140:141]
	v_pk_fma_f32 v[152:153], v[146:147], v[162:163], v[150:151]
	v_pk_fma_f32 v[154:155], v[144:145], v[160:161], v[148:149]
	v_cndmask_b32_e64 v153, v153, v163, s[40:41]
	v_cndmask_b32_e64 v152, v152, v162, s[40:41]
	v_cndmask_b32_e64 v155, v155, v161, s[40:41]
	v_cndmask_b32_e64 v154, v154, v160, s[40:41]
	v_cndmask_b32_e64 v157, v157, v167, s[40:41]
	v_cndmask_b32_e64 v156, v156, v166, s[40:41]
	v_cndmask_b32_e64 v159, v159, v165, s[40:41]
	v_cndmask_b32_e64 v158, v158, v164, s[40:41]
	v_pk_mul_f32 v[154:155], v[154:155], s[94:95] op_sel_hi:[1,0]
	v_pk_mul_f32 v[152:153], v[152:153], s[94:95] op_sel_hi:[1,0]
	v_pk_mul_f32 v[156:157], v[156:157], s[94:95] op_sel_hi:[1,0]
	v_pk_fma_f32 v[160:161], v[134:135], v[82:83], v[152:153]
	v_pk_fma_f32 v[152:153], v[132:133], v[80:81], v[154:155]
	v_pk_mul_f32 v[154:155], v[158:159], s[94:95] op_sel_hi:[1,0]
	v_pk_fma_f32 v[156:157], v[130:131], v[18:19], v[156:157]
	v_pk_fma_f32 v[154:155], v[128:129], v[16:17], v[154:155]
	v_cvt_pk_bf16_f32 v152, v152, v153
	v_cvt_pk_bf16_f32 v154, v154, v155
	v_cvt_pk_bf16_f32 v155, v156, v157
	v_lshl_add_u64 v[156:157], s[6:7], 0, v[176:177]
	v_lshlrev_b64 v[156:157], 11, v[156:157]
	v_cvt_pk_bf16_f32 v153, v160, v161
	v_lshl_add_u64 v[156:157], v[172:173], 0, v[156:157]
	global_store_dwordx4 v[156:157], v[152:155], off offset:256 nt
	s_waitcnt vmcnt(4)
	v_pk_fma_f32 v[156:157], v[138:139], v[214:215], v[142:143]
	v_pk_fma_f32 v[158:159], v[136:137], v[212:213], v[140:141]
	v_pk_fma_f32 v[152:153], v[146:147], v[210:211], v[150:151]
	v_pk_fma_f32 v[154:155], v[144:145], v[208:209], v[148:149]
	v_cndmask_b32_e64 v153, v153, v211, s[40:41]
	v_cndmask_b32_e64 v152, v152, v210, s[40:41]
	v_cndmask_b32_e64 v155, v155, v209, s[40:41]
	v_cndmask_b32_e64 v154, v154, v208, s[40:41]
	v_cndmask_b32_e64 v157, v157, v215, s[40:41]
	v_cndmask_b32_e64 v156, v156, v214, s[40:41]
	v_cndmask_b32_e64 v159, v159, v213, s[40:41]
	v_cndmask_b32_e64 v158, v158, v212, s[40:41]
	v_pk_mul_f32 v[154:155], v[154:155], s[94:95] op_sel_hi:[1,0]
	v_pk_mul_f32 v[152:153], v[152:153], s[94:95] op_sel_hi:[1,0]
	v_pk_mul_f32 v[156:157], v[156:157], s[94:95] op_sel_hi:[1,0]
	v_pk_fma_f32 v[160:161], v[134:135], v[74:75], v[152:153]
	v_pk_fma_f32 v[152:153], v[132:133], v[72:73], v[154:155]
	v_pk_mul_f32 v[154:155], v[158:159], s[94:95] op_sel_hi:[1,0]
	v_pk_fma_f32 v[156:157], v[130:131], v[10:11], v[156:157]
	v_pk_fma_f32 v[154:155], v[128:129], v[8:9], v[154:155]
	v_cvt_pk_bf16_f32 v152, v152, v153
	v_cvt_pk_bf16_f32 v154, v154, v155
	v_cvt_pk_bf16_f32 v155, v156, v157
	v_lshl_add_u64 v[156:157], s[6:7], 0, v[174:175]
	v_lshlrev_b64 v[156:157], 11, v[156:157]
	v_cvt_pk_bf16_f32 v153, v160, v161
	v_lshl_add_u64 v[156:157], v[172:173], 0, v[156:157]
	global_store_dwordx4 v[156:157], v[152:155], off offset:256 nt
	s_waitcnt vmcnt(4)
	v_pk_fma_f32 v[158:159], v[146:147], v[218:219], v[150:151]
	v_pk_fma_f32 v[156:157], v[144:145], v[216:217], v[148:149]
	s_waitcnt vmcnt(3)
	v_pk_fma_f32 v[154:155], v[138:139], v[222:223], v[142:143]
	v_pk_fma_f32 v[152:153], v[136:137], v[220:221], v[140:141]
	v_cndmask_b32_e64 v155, v155, v223, s[40:41]
	v_cndmask_b32_e64 v153, v153, v221, s[40:41]
	v_cndmask_b32_e64 v152, v152, v220, s[40:41]
	v_cndmask_b32_e64 v154, v154, v222, s[40:41]
	v_cndmask_b32_e64 v157, v157, v217, s[40:41]
	v_cndmask_b32_e64 v156, v156, v216, s[40:41]
	v_cndmask_b32_e64 v159, v159, v219, s[40:41]
	v_cndmask_b32_e64 v158, v158, v218, s[40:41]
	s_cbranch_execnz .LBB0_843

.LBB0_821:
	s_mov_b32 s46, 0x3fb504f3
	v_pk_mul_f32 v[210:211], v[214:215], s[46:47] op_sel_hi:[1,0]
	v_pk_mul_f32 v[212:213], v[212:213], s[46:47] op_sel_hi:[1,0]
	v_pk_mul_f32 v[166:167], v[166:167], s[46:47] op_sel_hi:[1,0]
	v_pk_mul_f32 v[164:165], v[164:165], s[46:47] op_sel_hi:[1,0]
	v_lshl_add_u64 v[186:187], s[6:7], 0, v[186:187]
	v_pk_fma_f32 v[210:211], v[134:135], v[122:123], v[210:211]
	v_pk_fma_f32 v[212:213], v[132:133], v[120:121], v[212:213]
	v_pk_fma_f32 v[214:215], v[130:131], v[58:59], v[166:167]
	v_pk_fma_f32 v[166:167], v[128:129], v[56:57], v[164:165]
	v_lshlrev_b64 v[186:187], 11, v[186:187]
	v_cvt_pk_bf16_f32 v164, v212, v213
	v_cvt_pk_bf16_f32 v165, v210, v211
	v_cvt_pk_bf16_f32 v166, v166, v167
	v_cvt_pk_bf16_f32 v167, v214, v215
	v_lshl_add_u64 v[186:187], v[172:173], 0, v[186:187]
	global_store_dwordx4 v[186:187], v[164:167], off offset:256 nt
	s_and_b64 vcc, exec, s[4:5]
	s_waitcnt vmcnt(3)
	v_lshlrev_b32_e32 v164, 16, v160
	v_and_b32_e32 v165, 0xffff0000, v160
	v_lshlrev_b32_e32 v166, 16, v161
	v_and_b32_e32 v167, 0xffff0000, v161
	v_lshlrev_b32_e32 v160, 16, v162
	v_and_b32_e32 v161, 0xffff0000, v162
	v_lshlrev_b32_e32 v162, 16, v163
	v_and_b32_e32 v163, 0xffff0000, v163
	s_cbranch_vccnz .LBB0_823
	v_sub_f32_e32 v167, v167, v208
	v_sub_f32_e32 v166, v166, v208
	v_sub_f32_e32 v165, v165, v208
	v_sub_f32_e32 v164, v164, v208
	v_mov_b32_e32 v186, v209
	v_sub_f32_e32 v163, v163, v208
	v_sub_f32_e32 v162, v162, v208
	v_sub_f32_e32 v161, v161, v208
	v_sub_f32_e32 v160, v160, v208
	v_pk_mul_f32 v[164:165], v[186:187], v[164:165] op_sel_hi:[0,1]
	v_pk_mul_f32 v[166:167], v[186:187], v[166:167] op_sel_hi:[0,1]
	v_pk_mul_f32 v[160:161], v[186:187], v[160:161] op_sel_hi:[0,1]
	v_pk_mul_f32 v[162:163], v[186:187], v[162:163] op_sel_hi:[0,1]
	v_pk_fma_f32 v[166:167], v[146:147], v[166:167], v[150:151]
	v_pk_fma_f32 v[164:165], v[144:145], v[164:165], v[148:149]
	v_pk_fma_f32 v[162:163], v[138:139], v[162:163], v[142:143]
	v_pk_fma_f32 v[160:161], v[136:137], v[160:161], v[140:141]
.LBB0_823:
	v_pk_mul_f32 v[164:165], v[164:165], s[46:47] op_sel_hi:[1,0]
	v_pk_mul_f32 v[162:163], v[162:163], s[46:47] op_sel_hi:[1,0]
	v_pk_fma_f32 v[164:165], v[132:133], v[112:113], v[164:165]
	v_pk_mul_f32 v[160:161], v[160:161], s[46:47] op_sel_hi:[1,0]
	v_pk_mul_f32 v[166:167], v[166:167], s[46:47] op_sel_hi:[1,0]
	v_pk_fma_f32 v[186:187], v[130:131], v[50:51], v[162:163]
	v_pk_fma_f32 v[162:163], v[128:129], v[48:49], v[160:161]
	v_cvt_pk_bf16_f32 v160, v164, v165
	v_lshl_add_u64 v[164:165], s[6:7], 0, v[184:185]
	v_pk_fma_f32 v[166:167], v[134:135], v[114:115], v[166:167]
	v_lshlrev_b64 v[164:165], 11, v[164:165]
	v_cvt_pk_bf16_f32 v161, v166, v167
	v_cvt_pk_bf16_f32 v162, v162, v163
	v_cvt_pk_bf16_f32 v163, v186, v187
	v_lshl_add_u64 v[164:165], v[172:173], 0, v[164:165]
	global_store_dwordx4 v[164:165], v[160:163], off offset:256 nt
	s_and_b64 vcc, exec, s[4:5]
	s_waitcnt vmcnt(3)
	v_lshlrev_b32_e32 v160, 16, v156
	v_and_b32_e32 v161, 0xffff0000, v156
	v_lshlrev_b32_e32 v162, 16, v157
	v_and_b32_e32 v163, 0xffff0000, v157
	v_lshlrev_b32_e32 v156, 16, v158
	v_and_b32_e32 v157, 0xffff0000, v158
	v_lshlrev_b32_e32 v158, 16, v159
	v_and_b32_e32 v159, 0xffff0000, v159
	s_cbranch_vccnz .LBB0_825
	v_sub_f32_e32 v163, v163, v190
	v_sub_f32_e32 v162, v162, v190
	v_sub_f32_e32 v161, v161, v190
	v_sub_f32_e32 v160, v160, v190
	v_mov_b32_e32 v164, v191
	v_sub_f32_e32 v159, v159, v190
	v_sub_f32_e32 v158, v158, v190
	v_sub_f32_e32 v157, v157, v190
	v_sub_f32_e32 v156, v156, v190
	v_pk_mul_f32 v[160:161], v[164:165], v[160:161] op_sel_hi:[0,1]
	v_pk_mul_f32 v[162:163], v[164:165], v[162:163] op_sel_hi:[0,1]
	v_pk_mul_f32 v[156:157], v[164:165], v[156:157] op_sel_hi:[0,1]
	v_pk_mul_f32 v[158:159], v[164:165], v[158:159] op_sel_hi:[0,1]
	v_pk_fma_f32 v[162:163], v[146:147], v[162:163], v[150:151]
	v_pk_fma_f32 v[160:161], v[144:145], v[160:161], v[148:149]
	v_pk_fma_f32 v[158:159], v[138:139], v[158:159], v[142:143]
	v_pk_fma_f32 v[156:157], v[136:137], v[156:157], v[140:141]
.LBB0_825:
	v_pk_mul_f32 v[160:161], v[160:161], s[46:47] op_sel_hi:[1,0]
	v_pk_mul_f32 v[158:159], v[158:159], s[46:47] op_sel_hi:[1,0]
	v_pk_fma_f32 v[160:161], v[132:133], v[104:105], v[160:161]
	v_pk_mul_f32 v[156:157], v[156:157], s[46:47] op_sel_hi:[1,0]
	v_pk_mul_f32 v[162:163], v[162:163], s[46:47] op_sel_hi:[1,0]
	v_pk_fma_f32 v[164:165], v[130:131], v[42:43], v[158:159]
	v_pk_fma_f32 v[158:159], v[128:129], v[40:41], v[156:157]
	v_cvt_pk_bf16_f32 v156, v160, v161
	v_lshl_add_u64 v[160:161], s[6:7], 0, v[182:183]
	v_pk_fma_f32 v[162:163], v[134:135], v[106:107], v[162:163]
	v_lshlrev_b64 v[160:161], 11, v[160:161]
	v_cvt_pk_bf16_f32 v157, v162, v163
	v_cvt_pk_bf16_f32 v158, v158, v159
	v_cvt_pk_bf16_f32 v159, v164, v165
	v_lshl_add_u64 v[160:161], v[172:173], 0, v[160:161]
	global_store_dwordx4 v[160:161], v[156:159], off offset:256 nt
	s_and_b64 vcc, exec, s[4:5]
	s_waitcnt vmcnt(3)
	v_lshlrev_b32_e32 v156, 16, v152
	v_and_b32_e32 v157, 0xffff0000, v152
	v_lshlrev_b32_e32 v158, 16, v153
	v_and_b32_e32 v159, 0xffff0000, v153
	v_lshlrev_b32_e32 v152, 16, v154
	v_and_b32_e32 v153, 0xffff0000, v154
	v_lshlrev_b32_e32 v154, 16, v155
	v_and_b32_e32 v155, 0xffff0000, v155
	s_cbranch_vccnz .LBB0_827
	v_sub_f32_e32 v159, v159, v188
	v_sub_f32_e32 v158, v158, v188
	v_sub_f32_e32 v157, v157, v188
	v_sub_f32_e32 v156, v156, v188
	v_mov_b32_e32 v160, v189
	v_sub_f32_e32 v155, v155, v188
	v_sub_f32_e32 v154, v154, v188
	v_sub_f32_e32 v153, v153, v188
	v_sub_f32_e32 v152, v152, v188
	v_pk_mul_f32 v[156:157], v[160:161], v[156:157] op_sel_hi:[0,1]
	v_pk_mul_f32 v[158:159], v[160:161], v[158:159] op_sel_hi:[0,1]
	v_pk_mul_f32 v[152:153], v[160:161], v[152:153] op_sel_hi:[0,1]
	v_pk_mul_f32 v[154:155], v[160:161], v[154:155] op_sel_hi:[0,1]
	v_pk_fma_f32 v[158:159], v[146:147], v[158:159], v[150:151]
	v_pk_fma_f32 v[156:157], v[144:145], v[156:157], v[148:149]
	v_pk_fma_f32 v[154:155], v[138:139], v[154:155], v[142:143]
	v_pk_fma_f32 v[152:153], v[136:137], v[152:153], v[140:141]
.LBB0_827:
	v_pk_mul_f32 v[156:157], v[156:157], s[46:47] op_sel_hi:[1,0]
	v_pk_mul_f32 v[154:155], v[154:155], s[46:47] op_sel_hi:[1,0]
	v_pk_fma_f32 v[156:157], v[132:133], v[96:97], v[156:157]
	v_pk_mul_f32 v[152:153], v[152:153], s[46:47] op_sel_hi:[1,0]
	v_pk_mul_f32 v[158:159], v[158:159], s[46:47] op_sel_hi:[1,0]
	v_pk_fma_f32 v[160:161], v[130:131], v[34:35], v[154:155]
	v_pk_fma_f32 v[154:155], v[128:129], v[32:33], v[152:153]
	v_cvt_pk_bf16_f32 v152, v156, v157
	v_lshl_add_u64 v[156:157], s[6:7], 0, v[180:181]
	v_pk_fma_f32 v[158:159], v[134:135], v[98:99], v[158:159]
	v_lshlrev_b64 v[156:157], 11, v[156:157]
	v_cvt_pk_bf16_f32 v153, v158, v159
	v_cvt_pk_bf16_f32 v154, v154, v155
	v_cvt_pk_bf16_f32 v155, v160, v161
	v_lshl_add_u64 v[156:157], v[172:173], 0, v[156:157]
	global_store_dwordx4 v[156:157], v[152:155], off offset:256 nt
	v_mov_b32_e32 v183, 1.0
	v_mov_b32_e32 v182, 0
	v_lshl_add_u64 v[152:153], v[170:171], 0, s[38:39]
	v_lshlrev_b64 v[154:155], 11, v[152:153]
	v_lshl_add_u64 v[154:155], v[172:173], 0, v[154:155]
	global_load_dwordx4 v[164:167], v[154:155], off offset:256
	s_and_b64 vcc, exec, s[4:5]
	v_mov_b32_e32 v184, 0
	v_mov_b32_e32 v185, 1.0
	s_cbranch_vccnz .LBB0_829
	v_readlane_b32 s46, v254, 47
	v_readlane_b32 s47, v254, 48
	s_nop 1
	v_lshl_add_u64 v[154:155], v[152:153], 3, s[46:47]
	global_load_dwordx2 v[184:185], v[154:155], off

.LBB0_837:
	s_mov_b32 s46, 0x3fb504f3
	v_pk_mul_f32 v[184:185], v[188:189], s[46:47] op_sel_hi:[1,0]
	v_pk_mul_f32 v[186:187], v[186:187], s[46:47] op_sel_hi:[1,0]
	v_pk_mul_f32 v[166:167], v[166:167], s[46:47] op_sel_hi:[1,0]
	v_pk_mul_f32 v[164:165], v[164:165], s[46:47] op_sel_hi:[1,0]
	v_lshl_add_u64 v[178:179], s[6:7], 0, v[178:179]
	v_pk_fma_f32 v[184:185], v[134:135], v[90:91], v[184:185]
	v_pk_fma_f32 v[186:187], v[132:133], v[88:89], v[186:187]
	v_pk_fma_f32 v[188:189], v[130:131], v[26:27], v[166:167]
	v_pk_fma_f32 v[166:167], v[128:129], v[24:25], v[164:165]
	v_lshlrev_b64 v[178:179], 11, v[178:179]
	v_cvt_pk_bf16_f32 v164, v186, v187
	v_cvt_pk_bf16_f32 v165, v184, v185
	v_cvt_pk_bf16_f32 v166, v166, v167
	v_cvt_pk_bf16_f32 v167, v188, v189
	v_lshl_add_u64 v[178:179], v[172:173], 0, v[178:179]
	global_store_dwordx4 v[178:179], v[164:167], off offset:256 nt
	s_and_b64 vcc, exec, s[4:5]
	s_waitcnt vmcnt(3)
	v_lshlrev_b32_e32 v164, 16, v160
	v_and_b32_e32 v165, 0xffff0000, v160
	v_lshlrev_b32_e32 v166, 16, v161
	v_and_b32_e32 v167, 0xffff0000, v161
	v_lshlrev_b32_e32 v160, 16, v162
	v_and_b32_e32 v161, 0xffff0000, v162
	v_lshlrev_b32_e32 v162, 16, v163
	v_and_b32_e32 v163, 0xffff0000, v163
	s_cbranch_vccnz .LBB0_839
	v_sub_f32_e32 v167, v167, v182
	v_sub_f32_e32 v166, v166, v182
	v_sub_f32_e32 v165, v165, v182
	v_sub_f32_e32 v164, v164, v182
	v_mov_b32_e32 v178, v183
	v_sub_f32_e32 v163, v163, v182
	v_sub_f32_e32 v162, v162, v182
	v_sub_f32_e32 v161, v161, v182
	v_sub_f32_e32 v160, v160, v182
	v_pk_mul_f32 v[164:165], v[178:179], v[164:165] op_sel_hi:[0,1]
	v_pk_mul_f32 v[166:167], v[178:179], v[166:167] op_sel_hi:[0,1]
	v_pk_mul_f32 v[160:161], v[178:179], v[160:161] op_sel_hi:[0,1]
	v_pk_mul_f32 v[162:163], v[178:179], v[162:163] op_sel_hi:[0,1]
	v_pk_fma_f32 v[166:167], v[146:147], v[166:167], v[150:151]
	v_pk_fma_f32 v[164:165], v[144:145], v[164:165], v[148:149]
	v_pk_fma_f32 v[162:163], v[138:139], v[162:163], v[142:143]
	v_pk_fma_f32 v[160:161], v[136:137], v[160:161], v[140:141]
.LBB0_839:
	v_pk_mul_f32 v[164:165], v[164:165], s[46:47] op_sel_hi:[1,0]
	v_pk_mul_f32 v[162:163], v[162:163], s[46:47] op_sel_hi:[1,0]
	v_pk_fma_f32 v[164:165], v[132:133], v[80:81], v[164:165]
	v_pk_mul_f32 v[160:161], v[160:161], s[46:47] op_sel_hi:[1,0]
	v_ashrrev_i32_e32 v177, 31, v176
	v_pk_mul_f32 v[166:167], v[166:167], s[46:47] op_sel_hi:[1,0]
	v_pk_fma_f32 v[178:179], v[130:131], v[18:19], v[162:163]
	v_pk_fma_f32 v[162:163], v[128:129], v[16:17], v[160:161]
	v_cvt_pk_bf16_f32 v160, v164, v165
	v_lshl_add_u64 v[164:165], s[6:7], 0, v[176:177]
	v_pk_fma_f32 v[166:167], v[134:135], v[82:83], v[166:167]
	v_lshlrev_b64 v[164:165], 11, v[164:165]
	v_cvt_pk_bf16_f32 v161, v166, v167
	v_cvt_pk_bf16_f32 v162, v162, v163
	v_cvt_pk_bf16_f32 v163, v178, v179
	v_lshl_add_u64 v[164:165], v[172:173], 0, v[164:165]
	global_store_dwordx4 v[164:165], v[160:163], off offset:256 nt
	s_and_b64 vcc, exec, s[4:5]
	s_waitcnt vmcnt(3)
	v_lshlrev_b32_e32 v160, 16, v156
	v_and_b32_e32 v161, 0xffff0000, v156
	v_lshlrev_b32_e32 v162, 16, v157
	v_and_b32_e32 v163, 0xffff0000, v157
	v_lshlrev_b32_e32 v156, 16, v158
	v_and_b32_e32 v157, 0xffff0000, v158
	v_lshlrev_b32_e32 v158, 16, v159
	v_and_b32_e32 v159, 0xffff0000, v159
	s_cbranch_vccnz .LBB0_841
	v_sub_f32_e32 v163, v163, v180
	v_sub_f32_e32 v162, v162, v180
	v_sub_f32_e32 v161, v161, v180
	v_sub_f32_e32 v160, v160, v180
	v_mov_b32_e32 v164, v181
	v_sub_f32_e32 v159, v159, v180
	v_sub_f32_e32 v158, v158, v180
	v_sub_f32_e32 v157, v157, v180
	v_sub_f32_e32 v156, v156, v180
	v_pk_mul_f32 v[160:161], v[164:165], v[160:161] op_sel_hi:[0,1]
	v_pk_mul_f32 v[162:163], v[164:165], v[162:163] op_sel_hi:[0,1]
	v_pk_mul_f32 v[156:157], v[164:165], v[156:157] op_sel_hi:[0,1]
	v_pk_mul_f32 v[158:159], v[164:165], v[158:159] op_sel_hi:[0,1]
	v_pk_fma_f32 v[162:163], v[146:147], v[162:163], v[150:151]
	v_pk_fma_f32 v[160:161], v[144:145], v[160:161], v[148:149]
	v_pk_fma_f32 v[158:159], v[138:139], v[158:159], v[142:143]
	v_pk_fma_f32 v[156:157], v[136:137], v[156:157], v[140:141]
.LBB0_841:
	v_pk_mul_f32 v[160:161], v[160:161], s[46:47] op_sel_hi:[1,0]
	v_pk_mul_f32 v[158:159], v[158:159], s[46:47] op_sel_hi:[1,0]
	v_pk_fma_f32 v[160:161], v[132:133], v[72:73], v[160:161]
	v_pk_mul_f32 v[156:157], v[156:157], s[46:47] op_sel_hi:[1,0]
	v_ashrrev_i32_e32 v175, 31, v174
	v_pk_mul_f32 v[162:163], v[162:163], s[46:47] op_sel_hi:[1,0]
	v_pk_fma_f32 v[164:165], v[130:131], v[10:11], v[158:159]
	v_pk_fma_f32 v[158:159], v[128:129], v[8:9], v[156:157]
	v_cvt_pk_bf16_f32 v156, v160, v161
	v_lshl_add_u64 v[160:161], s[6:7], 0, v[174:175]
	v_pk_fma_f32 v[162:163], v[134:135], v[74:75], v[162:163]
	v_lshlrev_b64 v[160:161], 11, v[160:161]
	v_cvt_pk_bf16_f32 v157, v162, v163
	v_cvt_pk_bf16_f32 v158, v158, v159
	v_cvt_pk_bf16_f32 v159, v164, v165
	v_lshl_add_u64 v[160:161], v[172:173], 0, v[160:161]
	global_store_dwordx4 v[160:161], v[156:159], off offset:256 nt
	s_and_b64 vcc, exec, s[4:5]
	s_waitcnt vmcnt(3)
	v_lshlrev_b32_e32 v156, 16, v152
	v_and_b32_e32 v157, 0xffff0000, v152
	v_lshlrev_b32_e32 v158, 16, v153
	v_and_b32_e32 v159, 0xffff0000, v153
	v_lshlrev_b32_e32 v152, 16, v154
	v_and_b32_e32 v153, 0xffff0000, v154
	v_lshlrev_b32_e32 v154, 16, v155
	v_and_b32_e32 v155, 0xffff0000, v155
	s_cbranch_vccnz .LBB0_843
	v_sub_f32_e32 v159, v159, v170
	v_sub_f32_e32 v158, v158, v170
	v_sub_f32_e32 v157, v157, v170
	v_sub_f32_e32 v156, v156, v170
	v_mov_b32_e32 v160, v171
	v_pk_mul_f32 v[156:157], v[160:161], v[156:157] op_sel_hi:[0,1]
	v_pk_mul_f32 v[158:159], v[160:161], v[158:159] op_sel_hi:[0,1]
	v_pk_fma_f32 v[158:159], v[146:147], v[158:159], v[150:151]
	v_pk_fma_f32 v[156:157], v[144:145], v[156:157], v[148:149]
	v_sub_f32_e32 v145, v155, v170
	v_sub_f32_e32 v144, v154, v170
	v_sub_f32_e32 v147, v153, v170
	v_sub_f32_e32 v146, v152, v170
	v_pk_mul_f32 v[146:147], v[160:161], v[146:147] op_sel_hi:[0,1]
	v_pk_mul_f32 v[144:145], v[160:161], v[144:145] op_sel_hi:[0,1]
	v_pk_fma_f32 v[154:155], v[138:139], v[144:145], v[142:143]
	v_pk_fma_f32 v[152:153], v[136:137], v[146:147], v[140:141]
.LBB0_843:
	s_mov_b32 s4, 0x3fb504f3
	s_waitcnt vmcnt(3)
	v_pk_mul_f32 v[136:137], v[158:159], s[4:5] op_sel_hi:[1,0]
	v_pk_mul_f32 v[138:139], v[156:157], s[4:5] op_sel_hi:[1,0]
	s_waitcnt vmcnt(0)
	v_pk_fma_f32 v[134:135], v[134:135], v[66:67], v[136:137]
	v_pk_fma_f32 v[132:133], v[132:133], v[64:65], v[138:139]
	v_pk_mul_f32 v[136:137], v[154:155], s[4:5] op_sel_hi:[1,0]
	v_pk_mul_f32 v[138:139], v[152:153], s[4:5] op_sel_hi:[1,0]
	v_pk_fma_f32 v[136:137], v[130:131], v[2:3], v[136:137]
	v_pk_fma_f32 v[130:131], v[128:129], v[0:1], v[138:139]
	v_cvt_pk_bf16_f32 v128, v132, v133
	v_cvt_pk_bf16_f32 v129, v134, v135
	v_cvt_pk_bf16_f32 v130, v130, v131
	v_cvt_pk_bf16_f32 v131, v136, v137
	global_store_dwordx4 v[168:169], v[128:131], off offset:256 nt
	s_mov_b64 s[4:5], 0

.LBB0_846:
	v_and_b32_e32 v135, 3, v247
	v_lshrrev_b32_e32 v134, 2, v247
	v_lshl_add_u32 v136, v135, 4, v134
	v_lshlrev_b32_e32 v136, 2, v136
	s_add_i32 s2, s90, s22
	v_lshl_add_u32 v128, v135, 3, s2
	v_readlane_b32 s2, v254, 51
	v_ashrrev_i32_e32 v129, 31, v128
	v_readlane_b32 s3, v254, 52
	v_or_b32_e32 v130, s57, v134
	v_mov_b32_e32 v131, s35
	v_lshl_add_u64 v[128:129], v[128:129], 1, s[2:3]
	s_ashr_i32 s7, s6, 31
	v_readlane_b32 s2, v254, 49
	v_lshl_add_u64 v[130:131], v[130:131], 0, s[6:7]
	v_readlane_b32 s3, v254, 50
	v_mul_lo_u32 v132, v131, s2
	s_nop 0
	v_mul_lo_u32 v133, v130, s3
	v_mad_u64_u32 v[130:131], s[2:3], v130, s2, 0
	v_add3_u32 v131, v131, v133, v132
	v_lshl_add_u64 v[132:133], v[130:131], 1, v[128:129]
	v_readlane_b32 s2, v255, 28
	v_readlane_b32 s3, v255, 29
	v_cvt_pk_bf16_f32 v140, v124, v125
	v_cvt_pk_bf16_f32 v141, v126, v127
	v_cvt_pk_bf16_f32 v142, v60, v61
	v_cvt_pk_bf16_f32 v143, v62, v63
	ds_bpermute_b32 v148, v136, v140
	ds_bpermute_b32 v149, v136, v141
	ds_bpermute_b32 v150, v136, v142
	ds_bpermute_b32 v151, v136, v143
	v_cvt_pk_bf16_f32 v144, v120, v121
	v_cvt_pk_bf16_f32 v145, v122, v123
	v_cvt_pk_bf16_f32 v146, v56, v57
	v_cvt_pk_bf16_f32 v147, v58, v59
	ds_bpermute_b32 v152, v136, v144
	ds_bpermute_b32 v153, v136, v145
	ds_bpermute_b32 v154, v136, v146
	ds_bpermute_b32 v155, v136, v147
	s_waitcnt lgkmcnt(4)
	global_store_dwordx4 v[132:133], v[148:151], off nt
	v_cvt_pk_bf16_f32 v140, v116, v117
	v_cvt_pk_bf16_f32 v141, v118, v119
	v_cvt_pk_bf16_f32 v142, v52, v53
	v_cvt_pk_bf16_f32 v143, v54, v55
	ds_bpermute_b32 v156, v136, v140
	ds_bpermute_b32 v157, v136, v141
	ds_bpermute_b32 v158, v136, v142
	ds_bpermute_b32 v159, v136, v143
	s_waitcnt lgkmcnt(4)
	global_store_dwordx4 v[132:133], v[152:155], off offset:256 nt
	v_lshl_add_u64 v[132:133], v[132:133], 0, s[84:85]
	v_cvt_pk_bf16_f32 v144, v112, v113
	v_cvt_pk_bf16_f32 v145, v114, v115
	v_cvt_pk_bf16_f32 v146, v48, v49
	v_cvt_pk_bf16_f32 v147, v50, v51
	ds_bpermute_b32 v160, v136, v144
	ds_bpermute_b32 v161, v136, v145
	ds_bpermute_b32 v162, v136, v146
	ds_bpermute_b32 v163, v136, v147
	s_waitcnt lgkmcnt(4)
	global_store_dwordx4 v[132:133], v[156:159], off nt
	v_cvt_pk_bf16_f32 v140, v108, v109
	v_cvt_pk_bf16_f32 v141, v110, v111
	v_cvt_pk_bf16_f32 v142, v44, v45
	v_cvt_pk_bf16_f32 v143, v46, v47
	ds_bpermute_b32 v148, v136, v140
	ds_bpermute_b32 v149, v136, v141
	ds_bpermute_b32 v150, v136, v142
	ds_bpermute_b32 v151, v136, v143
	s_waitcnt lgkmcnt(4)
	global_store_dwordx4 v[132:133], v[160:163], off offset:256 nt
	v_lshl_add_u64 v[132:133], v[132:133], 0, s[84:85]
	v_cvt_pk_bf16_f32 v144, v104, v105
	v_cvt_pk_bf16_f32 v145, v106, v107
	v_cvt_pk_bf16_f32 v146, v40, v41
	v_cvt_pk_bf16_f32 v147, v42, v43
	ds_bpermute_b32 v152, v136, v144
	ds_bpermute_b32 v153, v136, v145
	ds_bpermute_b32 v154, v136, v146
	ds_bpermute_b32 v155, v136, v147
	s_waitcnt lgkmcnt(4)
	global_store_dwordx4 v[132:133], v[148:151], off nt
	v_cvt_pk_bf16_f32 v140, v100, v101
	v_cvt_pk_bf16_f32 v141, v102, v103
	v_cvt_pk_bf16_f32 v142, v36, v37
	v_cvt_pk_bf16_f32 v143, v38, v39
	ds_bpermute_b32 v156, v136, v140
	ds_bpermute_b32 v157, v136, v141
	ds_bpermute_b32 v158, v136, v142
	ds_bpermute_b32 v159, v136, v143
	s_waitcnt lgkmcnt(4)
	global_store_dwordx4 v[132:133], v[152:155], off offset:256 nt
	v_lshl_add_u64 v[132:133], v[132:133], 0, s[84:85]
	v_cvt_pk_bf16_f32 v144, v96, v97
	v_cvt_pk_bf16_f32 v145, v98, v99
	v_cvt_pk_bf16_f32 v146, v32, v33
	v_cvt_pk_bf16_f32 v147, v34, v35
	ds_bpermute_b32 v160, v136, v144
	ds_bpermute_b32 v161, v136, v145
	ds_bpermute_b32 v162, v136, v146
	ds_bpermute_b32 v163, v136, v147
	s_waitcnt lgkmcnt(4)
	global_store_dwordx4 v[132:133], v[156:159], off nt
	v_cvt_pk_bf16_f32 v140, v92, v93
	v_cvt_pk_bf16_f32 v141, v94, v95
	v_cvt_pk_bf16_f32 v142, v28, v29
	v_cvt_pk_bf16_f32 v143, v30, v31
	ds_bpermute_b32 v148, v136, v140
	ds_bpermute_b32 v149, v136, v141
	ds_bpermute_b32 v150, v136, v142
	ds_bpermute_b32 v151, v136, v143
	s_waitcnt lgkmcnt(4)
	global_store_dwordx4 v[132:133], v[160:163], off offset:256 nt
	v_lshl_add_u64 v[132:133], s[2:3], 1, v[132:133]
	v_cvt_pk_bf16_f32 v144, v88, v89
	v_cvt_pk_bf16_f32 v145, v90, v91
	v_cvt_pk_bf16_f32 v146, v24, v25
	v_cvt_pk_bf16_f32 v147, v26, v27
	ds_bpermute_b32 v152, v136, v144
	ds_bpermute_b32 v153, v136, v145
	ds_bpermute_b32 v154, v136, v146
	ds_bpermute_b32 v155, v136, v147
	s_waitcnt lgkmcnt(4)
	global_store_dwordx4 v[132:133], v[148:151], off nt
	v_cvt_pk_bf16_f32 v140, v84, v85
	v_cvt_pk_bf16_f32 v141, v86, v87
	v_cvt_pk_bf16_f32 v142, v20, v21
	v_cvt_pk_bf16_f32 v143, v22, v23
	ds_bpermute_b32 v156, v136, v140
	ds_bpermute_b32 v157, v136, v141
	ds_bpermute_b32 v158, v136, v142
	ds_bpermute_b32 v159, v136, v143
	s_waitcnt lgkmcnt(4)
	global_store_dwordx4 v[132:133], v[152:155], off offset:256 nt
	v_lshl_add_u64 v[132:133], v[132:133], 0, s[84:85]
	v_cvt_pk_bf16_f32 v144, v80, v81
	v_cvt_pk_bf16_f32 v145, v82, v83
	v_cvt_pk_bf16_f32 v146, v16, v17
	v_cvt_pk_bf16_f32 v147, v18, v19
	ds_bpermute_b32 v160, v136, v144
	ds_bpermute_b32 v161, v136, v145
	ds_bpermute_b32 v162, v136, v146
	ds_bpermute_b32 v163, v136, v147
	s_waitcnt lgkmcnt(4)
	global_store_dwordx4 v[132:133], v[156:159], off nt
	v_cvt_pk_bf16_f32 v140, v76, v77
	v_cvt_pk_bf16_f32 v141, v78, v79
	v_cvt_pk_bf16_f32 v142, v12, v13
	v_cvt_pk_bf16_f32 v143, v14, v15
	ds_bpermute_b32 v148, v136, v140
	ds_bpermute_b32 v149, v136, v141
	ds_bpermute_b32 v150, v136, v142
	ds_bpermute_b32 v151, v136, v143
	s_waitcnt lgkmcnt(4)
	global_store_dwordx4 v[132:133], v[160:163], off offset:256 nt
	v_lshl_add_u64 v[132:133], v[132:133], 0, s[84:85]
	v_cvt_pk_bf16_f32 v144, v72, v73
	v_cvt_pk_bf16_f32 v145, v74, v75
	v_cvt_pk_bf16_f32 v146, v8, v9
	v_cvt_pk_bf16_f32 v147, v10, v11
	ds_bpermute_b32 v152, v136, v144
	ds_bpermute_b32 v153, v136, v145
	ds_bpermute_b32 v154, v136, v146
	ds_bpermute_b32 v155, v136, v147
	s_waitcnt lgkmcnt(4)
	global_store_dwordx4 v[132:133], v[148:151], off nt
	v_cvt_pk_bf16_f32 v140, v68, v69
	v_cvt_pk_bf16_f32 v141, v70, v71
	v_cvt_pk_bf16_f32 v142, v4, v5
	v_cvt_pk_bf16_f32 v143, v6, v7
	ds_bpermute_b32 v156, v136, v140
	ds_bpermute_b32 v157, v136, v141
	ds_bpermute_b32 v158, v136, v142
	ds_bpermute_b32 v159, v136, v143
	s_waitcnt lgkmcnt(4)
	global_store_dwordx4 v[132:133], v[152:155], off offset:256 nt
	v_lshl_add_u64 v[132:133], v[132:133], 0, s[84:85]
	v_cvt_pk_bf16_f32 v144, v64, v65
	v_cvt_pk_bf16_f32 v145, v66, v67
	v_cvt_pk_bf16_f32 v146, v0, v1
	v_cvt_pk_bf16_f32 v147, v2, v3
	ds_bpermute_b32 v160, v136, v144
	ds_bpermute_b32 v161, v136, v145
	ds_bpermute_b32 v162, v136, v146
	ds_bpermute_b32 v163, v136, v147
	s_waitcnt lgkmcnt(4)
	global_store_dwordx4 v[132:133], v[156:159], off nt
	s_waitcnt lgkmcnt(0)
	global_store_dwordx4 v[132:133], v[160:163], off offset:256 nt
	s_cbranch_execz .LBB0_723
